# baseline (speedup 1.0000x reference)
; DI int my_tid() { int t = threadIdx.x; asm volatile("" : "+v"(t)); return t; }
; DI unsigned fkey(float f) { const unsigned u = __float_as_uint(f); return (u & 0x80000000u) ? ~u : (u | 0x80000000u); }
; #define TK_PREFETCH(t_, p_) do { const int tk0_ = ((t_) >> 3) * 64, hp_ = ((t_) & 7) * 2 + (p_); \
;         _Pragma("unroll") for (int i_ = 0; i_ < 4; ++i_) { const int c_ = tid + 256 * i_; pre[i_] = *(const u32x4*)(qp + (size_t)(tk0_ + (c_ >> 4)) * 2048 + hp_ * 128 + (c_ & 15) * 8); } } while (0)
; DI void topk_phase(unsigned char* smem_, const bf16_t* __restrict__ qp, const bf16_t* __restrict__ keys, int* __restrict__ eidx, float* __restrict__ gate) {
;     const int tid5 = my_tid(), half = __builtin_amdgcn_readfirstlane(tid5 >> 8), tid = tid5 & 255, lane = tid & 63, wid = __builtin_amdgcn_readfirstlane((tid5 >> 6) & 3), l31 = lane & 31, hi = lane >> 5;
;     unsigned char* smem = smem_ + half * 69632;
;     const int G = gridDim.x * 2, bx = blockIdx.x * 2 + half;
;     constexpr int LDA = 136, LDS_ = 132, NT = 512 * 8;
;     bf16_t* As = (bf16_t*)smem;
;     float* S = (float*)(smem + 17408);
;     float* SV = (float*)(smem + 53248);
;     int* SI = (int*)(smem + 53248 + 8192);
;     const int row = tid >> 2, q = tid & 3;
;     int cur_h = -1;
;     bf16x8 kf[2][8];
;     u32x4 pre[4];
;     ...
;     TK_PREFETCH(bx, 0);
;     ...
;     constexpr unsigned KT[13] = {0x03020100u, 0x07060504u, 0x0b0a0908u, 0x0f0e0d0cu, 0x13121110u, 0x17161514u, 0x23222120u, 0x32313024u, 0x42414033u, 0x61605150u, 0x90807170u, 0xd0c0b0a0u, 0x0000f0e0u};
;     unsigned c16[16];
; #pragma unroll
;     for (int i = 0; i < 13; ++i) {
;         const unsigned ab = (KT[i] >> (8 * q)) & 255u;
;         const float c = SV[row * 32 + (ab >> 4)] + SV[row * 32 + 16 + (ab & 15u)];
;         c16[i] = (fkey(c) & ~255u) | (255u - ab);
;     }
.LBB0_51:
	s_andn2_b64 vcc, exec, s[0:1]
	s_cbranch_vccnz .LBB0_84
	v_mov_b32_e32 v0, v192
	v_readlane_b32 s2, v251, 57
	v_readfirstlane_b32 s1, v0
	s_ashr_i32 s0, s1, 8
	s_add_i32 s18, s0, s2
	s_cmpk_gt_i32 s18, 0xfff
	s_cbranch_scc1 .LBB0_83
	s_mul_i32 s2, s0, 0x11000
	s_add_i32 s19, s2, 0
	s_lshl_b32 s2, s18, 9
	v_lshlrev_b32_e32 v1, 3, v0
	s_and_b32 s2, s2, 0xe00
	v_and_b32_e32 v2, 0x78, v1
	s_add_u32 s2, s86, s2
	s_addc_u32 s3, s87, 0
	v_lshlrev_b32_e32 v128, 1, v2
	v_bfe_u32 v165, v0, 4, 4
	v_lshl_add_u64 v[4:5], s[2:3], 0, v[128:129]
	s_lshl_b32 s2, s18, 3
	v_or_b32_e32 v168, 48, v165
	s_andn2_b32 s2, s2, 63
	v_or_b32_e32 v167, 32, v165
	v_or_b32_e32 v6, s2, v168
	v_ashrrev_i32_e32 v7, 31, v6
	v_or_b32_e32 v8, s2, v167
	v_lshlrev_b64 v[6:7], 12, v[6:7]
	v_ashrrev_i32_e32 v9, 31, v8
	v_or_b32_e32 v166, 16, v165
	v_lshl_add_u64 v[6:7], v[4:5], 0, v[6:7]
	v_lshlrev_b64 v[8:9], 12, v[8:9]
	v_lshl_add_u64 v[8:9], v[4:5], 0, v[8:9]
	global_load_dwordx4 v[108:111], v[6:7], off
	global_load_dwordx4 v[104:107], v[8:9], off
	v_or_b32_e32 v6, s2, v166
	v_ashrrev_i32_e32 v7, 31, v6
	v_or_b32_e32 v8, s2, v165
	v_lshlrev_b64 v[6:7], 12, v[6:7]
	v_ashrrev_i32_e32 v9, 31, v8
	v_lshl_add_u64 v[6:7], v[4:5], 0, v[6:7]
	v_lshlrev_b64 v[8:9], 12, v[8:9]
	v_lshl_add_u64 v[4:5], v[4:5], 0, v[8:9]
	global_load_dwordx4 v[100:103], v[6:7], off
	global_load_dwordx4 v[96:99], v[4:5], off
	v_bfe_u32 v164, v0, 2, 6
	v_and_b32_e32 v3, 3, v0
	v_and_b32_e32 v10, 31, v0
	v_lshrrev_b32_e32 v0, 1, v0
	v_readlane_b32 s2, v252, 41
	s_bfe_u32 s1, s1, 0x20006
	v_and_b32_e32 v0, 16, v0
	v_mov_b32_e32 v1, v129
	v_readlane_b32 s3, v252, 42
	v_add_u32_e32 v4, s19, v0
	v_mov_b32_e32 v5, s19
	v_lshl_add_u64 v[112:113], s[2:3], 0, v[0:1]
	s_lshl_b32 s2, s1, 7
	s_add_i32 s2, s19, s2
	v_add_u32_e32 v0, s2, v0
	s_movk_i32 s2, 0x210
	v_cmp_lt_i32_e32 vcc, v204, v200
	v_mad_u32_u24 v169, v164, s2, v5
	v_lshl_or_b32 v176, s1, 5, v10
	v_cndmask_b32_e32 v5, v197, v204, vcc
	v_cmp_lt_i32_e32 vcc, v203, v200
	v_lshlrev_b32_e32 v172, 2, v5
	s_mov_b32 s1, 0x3020100
	v_cndmask_b32_e32 v5, v197, v203, vcc
	v_lshlrev_b32_e32 v173, 2, v5
	v_lshlrev_b32_e32 v5, 3, v3
	v_bfe_u32 v185, s1, v5, 2
	s_mov_b32 s1, 0x7060504
	s_movk_i32 s2, 0xfe70
	v_bfe_u32 v187, s1, v5, 3
	s_mov_b32 s1, 0xb0a0908
	v_lshlrev_b32_e32 v170, 5, v3
	v_lshl_add_u32 v171, v3, 7, v169
	v_mad_i32_i24 v175, v164, s2, v169
	v_cmp_lt_u32_e64 s[2:3], 1, v3
	v_cmp_eq_u32_e64 s[4:5], 0, v3
	v_cmp_eq_u32_e64 s[6:7], 1, v3
	v_cmp_eq_u32_e64 s[8:9], 2, v3
	v_cmp_eq_u32_e64 s[10:11], 3, v3
	v_lshrrev_b32_e64 v3, v5, s1
	s_mov_b32 s1, 0xf0e0d0c
	v_bfe_u32 v191, s1, v5, 4
	s_mov_b32 s1, 0x13121110
	v_and_b32_e32 v189, 11, v3
	v_lshrrev_b32_e64 v3, v5, s1
	v_and_b32_e32 v212, 19, v3
	v_bfe_u32 v3, s1, v5, 2
	s_mov_b32 s1, 0x17161514
	v_lshl_add_u32 v213, v3, 2, v175
	v_lshrrev_b32_e64 v3, v5, s1
	v_and_b32_e32 v214, 23, v3
	v_bfe_u32 v3, s1, v5, 3
	s_mov_b32 s1, 0x23222120
	v_lshl_add_u32 v215, v3, 2, v175
	v_lshrrev_b32_e64 v3, v5, s1
	v_and_b32_e32 v216, 35, v3
	v_bfe_u32 v3, s1, v5, 2
	s_mov_b32 s1, 0x32313024
	v_lshl_add_u32 v217, v3, 2, v175
	v_lshrrev_b32_e64 v3, v5, s1
	v_and_b32_e32 v218, 55, v3
	v_lshrrev_b32_e32 v3, 2, v3
	v_and_b32_e32 v3, 12, v3
	v_add_u32_e32 v219, v175, v3
	v_bfe_u32 v3, s1, v5, 3
	s_mov_b32 s1, 0x42414033
	v_lshl_add_u32 v220, v3, 2, v175
	v_lshrrev_b32_e64 v3, v5, s1
	v_and_b32_e32 v221, 0x73, v3
	v_lshrrev_b32_e32 v3, 2, v221
	v_add_u32_e32 v222, v175, v3
	v_bfe_u32 v3, s1, v5, 2
	s_mov_b32 s1, 0x61605150
	v_lshl_add_u32 v223, v3, 2, v175
	v_lshrrev_b32_e64 v3, v5, s1
	v_and_b32_e32 v224, 0x71, v3
	v_lshrrev_b32_e32 v3, 2, v224
	v_add_u32_e32 v225, v175, v3
	v_bfe_u32 v3, s1, v5, 1
	s_mov_b32 s1, 0x90807170
	v_lshl_add_u32 v226, v3, 2, v175
	v_lshrrev_b32_e64 v3, v5, s1
	v_and_b32_e32 v227, 0xf1, v3
	v_lshrrev_b32_e32 v3, 2, v227
	v_add_u32_e32 v228, v175, v3
	v_bfe_u32 v3, s1, v5, 1
	s_mov_b32 s1, 0xd0c0b0a0
	v_lshl_add_u32 v229, v3, 2, v175
	v_lshrrev_b32_e64 v3, v5, s1
	s_mov_b32 s1, 0xf0e0
	v_lshrrev_b32_e64 v5, v5, s1
	v_readlane_b32 s1, v251, 49
	v_and_b32_e32 v230, 0xf0, v3
	v_and_b32_e32 v231, 0xf0, v5
	s_add_i32 s1, s1, s0
	v_add_u32_e32 v1, s19, v128
	v_mul_u32_u24_e32 v6, 0x110, v165
	v_mul_u32_u24_e32 v7, 0x110, v10
	v_mul_u32_u24_e32 v8, 0x210, v10
	v_lshrrev_b32_e32 v3, 2, v230
	v_lshrrev_b32_e32 v5, 2, v231
	s_lshl_b32 s21, s1, 8
	s_lshl_b32 s0, s0, 3
	v_readlane_b32 s1, v251, 52
	s_mov_b32 s20, -1
	v_lshlrev_b32_e32 v174, 5, v164
	v_lshl_add_u64 v[114:115], s[86:87], 0, v[128:129]
	v_or_b32_e32 v177, 4, v170
	v_or_b32_e32 v178, 8, v170
	v_or_b32_e32 v179, 12, v170
	v_or_b32_e32 v180, 16, v170
	v_or_b32_e32 v181, 20, v170
	v_or_b32_e32 v182, 24, v170
	v_or_b32_e32 v183, 28, v170
	v_sub_u32_e32 v170, 0x7f, v170
	v_sub_u32_e32 v177, 0x7f, v177
	v_sub_u32_e32 v178, 0x7f, v178
	v_sub_u32_e32 v179, 0x7f, v179
	v_sub_u32_e32 v180, 0x7f, v180
	v_sub_u32_e32 v181, 0x7f, v181
	v_sub_u32_e32 v182, 0x7f, v182
	v_sub_u32_e32 v183, 0x7f, v183
	v_lshl_add_u32 v184, v164, 7, s19
	v_lshl_add_u32 v186, v185, 2, v175
	v_lshl_add_u32 v188, v187, 2, v175
	v_lshl_add_u32 v190, v189, 2, v175
	v_lshl_add_u32 v211, v191, 2, v175
	s_add_i32 s22, s1, s0
	v_lshlrev_b32_e32 v128, 1, v2
	v_add_u32_e32 v232, v175, v3
	v_add_u32_e32 v233, v175, v5
	v_add_u32_e32 v234, v1, v6
	v_add_u32_e32 v235, v4, v7
	v_add_u32_e32 v236, v0, v8
	s_branch .LBB0_55

; #define MFMA32(a, b, c) __builtin_amdgcn_mfma_f32_32x32x16_bf16((a), (b), (c), 0, 0, 0)
; DI unsigned fkey(float f) { const unsigned u = __float_as_uint(f); return (u & 0x80000000u) ? ~u : (u | 0x80000000u); }
; DI void topk_phase(unsigned char* smem_, const bf16_t* __restrict__ qp, const bf16_t* __restrict__ keys, int* __restrict__ eidx, float* __restrict__ gate) {
;     ...
;     for (int t = bx; t < NT; t += G) {
;         const int h = t & 7, tok0 = (t >> 3) * 64;
;         if (h != cur_h) {
;             cur_h = h;
; #pragma unroll
;             for (int p = 0; p < 2; ++p)
; #pragma unroll
;                 for (int ks = 0; ks < 8; ++ks) kf[p][ks] = *(const bf16x8*)(keys + ((size_t)(h * 2 + p) * 128 + 32 * wid + l31) * 128 + ks * 16 + hi * 8);
;         }
; #pragma unroll
;     for (int p = 0; p < 2; ++p) {
; #pragma unroll
;         for (int i = 0; i < 4; ++i) { const int c = tid + 256 * i; *(u32x4*)(As + (c >> 4) * LDA + (c & 15) * 8) = pre[i]; }
;         __syncthreads();
;         f32x16 acc[2];
; #pragma unroll
;         for (int i = 0; i < 16; ++i) { acc[0][i] = 0.f; acc[1][i] = 0.f; }
; #pragma unroll
;         for (int ks = 0; ks < 8; ++ks) {
; #pragma unroll
;             for (int th = 0; th < 2; ++th) { const bf16x8 qf = *(const bf16x8*)(As + (32 * th + l31) * LDA + ks * 16 + hi * 8); acc[th] = MFMA32(kf[p][ks], qf, acc[th]); }
;         }
; #pragma unroll
;         for (int th = 0; th < 2; ++th)
; #pragma unroll
;             for (int g = 0; g < 4; ++g) { f32x4 o; o.x = acc[th][4 * g]; o.y = acc[th][4 * g + 1]; o.z = acc[th][4 * g + 2]; o.w = acc[th][4 * g + 3]; *(f32x4*)(S + (32 * th + l31) * LDS_ + 32 * wid + 8 * g + 4 * hi) = o; }
;         __syncthreads();
;         if (p == 0) TK_PREFETCH(t, 1); else if (t + G < NT) TK_PREFETCH(t + G, 0);
;         unsigned v[32];
; #pragma unroll
;         for (int i = 0; i < 8; ++i) {
;             const f32x4 sv4 = *(const f32x4*)(S + row * LDS_ + 32 * q + 4 * i);
;             const int ib = 127 - (32 * q + 4 * i);
;             v[4 * i] = (fkey(sv4.x) & ~127u) | (unsigned)ib; v[4 * i + 1] = (fkey(sv4.y) & ~127u) | (unsigned)(ib - 1);
;             v[4 * i + 2] = (fkey(sv4.z) & ~127u) | (unsigned)(ib - 2); v[4 * i + 3] = (fkey(sv4.w) & ~127u) | (unsigned)(ib - 3);
;         }
.LBB0_55:
	s_mov_b32 s98, 0x80000000
	s_mov_b32 s99, 0xffffff80
	s_and_b32 s23, s18, 7
	s_lshl_b32 s0, s23, 8
	s_cmp_eq_u32 s23, s20
	s_cbranch_scc1 .LBB0_57
	v_or_b32_e32 v0, s0, v176
	v_lshlrev_b32_e32 v0, 8, v0
	v_mov_b32_e32 v1, v129
	v_lshl_add_u64 v[0:1], v[112:113], 0, v[0:1]
	global_load_dwordx4 v[32:35], v[0:1], off
	global_load_dwordx4 v[36:39], v[0:1], off offset:32
	global_load_dwordx4 v[40:43], v[0:1], off offset:64
	global_load_dwordx4 v[44:47], v[0:1], off offset:96
	global_load_dwordx4 v[48:51], v[0:1], off offset:128
	global_load_dwordx4 v[52:55], v[0:1], off offset:160
	global_load_dwordx4 v[56:59], v[0:1], off offset:192
	global_load_dwordx4 v[60:63], v[0:1], off offset:224
	v_add_co_u32_e32 v0, vcc, 0x8000, v0
	s_mov_b32 s20, s23
	s_nop 0
	v_addc_co_u32_e32 v1, vcc, 0, v1, vcc
	global_load_dwordx4 v[64:67], v[0:1], off
	global_load_dwordx4 v[68:71], v[0:1], off offset:32
	global_load_dwordx4 v[72:75], v[0:1], off offset:64
	global_load_dwordx4 v[76:79], v[0:1], off offset:96
	global_load_dwordx4 v[80:83], v[0:1], off offset:128
	global_load_dwordx4 v[84:87], v[0:1], off offset:160
	global_load_dwordx4 v[88:91], v[0:1], off offset:192
	global_load_dwordx4 v[92:95], v[0:1], off offset:224
.LBB0_57:
	s_waitcnt vmcnt(0)
	ds_write_b128 v234, v[96:99]
	ds_write_b128 v234, v[100:103] offset:4352
	ds_write_b128 v234, v[104:107] offset:8704
	ds_write_b128 v234, v[108:111] offset:13056
	s_waitcnt lgkmcnt(0)
	s_barrier
	ds_read_b128 v[0:3], v235
	ds_read_b128 v[96:99], v235 offset:32
	s_waitcnt lgkmcnt(1)
	v_mfma_f32_32x32x16_bf16 v[16:31], v[32:35], v[0:3], 0
	ds_read_b128 v[0:3], v235 offset:8704
	s_and_b32 s24, s22, 0xffffffc0
	s_lshl_b32 s0, s0, 1
	s_add_u32 s0, s86, s0
	s_addc_u32 s1, s87, 0
	s_waitcnt lgkmcnt(1)
	v_mfma_f32_32x32x16_bf16 v[16:31], v[36:39], v[96:99], v[16:31]
	ds_read_b128 v[96:99], v235 offset:8736
	s_waitcnt lgkmcnt(1)
	v_mfma_f32_32x32x16_bf16 v[0:15], v[32:35], v[0:3], 0
	s_waitcnt lgkmcnt(0)
	v_mfma_f32_32x32x16_bf16 v[0:15], v[36:39], v[96:99], v[0:15]
	ds_read_b128 v[96:99], v235 offset:64
	s_waitcnt lgkmcnt(0)
	v_mfma_f32_32x32x16_bf16 v[16:31], v[40:43], v[96:99], v[16:31]
	ds_read_b128 v[96:99], v235 offset:8768
	s_waitcnt lgkmcnt(0)
	v_mfma_f32_32x32x16_bf16 v[0:15], v[40:43], v[96:99], v[0:15]
	ds_read_b128 v[96:99], v235 offset:96
	s_waitcnt lgkmcnt(0)
	v_mfma_f32_32x32x16_bf16 v[16:31], v[44:47], v[96:99], v[16:31]
	ds_read_b128 v[96:99], v235 offset:8800
	s_waitcnt lgkmcnt(0)
	v_mfma_f32_32x32x16_bf16 v[0:15], v[44:47], v[96:99], v[0:15]
	ds_read_b128 v[96:99], v235 offset:128
	s_waitcnt lgkmcnt(0)
	v_mfma_f32_32x32x16_bf16 v[16:31], v[48:51], v[96:99], v[16:31]
	ds_read_b128 v[96:99], v235 offset:8832
	s_waitcnt lgkmcnt(0)
	v_mfma_f32_32x32x16_bf16 v[0:15], v[48:51], v[96:99], v[0:15]
	ds_read_b128 v[96:99], v235 offset:160
	s_waitcnt lgkmcnt(0)
	v_mfma_f32_32x32x16_bf16 v[16:31], v[52:55], v[96:99], v[16:31]
	ds_read_b128 v[96:99], v235 offset:8864
	s_waitcnt lgkmcnt(0)
	v_mfma_f32_32x32x16_bf16 v[0:15], v[52:55], v[96:99], v[0:15]
	ds_read_b128 v[96:99], v235 offset:192
	s_waitcnt lgkmcnt(0)
	v_mfma_f32_32x32x16_bf16 v[16:31], v[56:59], v[96:99], v[16:31]
	ds_read_b128 v[96:99], v235 offset:8896
	s_waitcnt lgkmcnt(0)
	v_mfma_f32_32x32x16_bf16 v[0:15], v[56:59], v[96:99], v[0:15]
	ds_read_b128 v[96:99], v235 offset:224
	s_waitcnt lgkmcnt(0)
	v_mfma_f32_32x32x16_bf16 v[16:31], v[60:63], v[96:99], v[16:31]
	ds_read_b128 v[96:99], v235 offset:8928
	s_nop 10
	ds_write_b128 v236, v[16:19] offset:17408
	ds_write_b128 v236, v[20:23] offset:17440
	ds_write_b128 v236, v[24:27] offset:17472
	ds_write_b128 v236, v[28:31] offset:17504
	s_waitcnt lgkmcnt(4)
	v_mfma_f32_32x32x16_bf16 v[0:15], v[60:63], v[96:99], v[0:15]
	s_nop 11
	ds_write_b128 v236, v[0:3] offset:34304
	ds_write_b128 v236, v[4:7] offset:34336
	ds_write_b128 v236, v[8:11] offset:34368
	ds_write_b128 v236, v[12:15] offset:34400
	v_or_b32_e32 v0, s24, v165
	v_ashrrev_i32_e32 v1, 31, v0
	v_lshlrev_b64 v[0:1], 12, v[0:1]
	v_lshl_add_u64 v[0:1], s[0:1], 0, v[0:1]
	v_lshl_add_u64 v[0:1], v[0:1], 0, v[128:129]
	s_waitcnt lgkmcnt(0)
	s_barrier
	global_load_dwordx4 v[96:99], v[0:1], off offset:256
	v_or_b32_e32 v0, s24, v166
	v_ashrrev_i32_e32 v1, 31, v0
	v_lshlrev_b64 v[0:1], 12, v[0:1]
	v_lshl_add_u64 v[0:1], s[0:1], 0, v[0:1]
	v_lshl_add_u64 v[0:1], v[0:1], 0, v[128:129]
	global_load_dwordx4 v[100:103], v[0:1], off offset:256
	v_or_b32_e32 v0, s24, v167
	v_ashrrev_i32_e32 v1, 31, v0
	v_lshlrev_b64 v[0:1], 12, v[0:1]
	v_lshl_add_u64 v[0:1], s[0:1], 0, v[0:1]
	v_lshl_add_u64 v[0:1], v[0:1], 0, v[128:129]
	global_load_dwordx4 v[104:107], v[0:1], off offset:256
	v_or_b32_e32 v0, s24, v168
	v_ashrrev_i32_e32 v1, 31, v0
	v_lshlrev_b64 v[0:1], 12, v[0:1]
	v_lshl_add_u64 v[0:1], s[0:1], 0, v[0:1]
	v_lshl_add_u64 v[4:5], v[0:1], 0, v[128:129]
	ds_read_b128 v[0:3], v171 offset:17408
	global_load_dwordx4 v[108:111], v[4:5], off offset:256
	ds_read_b128 v[4:7], v171 offset:17424
	ds_read_b128 v[8:11], v171 offset:17440
	ds_read_b128 v[12:15], v171 offset:17456
	s_waitcnt lgkmcnt(3)
	v_ashrrev_i32_e32 v16, 31, v0


; DI unsigned fkey(float f) { const unsigned u = __float_as_uint(f); return (u & 0x80000000u) ? ~u : (u | 0x80000000u); }
; DI void topk_phase(unsigned char* smem_, const bf16_t* __restrict__ qp, const bf16_t* __restrict__ keys, int* __restrict__ eidx, float* __restrict__ gate) {
;     ...
;         for (int i = 0; i < 8; ++i) {
;             const f32x4 sv4 = *(const f32x4*)(S + row * LDS_ + 32 * q + 4 * i);
;             const int ib = 127 - (32 * q + 4 * i);
;             v[4 * i] = (fkey(sv4.x) & ~127u) | (unsigned)ib; v[4 * i + 1] = (fkey(sv4.y) & ~127u) | (unsigned)(ib - 1);
;             v[4 * i + 2] = (fkey(sv4.z) & ~127u) | (unsigned)(ib - 2); v[4 * i + 3] = (fkey(sv4.w) & ~127u) | (unsigned)(ib - 3);
;         }
	s_waitcnt lgkmcnt(0)
	v_not_b32_e32 v20, v15
	v_or_b32_e32 v21, 0x80000000, v15
	v_bitop3_b32 v0, v16, s98, v0 bitop3:0x56
	v_ashrrev_i32_e32 v16, 31, v1


; DI unsigned fkey(float f) { const unsigned u = __float_as_uint(f); return (u & 0x80000000u) ? ~u : (u | 0x80000000u); }
; DI void topk_phase(unsigned char* smem_, const bf16_t* __restrict__ qp, const bf16_t* __restrict__ keys, int* __restrict__ eidx, float* __restrict__ gate) {
;     ...
;         for (int i = 0; i < 8; ++i) {
;             const f32x4 sv4 = *(const f32x4*)(S + row * LDS_ + 32 * q + 4 * i);
;             const int ib = 127 - (32 * q + 4 * i);
;             v[4 * i] = (fkey(sv4.x) & ~127u) | (unsigned)ib; v[4 * i + 1] = (fkey(sv4.y) & ~127u) | (unsigned)(ib - 1);
;             v[4 * i + 2] = (fkey(sv4.z) & ~127u) | (unsigned)(ib - 2); v[4 * i + 3] = (fkey(sv4.w) & ~127u) | (unsigned)(ib - 3);
;         }
	v_and_or_b32 v0, v0, s99, v170

; DI unsigned fkey(float f) { const unsigned u = __float_as_uint(f); return (u & 0x80000000u) ? ~u : (u | 0x80000000u); }
; DI void topk_phase(unsigned char* smem_, const bf16_t* __restrict__ qp, const bf16_t* __restrict__ keys, int* __restrict__ eidx, float* __restrict__ gate) {
;     ...
;         for (int i = 0; i < 8; ++i) {
;             const f32x4 sv4 = *(const f32x4*)(S + row * LDS_ + 32 * q + 4 * i);
;             const int ib = 127 - (32 * q + 4 * i);
;             v[4 * i] = (fkey(sv4.x) & ~127u) | (unsigned)ib; v[4 * i + 1] = (fkey(sv4.y) & ~127u) | (unsigned)(ib - 1);
;             v[4 * i + 2] = (fkey(sv4.z) & ~127u) | (unsigned)(ib - 2); v[4 * i + 3] = (fkey(sv4.w) & ~127u) | (unsigned)(ib - 3);
;         }
	v_bitop3_b32 v1, v16, s98, v1 bitop3:0x56
	v_ashrrev_i32_e32 v16, 31, v2


; DI unsigned fkey(float f) { const unsigned u = __float_as_uint(f); return (u & 0x80000000u) ? ~u : (u | 0x80000000u); }
; DI void topk_phase(unsigned char* smem_, const bf16_t* __restrict__ qp, const bf16_t* __restrict__ keys, int* __restrict__ eidx, float* __restrict__ gate) {
;     ...
;         for (int i = 0; i < 8; ++i) {
;             const f32x4 sv4 = *(const f32x4*)(S + row * LDS_ + 32 * q + 4 * i);
;             const int ib = 127 - (32 * q + 4 * i);
;             v[4 * i] = (fkey(sv4.x) & ~127u) | (unsigned)ib; v[4 * i + 1] = (fkey(sv4.y) & ~127u) | (unsigned)(ib - 1);
;             v[4 * i + 2] = (fkey(sv4.z) & ~127u) | (unsigned)(ib - 2); v[4 * i + 3] = (fkey(sv4.w) & ~127u) | (unsigned)(ib - 3);
;         }
	v_and_or_b32 v1, v1, s99, v170

; DI unsigned fkey(float f) { const unsigned u = __float_as_uint(f); return (u & 0x80000000u) ? ~u : (u | 0x80000000u); }
; DI void topk_phase(unsigned char* smem_, const bf16_t* __restrict__ qp, const bf16_t* __restrict__ keys, int* __restrict__ eidx, float* __restrict__ gate) {
;     ...
;         for (int i = 0; i < 8; ++i) {
;             const f32x4 sv4 = *(const f32x4*)(S + row * LDS_ + 32 * q + 4 * i);
;             const int ib = 127 - (32 * q + 4 * i);
;             v[4 * i] = (fkey(sv4.x) & ~127u) | (unsigned)ib; v[4 * i + 1] = (fkey(sv4.y) & ~127u) | (unsigned)(ib - 1);
;             v[4 * i + 2] = (fkey(sv4.z) & ~127u) | (unsigned)(ib - 2); v[4 * i + 3] = (fkey(sv4.w) & ~127u) | (unsigned)(ib - 3);
;         }
	v_bitop3_b32 v2, v16, s98, v2 bitop3:0x56
	v_ashrrev_i32_e32 v16, 31, v3


; DI unsigned fkey(float f) { const unsigned u = __float_as_uint(f); return (u & 0x80000000u) ? ~u : (u | 0x80000000u); }
; DI void topk_phase(unsigned char* smem_, const bf16_t* __restrict__ qp, const bf16_t* __restrict__ keys, int* __restrict__ eidx, float* __restrict__ gate) {
;     ...
;         for (int i = 0; i < 8; ++i) {
;             const f32x4 sv4 = *(const f32x4*)(S + row * LDS_ + 32 * q + 4 * i);
;             const int ib = 127 - (32 * q + 4 * i);
;             v[4 * i] = (fkey(sv4.x) & ~127u) | (unsigned)ib; v[4 * i + 1] = (fkey(sv4.y) & ~127u) | (unsigned)(ib - 1);
;             v[4 * i + 2] = (fkey(sv4.z) & ~127u) | (unsigned)(ib - 2); v[4 * i + 3] = (fkey(sv4.w) & ~127u) | (unsigned)(ib - 3);
;         }
	v_and_or_b32 v2, v2, s99, v170

; DI unsigned fkey(float f) { const unsigned u = __float_as_uint(f); return (u & 0x80000000u) ? ~u : (u | 0x80000000u); }
; DI void topk_phase(unsigned char* smem_, const bf16_t* __restrict__ qp, const bf16_t* __restrict__ keys, int* __restrict__ eidx, float* __restrict__ gate) {
;     ...
;         for (int i = 0; i < 8; ++i) {
;             const f32x4 sv4 = *(const f32x4*)(S + row * LDS_ + 32 * q + 4 * i);
;             const int ib = 127 - (32 * q + 4 * i);
;             v[4 * i] = (fkey(sv4.x) & ~127u) | (unsigned)ib; v[4 * i + 1] = (fkey(sv4.y) & ~127u) | (unsigned)(ib - 1);
;             v[4 * i + 2] = (fkey(sv4.z) & ~127u) | (unsigned)(ib - 2); v[4 * i + 3] = (fkey(sv4.w) & ~127u) | (unsigned)(ib - 3);
;         }
	v_bitop3_b32 v3, v16, s98, v3 bitop3:0x56
	v_ashrrev_i32_e32 v16, 31, v4


; DI unsigned fkey(float f) { const unsigned u = __float_as_uint(f); return (u & 0x80000000u) ? ~u : (u | 0x80000000u); }
; DI void topk_phase(unsigned char* smem_, const bf16_t* __restrict__ qp, const bf16_t* __restrict__ keys, int* __restrict__ eidx, float* __restrict__ gate) {
;     ...
;         for (int i = 0; i < 8; ++i) {
;             const f32x4 sv4 = *(const f32x4*)(S + row * LDS_ + 32 * q + 4 * i);
;             const int ib = 127 - (32 * q + 4 * i);
;             v[4 * i] = (fkey(sv4.x) & ~127u) | (unsigned)ib; v[4 * i + 1] = (fkey(sv4.y) & ~127u) | (unsigned)(ib - 1);
;             v[4 * i + 2] = (fkey(sv4.z) & ~127u) | (unsigned)(ib - 2); v[4 * i + 3] = (fkey(sv4.w) & ~127u) | (unsigned)(ib - 3);
;         }
	v_and_or_b32 v3, v3, s99, v170

; DI unsigned fkey(float f) { const unsigned u = __float_as_uint(f); return (u & 0x80000000u) ? ~u : (u | 0x80000000u); }
; DI void topk_phase(unsigned char* smem_, const bf16_t* __restrict__ qp, const bf16_t* __restrict__ keys, int* __restrict__ eidx, float* __restrict__ gate) {
;     ...
;         for (int i = 0; i < 8; ++i) {
;             const f32x4 sv4 = *(const f32x4*)(S + row * LDS_ + 32 * q + 4 * i);
;             const int ib = 127 - (32 * q + 4 * i);
;             v[4 * i] = (fkey(sv4.x) & ~127u) | (unsigned)ib; v[4 * i + 1] = (fkey(sv4.y) & ~127u) | (unsigned)(ib - 1);
;             v[4 * i + 2] = (fkey(sv4.z) & ~127u) | (unsigned)(ib - 2); v[4 * i + 3] = (fkey(sv4.w) & ~127u) | (unsigned)(ib - 3);
;         }
	v_bitop3_b32 v4, v16, s98, v4 bitop3:0x56
	v_ashrrev_i32_e32 v16, 31, v5


; DI unsigned fkey(float f) { const unsigned u = __float_as_uint(f); return (u & 0x80000000u) ? ~u : (u | 0x80000000u); }
; DI void topk_phase(unsigned char* smem_, const bf16_t* __restrict__ qp, const bf16_t* __restrict__ keys, int* __restrict__ eidx, float* __restrict__ gate) {
;     ...
;         for (int i = 0; i < 8; ++i) {
;             const f32x4 sv4 = *(const f32x4*)(S + row * LDS_ + 32 * q + 4 * i);
;             const int ib = 127 - (32 * q + 4 * i);
;             v[4 * i] = (fkey(sv4.x) & ~127u) | (unsigned)ib; v[4 * i + 1] = (fkey(sv4.y) & ~127u) | (unsigned)(ib - 1);
;             v[4 * i + 2] = (fkey(sv4.z) & ~127u) | (unsigned)(ib - 2); v[4 * i + 3] = (fkey(sv4.w) & ~127u) | (unsigned)(ib - 3);
;         }
	v_and_or_b32 v4, v4, s99, v177

; DI unsigned fkey(float f) { const unsigned u = __float_as_uint(f); return (u & 0x80000000u) ? ~u : (u | 0x80000000u); }
; DI void topk_phase(unsigned char* smem_, const bf16_t* __restrict__ qp, const bf16_t* __restrict__ keys, int* __restrict__ eidx, float* __restrict__ gate) {
;     ...
;         for (int i = 0; i < 8; ++i) {
;             const f32x4 sv4 = *(const f32x4*)(S + row * LDS_ + 32 * q + 4 * i);
;             const int ib = 127 - (32 * q + 4 * i);
;             v[4 * i] = (fkey(sv4.x) & ~127u) | (unsigned)ib; v[4 * i + 1] = (fkey(sv4.y) & ~127u) | (unsigned)(ib - 1);
;             v[4 * i + 2] = (fkey(sv4.z) & ~127u) | (unsigned)(ib - 2); v[4 * i + 3] = (fkey(sv4.w) & ~127u) | (unsigned)(ib - 3);
;         }
	v_bitop3_b32 v5, v16, s98, v5 bitop3:0x56
	v_ashrrev_i32_e32 v16, 31, v6


; DI unsigned fkey(float f) { const unsigned u = __float_as_uint(f); return (u & 0x80000000u) ? ~u : (u | 0x80000000u); }
; DI void topk_phase(unsigned char* smem_, const bf16_t* __restrict__ qp, const bf16_t* __restrict__ keys, int* __restrict__ eidx, float* __restrict__ gate) {
;     ...
;         for (int i = 0; i < 8; ++i) {
;             const f32x4 sv4 = *(const f32x4*)(S + row * LDS_ + 32 * q + 4 * i);
;             const int ib = 127 - (32 * q + 4 * i);
;             v[4 * i] = (fkey(sv4.x) & ~127u) | (unsigned)ib; v[4 * i + 1] = (fkey(sv4.y) & ~127u) | (unsigned)(ib - 1);
;             v[4 * i + 2] = (fkey(sv4.z) & ~127u) | (unsigned)(ib - 2); v[4 * i + 3] = (fkey(sv4.w) & ~127u) | (unsigned)(ib - 3);
;         }
	v_and_or_b32 v5, v5, s99, v177

; DI unsigned fkey(float f) { const unsigned u = __float_as_uint(f); return (u & 0x80000000u) ? ~u : (u | 0x80000000u); }
; DI void topk_phase(unsigned char* smem_, const bf16_t* __restrict__ qp, const bf16_t* __restrict__ keys, int* __restrict__ eidx, float* __restrict__ gate) {
;     ...
;         for (int i = 0; i < 8; ++i) {
;             const f32x4 sv4 = *(const f32x4*)(S + row * LDS_ + 32 * q + 4 * i);
;             const int ib = 127 - (32 * q + 4 * i);
;             v[4 * i] = (fkey(sv4.x) & ~127u) | (unsigned)ib; v[4 * i + 1] = (fkey(sv4.y) & ~127u) | (unsigned)(ib - 1);
;             v[4 * i + 2] = (fkey(sv4.z) & ~127u) | (unsigned)(ib - 2); v[4 * i + 3] = (fkey(sv4.w) & ~127u) | (unsigned)(ib - 3);
;         }
	v_bitop3_b32 v6, v16, s98, v6 bitop3:0x56
	v_ashrrev_i32_e32 v16, 31, v7


; DI unsigned fkey(float f) { const unsigned u = __float_as_uint(f); return (u & 0x80000000u) ? ~u : (u | 0x80000000u); }
; DI void topk_phase(unsigned char* smem_, const bf16_t* __restrict__ qp, const bf16_t* __restrict__ keys, int* __restrict__ eidx, float* __restrict__ gate) {
;     ...
;         for (int i = 0; i < 8; ++i) {
;             const f32x4 sv4 = *(const f32x4*)(S + row * LDS_ + 32 * q + 4 * i);
;             const int ib = 127 - (32 * q + 4 * i);
;             v[4 * i] = (fkey(sv4.x) & ~127u) | (unsigned)ib; v[4 * i + 1] = (fkey(sv4.y) & ~127u) | (unsigned)(ib - 1);
;             v[4 * i + 2] = (fkey(sv4.z) & ~127u) | (unsigned)(ib - 2); v[4 * i + 3] = (fkey(sv4.w) & ~127u) | (unsigned)(ib - 3);
;         }
	v_and_or_b32 v6, v6, s99, v177

; DI unsigned fkey(float f) { const unsigned u = __float_as_uint(f); return (u & 0x80000000u) ? ~u : (u | 0x80000000u); }
; DI void topk_phase(unsigned char* smem_, const bf16_t* __restrict__ qp, const bf16_t* __restrict__ keys, int* __restrict__ eidx, float* __restrict__ gate) {
;     ...
;         for (int i = 0; i < 8; ++i) {
;             const f32x4 sv4 = *(const f32x4*)(S + row * LDS_ + 32 * q + 4 * i);
;             const int ib = 127 - (32 * q + 4 * i);
;             v[4 * i] = (fkey(sv4.x) & ~127u) | (unsigned)ib; v[4 * i + 1] = (fkey(sv4.y) & ~127u) | (unsigned)(ib - 1);
;             v[4 * i + 2] = (fkey(sv4.z) & ~127u) | (unsigned)(ib - 2); v[4 * i + 3] = (fkey(sv4.w) & ~127u) | (unsigned)(ib - 3);
;         }
	v_bitop3_b32 v7, v16, s98, v7 bitop3:0x56
	v_ashrrev_i32_e32 v16, 31, v8


; DI unsigned fkey(float f) { const unsigned u = __float_as_uint(f); return (u & 0x80000000u) ? ~u : (u | 0x80000000u); }
; DI void topk_phase(unsigned char* smem_, const bf16_t* __restrict__ qp, const bf16_t* __restrict__ keys, int* __restrict__ eidx, float* __restrict__ gate) {
;     ...
;         for (int i = 0; i < 8; ++i) {
;             const f32x4 sv4 = *(const f32x4*)(S + row * LDS_ + 32 * q + 4 * i);
;             const int ib = 127 - (32 * q + 4 * i);
;             v[4 * i] = (fkey(sv4.x) & ~127u) | (unsigned)ib; v[4 * i + 1] = (fkey(sv4.y) & ~127u) | (unsigned)(ib - 1);
;             v[4 * i + 2] = (fkey(sv4.z) & ~127u) | (unsigned)(ib - 2); v[4 * i + 3] = (fkey(sv4.w) & ~127u) | (unsigned)(ib - 3);
;         }
	v_and_or_b32 v7, v7, s99, v177

; DI unsigned fkey(float f) { const unsigned u = __float_as_uint(f); return (u & 0x80000000u) ? ~u : (u | 0x80000000u); }
; DI void topk_phase(unsigned char* smem_, const bf16_t* __restrict__ qp, const bf16_t* __restrict__ keys, int* __restrict__ eidx, float* __restrict__ gate) {
;     ...
;         for (int i = 0; i < 8; ++i) {
;             const f32x4 sv4 = *(const f32x4*)(S + row * LDS_ + 32 * q + 4 * i);
;             const int ib = 127 - (32 * q + 4 * i);
;             v[4 * i] = (fkey(sv4.x) & ~127u) | (unsigned)ib; v[4 * i + 1] = (fkey(sv4.y) & ~127u) | (unsigned)(ib - 1);
;             v[4 * i + 2] = (fkey(sv4.z) & ~127u) | (unsigned)(ib - 2); v[4 * i + 3] = (fkey(sv4.w) & ~127u) | (unsigned)(ib - 3);
;         }
	v_bitop3_b32 v8, v16, s98, v8 bitop3:0x56
	v_ashrrev_i32_e32 v16, 31, v9


; DI unsigned fkey(float f) { const unsigned u = __float_as_uint(f); return (u & 0x80000000u) ? ~u : (u | 0x80000000u); }
; DI void topk_phase(unsigned char* smem_, const bf16_t* __restrict__ qp, const bf16_t* __restrict__ keys, int* __restrict__ eidx, float* __restrict__ gate) {
;     ...
;         for (int i = 0; i < 8; ++i) {
;             const f32x4 sv4 = *(const f32x4*)(S + row * LDS_ + 32 * q + 4 * i);
;             const int ib = 127 - (32 * q + 4 * i);
;             v[4 * i] = (fkey(sv4.x) & ~127u) | (unsigned)ib; v[4 * i + 1] = (fkey(sv4.y) & ~127u) | (unsigned)(ib - 1);
;             v[4 * i + 2] = (fkey(sv4.z) & ~127u) | (unsigned)(ib - 2); v[4 * i + 3] = (fkey(sv4.w) & ~127u) | (unsigned)(ib - 3);
;         }
	v_and_or_b32 v8, v8, s99, v178

; DI unsigned fkey(float f) { const unsigned u = __float_as_uint(f); return (u & 0x80000000u) ? ~u : (u | 0x80000000u); }
; DI void topk_phase(unsigned char* smem_, const bf16_t* __restrict__ qp, const bf16_t* __restrict__ keys, int* __restrict__ eidx, float* __restrict__ gate) {
;     ...
;         for (int i = 0; i < 8; ++i) {
;             const f32x4 sv4 = *(const f32x4*)(S + row * LDS_ + 32 * q + 4 * i);
;             const int ib = 127 - (32 * q + 4 * i);
;             v[4 * i] = (fkey(sv4.x) & ~127u) | (unsigned)ib; v[4 * i + 1] = (fkey(sv4.y) & ~127u) | (unsigned)(ib - 1);
;             v[4 * i + 2] = (fkey(sv4.z) & ~127u) | (unsigned)(ib - 2); v[4 * i + 3] = (fkey(sv4.w) & ~127u) | (unsigned)(ib - 3);
;         }
	v_bitop3_b32 v9, v16, s98, v9 bitop3:0x56
	v_ashrrev_i32_e32 v16, 31, v10


; DI unsigned fkey(float f) { const unsigned u = __float_as_uint(f); return (u & 0x80000000u) ? ~u : (u | 0x80000000u); }
; DI void topk_phase(unsigned char* smem_, const bf16_t* __restrict__ qp, const bf16_t* __restrict__ keys, int* __restrict__ eidx, float* __restrict__ gate) {
;     ...
;         for (int i = 0; i < 8; ++i) {
;             const f32x4 sv4 = *(const f32x4*)(S + row * LDS_ + 32 * q + 4 * i);
;             const int ib = 127 - (32 * q + 4 * i);
;             v[4 * i] = (fkey(sv4.x) & ~127u) | (unsigned)ib; v[4 * i + 1] = (fkey(sv4.y) & ~127u) | (unsigned)(ib - 1);
;             v[4 * i + 2] = (fkey(sv4.z) & ~127u) | (unsigned)(ib - 2); v[4 * i + 3] = (fkey(sv4.w) & ~127u) | (unsigned)(ib - 3);
;         }
	v_and_or_b32 v9, v9, s99, v178

; DI unsigned fkey(float f) { const unsigned u = __float_as_uint(f); return (u & 0x80000000u) ? ~u : (u | 0x80000000u); }
; DI void topk_phase(unsigned char* smem_, const bf16_t* __restrict__ qp, const bf16_t* __restrict__ keys, int* __restrict__ eidx, float* __restrict__ gate) {
;     ...
;         for (int i = 0; i < 8; ++i) {
;             const f32x4 sv4 = *(const f32x4*)(S + row * LDS_ + 32 * q + 4 * i);
;             const int ib = 127 - (32 * q + 4 * i);
;             v[4 * i] = (fkey(sv4.x) & ~127u) | (unsigned)ib; v[4 * i + 1] = (fkey(sv4.y) & ~127u) | (unsigned)(ib - 1);
;             v[4 * i + 2] = (fkey(sv4.z) & ~127u) | (unsigned)(ib - 2); v[4 * i + 3] = (fkey(sv4.w) & ~127u) | (unsigned)(ib - 3);
;         }
	v_bitop3_b32 v10, v16, s98, v10 bitop3:0x56
	v_and_or_b32 v10, v10, s99, v178

; DI unsigned fkey(float f) { const unsigned u = __float_as_uint(f); return (u & 0x80000000u) ? ~u : (u | 0x80000000u); }
; DI void topk_phase(unsigned char* smem_, const bf16_t* __restrict__ qp, const bf16_t* __restrict__ keys, int* __restrict__ eidx, float* __restrict__ gate) {
;     ...
;         for (int i = 0; i < 8; ++i) {
;             const f32x4 sv4 = *(const f32x4*)(S + row * LDS_ + 32 * q + 4 * i);
;             const int ib = 127 - (32 * q + 4 * i);
;             v[4 * i] = (fkey(sv4.x) & ~127u) | (unsigned)ib; v[4 * i + 1] = (fkey(sv4.y) & ~127u) | (unsigned)(ib - 1);
;             v[4 * i + 2] = (fkey(sv4.z) & ~127u) | (unsigned)(ib - 2); v[4 * i + 3] = (fkey(sv4.w) & ~127u) | (unsigned)(ib - 3);
;         }
	v_add_u32_e32 v16, -2, v10
	v_not_b32_e32 v10, v11
	v_or_b32_e32 v17, 0x80000000, v11
	v_cmp_gt_i32_e32 vcc, 0, v11
	v_ashrrev_i32_e32 v11, 31, v12

; DI unsigned fkey(float f) { const unsigned u = __float_as_uint(f); return (u & 0x80000000u) ? ~u : (u | 0x80000000u); }
; DI void topk_phase(unsigned char* smem_, const bf16_t* __restrict__ qp, const bf16_t* __restrict__ keys, int* __restrict__ eidx, float* __restrict__ gate) {
;     ...
;         for (int i = 0; i < 8; ++i) {
;             const f32x4 sv4 = *(const f32x4*)(S + row * LDS_ + 32 * q + 4 * i);
;             const int ib = 127 - (32 * q + 4 * i);
;             v[4 * i] = (fkey(sv4.x) & ~127u) | (unsigned)ib; v[4 * i + 1] = (fkey(sv4.y) & ~127u) | (unsigned)(ib - 1);
;             v[4 * i + 2] = (fkey(sv4.z) & ~127u) | (unsigned)(ib - 2); v[4 * i + 3] = (fkey(sv4.w) & ~127u) | (unsigned)(ib - 3);
;         }
	v_cndmask_b32_e32 v10, v17, v10, vcc
	v_and_or_b32 v10, v10, s99, v178

; DI unsigned fkey(float f) { const unsigned u = __float_as_uint(f); return (u & 0x80000000u) ? ~u : (u | 0x80000000u); }
; DI void topk_phase(unsigned char* smem_, const bf16_t* __restrict__ qp, const bf16_t* __restrict__ keys, int* __restrict__ eidx, float* __restrict__ gate) {
;     ...
;         for (int i = 0; i < 8; ++i) {
;             const f32x4 sv4 = *(const f32x4*)(S + row * LDS_ + 32 * q + 4 * i);
;             const int ib = 127 - (32 * q + 4 * i);
;             v[4 * i] = (fkey(sv4.x) & ~127u) | (unsigned)ib; v[4 * i + 1] = (fkey(sv4.y) & ~127u) | (unsigned)(ib - 1);
;             v[4 * i + 2] = (fkey(sv4.z) & ~127u) | (unsigned)(ib - 2); v[4 * i + 3] = (fkey(sv4.w) & ~127u) | (unsigned)(ib - 3);
;         }
	v_add_u32_e32 v17, -3, v10


; DI unsigned fkey(float f) { const unsigned u = __float_as_uint(f); return (u & 0x80000000u) ? ~u : (u | 0x80000000u); }
; DI void topk_phase(unsigned char* smem_, const bf16_t* __restrict__ qp, const bf16_t* __restrict__ keys, int* __restrict__ eidx, float* __restrict__ gate) {
;     ...
;         for (int i = 0; i < 8; ++i) {
;             const f32x4 sv4 = *(const f32x4*)(S + row * LDS_ + 32 * q + 4 * i);
;             const int ib = 127 - (32 * q + 4 * i);
;             v[4 * i] = (fkey(sv4.x) & ~127u) | (unsigned)ib; v[4 * i + 1] = (fkey(sv4.y) & ~127u) | (unsigned)(ib - 1);
;             v[4 * i + 2] = (fkey(sv4.z) & ~127u) | (unsigned)(ib - 2); v[4 * i + 3] = (fkey(sv4.w) & ~127u) | (unsigned)(ib - 3);
;         }
	v_add_u32_e32 v1, -1, v1
	v_add_u32_e32 v2, -2, v2
	v_bitop3_b32 v10, v11, s98, v12 bitop3:0x56
	v_and_or_b32 v10, v10, s99, v179

; DI unsigned fkey(float f) { const unsigned u = __float_as_uint(f); return (u & 0x80000000u) ? ~u : (u | 0x80000000u); }
; DI void topk_phase(unsigned char* smem_, const bf16_t* __restrict__ qp, const bf16_t* __restrict__ keys, int* __restrict__ eidx, float* __restrict__ gate) {
;     ...
;         for (int i = 0; i < 8; ++i) {
;             const f32x4 sv4 = *(const f32x4*)(S + row * LDS_ + 32 * q + 4 * i);
;             const int ib = 127 - (32 * q + 4 * i);
;             v[4 * i] = (fkey(sv4.x) & ~127u) | (unsigned)ib; v[4 * i + 1] = (fkey(sv4.y) & ~127u) | (unsigned)(ib - 1);
;             v[4 * i + 2] = (fkey(sv4.z) & ~127u) | (unsigned)(ib - 2); v[4 * i + 3] = (fkey(sv4.w) & ~127u) | (unsigned)(ib - 3);
;         }
	v_mov_b32_e32 v18, v10
	v_ashrrev_i32_e32 v10, 31, v13


; DI unsigned fkey(float f) { const unsigned u = __float_as_uint(f); return (u & 0x80000000u) ? ~u : (u | 0x80000000u); }
; DI void topk_phase(unsigned char* smem_, const bf16_t* __restrict__ qp, const bf16_t* __restrict__ keys, int* __restrict__ eidx, float* __restrict__ gate) {
;     ...
;         for (int i = 0; i < 8; ++i) {
;             const f32x4 sv4 = *(const f32x4*)(S + row * LDS_ + 32 * q + 4 * i);
;             const int ib = 127 - (32 * q + 4 * i);
;             v[4 * i] = (fkey(sv4.x) & ~127u) | (unsigned)ib; v[4 * i + 1] = (fkey(sv4.y) & ~127u) | (unsigned)(ib - 1);
;             v[4 * i + 2] = (fkey(sv4.z) & ~127u) | (unsigned)(ib - 2); v[4 * i + 3] = (fkey(sv4.w) & ~127u) | (unsigned)(ib - 3);
;         }
	v_add_u32_e32 v3, -3, v3

; DI unsigned fkey(float f) { const unsigned u = __float_as_uint(f); return (u & 0x80000000u) ? ~u : (u | 0x80000000u); }
; DI void topk_phase(unsigned char* smem_, const bf16_t* __restrict__ qp, const bf16_t* __restrict__ keys, int* __restrict__ eidx, float* __restrict__ gate) {
;     ...
;         for (int i = 0; i < 8; ++i) {
;             const f32x4 sv4 = *(const f32x4*)(S + row * LDS_ + 32 * q + 4 * i);
;             const int ib = 127 - (32 * q + 4 * i);
;             v[4 * i] = (fkey(sv4.x) & ~127u) | (unsigned)ib; v[4 * i + 1] = (fkey(sv4.y) & ~127u) | (unsigned)(ib - 1);
;             v[4 * i + 2] = (fkey(sv4.z) & ~127u) | (unsigned)(ib - 2); v[4 * i + 3] = (fkey(sv4.w) & ~127u) | (unsigned)(ib - 3);
;         }
	v_bitop3_b32 v10, v10, s98, v13 bitop3:0x56
	v_and_or_b32 v10, v10, s99, v179

; DI unsigned fkey(float f) { const unsigned u = __float_as_uint(f); return (u & 0x80000000u) ? ~u : (u | 0x80000000u); }
; DI void topk_phase(unsigned char* smem_, const bf16_t* __restrict__ qp, const bf16_t* __restrict__ keys, int* __restrict__ eidx, float* __restrict__ gate) {
;     ...
;         for (int i = 0; i < 8; ++i) {
;             const f32x4 sv4 = *(const f32x4*)(S + row * LDS_ + 32 * q + 4 * i);
;             const int ib = 127 - (32 * q + 4 * i);
;             v[4 * i] = (fkey(sv4.x) & ~127u) | (unsigned)ib; v[4 * i + 1] = (fkey(sv4.y) & ~127u) | (unsigned)(ib - 1);
;             v[4 * i + 2] = (fkey(sv4.z) & ~127u) | (unsigned)(ib - 2); v[4 * i + 3] = (fkey(sv4.w) & ~127u) | (unsigned)(ib - 3);
;         }
	v_add_u32_e32 v19, -1, v10
	v_ashrrev_i32_e32 v10, 31, v14


; DI unsigned fkey(float f) { const unsigned u = __float_as_uint(f); return (u & 0x80000000u) ? ~u : (u | 0x80000000u); }
; DI void topk_phase(unsigned char* smem_, const bf16_t* __restrict__ qp, const bf16_t* __restrict__ keys, int* __restrict__ eidx, float* __restrict__ gate) {
;     ...
;         for (int i = 0; i < 8; ++i) {
;             const f32x4 sv4 = *(const f32x4*)(S + row * LDS_ + 32 * q + 4 * i);
;             const int ib = 127 - (32 * q + 4 * i);
;             v[4 * i] = (fkey(sv4.x) & ~127u) | (unsigned)ib; v[4 * i + 1] = (fkey(sv4.y) & ~127u) | (unsigned)(ib - 1);
;             v[4 * i + 2] = (fkey(sv4.z) & ~127u) | (unsigned)(ib - 2); v[4 * i + 3] = (fkey(sv4.w) & ~127u) | (unsigned)(ib - 3);
;         }
	v_add_u32_e32 v5, -1, v5
	v_add_u32_e32 v6, -2, v6
	v_bitop3_b32 v10, v10, s98, v14 bitop3:0x56
	v_and_or_b32 v10, v10, s99, v179

; DI unsigned fkey(float f) { const unsigned u = __float_as_uint(f); return (u & 0x80000000u) ? ~u : (u | 0x80000000u); }
; DI void topk_phase(unsigned char* smem_, const bf16_t* __restrict__ qp, const bf16_t* __restrict__ keys, int* __restrict__ eidx, float* __restrict__ gate) {
;     ...
;         for (int i = 0; i < 8; ++i) {
;             const f32x4 sv4 = *(const f32x4*)(S + row * LDS_ + 32 * q + 4 * i);
;             const int ib = 127 - (32 * q + 4 * i);
;             v[4 * i] = (fkey(sv4.x) & ~127u) | (unsigned)ib; v[4 * i + 1] = (fkey(sv4.y) & ~127u) | (unsigned)(ib - 1);
;             v[4 * i + 2] = (fkey(sv4.z) & ~127u) | (unsigned)(ib - 2); v[4 * i + 3] = (fkey(sv4.w) & ~127u) | (unsigned)(ib - 3);
;         }
	v_add_u32_e32 v14, -2, v10
	ds_read_b128 v[10:13], v171 offset:17472
	v_cmp_gt_i32_e32 vcc, 0, v15
	v_add_u32_e32 v7, -3, v7

; DI unsigned fkey(float f) { const unsigned u = __float_as_uint(f); return (u & 0x80000000u) ? ~u : (u | 0x80000000u); }
; DI void topk_phase(unsigned char* smem_, const bf16_t* __restrict__ qp, const bf16_t* __restrict__ keys, int* __restrict__ eidx, float* __restrict__ gate) {
;     ...
;         for (int i = 0; i < 8; ++i) {
;             const f32x4 sv4 = *(const f32x4*)(S + row * LDS_ + 32 * q + 4 * i);
;             const int ib = 127 - (32 * q + 4 * i);
;             v[4 * i] = (fkey(sv4.x) & ~127u) | (unsigned)ib; v[4 * i + 1] = (fkey(sv4.y) & ~127u) | (unsigned)(ib - 1);
;             v[4 * i + 2] = (fkey(sv4.z) & ~127u) | (unsigned)(ib - 2); v[4 * i + 3] = (fkey(sv4.w) & ~127u) | (unsigned)(ib - 3);
;         }
	v_cndmask_b32_e32 v15, v21, v20, vcc
	s_waitcnt lgkmcnt(0)
	v_ashrrev_i32_e32 v20, 31, v10


; DI unsigned fkey(float f) { const unsigned u = __float_as_uint(f); return (u & 0x80000000u) ? ~u : (u | 0x80000000u); }
; DI void topk_phase(unsigned char* smem_, const bf16_t* __restrict__ qp, const bf16_t* __restrict__ keys, int* __restrict__ eidx, float* __restrict__ gate) {
;     ...
;         for (int i = 0; i < 8; ++i) {
;             const f32x4 sv4 = *(const f32x4*)(S + row * LDS_ + 32 * q + 4 * i);
;             const int ib = 127 - (32 * q + 4 * i);
;             v[4 * i] = (fkey(sv4.x) & ~127u) | (unsigned)ib; v[4 * i + 1] = (fkey(sv4.y) & ~127u) | (unsigned)(ib - 1);
;             v[4 * i + 2] = (fkey(sv4.z) & ~127u) | (unsigned)(ib - 2); v[4 * i + 3] = (fkey(sv4.w) & ~127u) | (unsigned)(ib - 3);
;         }
	v_not_b32_e32 v23, v13
	v_or_b32_e32 v24, 0x80000000, v13
	v_bitop3_b32 v10, v20, s98, v10 bitop3:0x56
	v_and_or_b32 v10, v10, s99, v180

; DI unsigned fkey(float f) { const unsigned u = __float_as_uint(f); return (u & 0x80000000u) ? ~u : (u | 0x80000000u); }
; DI void topk_phase(unsigned char* smem_, const bf16_t* __restrict__ qp, const bf16_t* __restrict__ keys, int* __restrict__ eidx, float* __restrict__ gate) {
;     ...
;         for (int i = 0; i < 8; ++i) {
;             const f32x4 sv4 = *(const f32x4*)(S + row * LDS_ + 32 * q + 4 * i);
;             const int ib = 127 - (32 * q + 4 * i);
;             v[4 * i] = (fkey(sv4.x) & ~127u) | (unsigned)ib; v[4 * i + 1] = (fkey(sv4.y) & ~127u) | (unsigned)(ib - 1);
;             v[4 * i + 2] = (fkey(sv4.z) & ~127u) | (unsigned)(ib - 2); v[4 * i + 3] = (fkey(sv4.w) & ~127u) | (unsigned)(ib - 3);
;         }
	v_mov_b32_e32 v20, v10
	v_not_b32_e32 v10, v11
	v_or_b32_e32 v21, 0x80000000, v11
	v_cmp_gt_i32_e32 vcc, 0, v11
	v_ashrrev_i32_e32 v11, 31, v12
	v_and_or_b32 v15, v15, s99, v179
	v_cndmask_b32_e32 v10, v21, v10, vcc
	v_and_or_b32 v10, v10, s99, v180

; DI unsigned fkey(float f) { const unsigned u = __float_as_uint(f); return (u & 0x80000000u) ? ~u : (u | 0x80000000u); }
; DI void topk_phase(unsigned char* smem_, const bf16_t* __restrict__ qp, const bf16_t* __restrict__ keys, int* __restrict__ eidx, float* __restrict__ gate) {
;     ...
;         for (int i = 0; i < 8; ++i) {
;             const f32x4 sv4 = *(const f32x4*)(S + row * LDS_ + 32 * q + 4 * i);
;             const int ib = 127 - (32 * q + 4 * i);
;             v[4 * i] = (fkey(sv4.x) & ~127u) | (unsigned)ib; v[4 * i + 1] = (fkey(sv4.y) & ~127u) | (unsigned)(ib - 1);
;             v[4 * i + 2] = (fkey(sv4.z) & ~127u) | (unsigned)(ib - 2); v[4 * i + 3] = (fkey(sv4.w) & ~127u) | (unsigned)(ib - 3);
;         }
	v_add_u32_e32 v21, -1, v10


; DI unsigned fkey(float f) { const unsigned u = __float_as_uint(f); return (u & 0x80000000u) ? ~u : (u | 0x80000000u); }
; DI void topk_phase(unsigned char* smem_, const bf16_t* __restrict__ qp, const bf16_t* __restrict__ keys, int* __restrict__ eidx, float* __restrict__ gate) {
;     ...
;         for (int i = 0; i < 8; ++i) {
;             const f32x4 sv4 = *(const f32x4*)(S + row * LDS_ + 32 * q + 4 * i);
;             const int ib = 127 - (32 * q + 4 * i);
;             v[4 * i] = (fkey(sv4.x) & ~127u) | (unsigned)ib; v[4 * i + 1] = (fkey(sv4.y) & ~127u) | (unsigned)(ib - 1);
;             v[4 * i + 2] = (fkey(sv4.z) & ~127u) | (unsigned)(ib - 2); v[4 * i + 3] = (fkey(sv4.w) & ~127u) | (unsigned)(ib - 3);
;         }
	v_add_u32_e32 v9, -1, v9
	v_bitop3_b32 v10, v11, s98, v12 bitop3:0x56
	v_and_or_b32 v10, v10, s99, v180

; DI unsigned fkey(float f) { const unsigned u = __float_as_uint(f); return (u & 0x80000000u) ? ~u : (u | 0x80000000u); }
; DI void topk_phase(unsigned char* smem_, const bf16_t* __restrict__ qp, const bf16_t* __restrict__ keys, int* __restrict__ eidx, float* __restrict__ gate) {
;     ...
;         for (int i = 0; i < 8; ++i) {
;             const f32x4 sv4 = *(const f32x4*)(S + row * LDS_ + 32 * q + 4 * i);
;             const int ib = 127 - (32 * q + 4 * i);
;             v[4 * i] = (fkey(sv4.x) & ~127u) | (unsigned)ib; v[4 * i + 1] = (fkey(sv4.y) & ~127u) | (unsigned)(ib - 1);
;             v[4 * i + 2] = (fkey(sv4.z) & ~127u) | (unsigned)(ib - 2); v[4 * i + 3] = (fkey(sv4.w) & ~127u) | (unsigned)(ib - 3);
;         }
	v_add_u32_e32 v22, -2, v10
	v_cmp_gt_i32_e32 vcc, 0, v13
	ds_read_b128 v[10:13], v171 offset:17488
	v_add_u32_e32 v15, -3, v15
	v_cndmask_b32_e32 v23, v24, v23, vcc
	v_and_or_b32 v23, v23, s99, v180

; DI unsigned fkey(float f) { const unsigned u = __float_as_uint(f); return (u & 0x80000000u) ? ~u : (u | 0x80000000u); }
; DI void topk_phase(unsigned char* smem_, const bf16_t* __restrict__ qp, const bf16_t* __restrict__ keys, int* __restrict__ eidx, float* __restrict__ gate) {
;     ...
;         for (int i = 0; i < 8; ++i) {
;             const f32x4 sv4 = *(const f32x4*)(S + row * LDS_ + 32 * q + 4 * i);
;             const int ib = 127 - (32 * q + 4 * i);
;             v[4 * i] = (fkey(sv4.x) & ~127u) | (unsigned)ib; v[4 * i + 1] = (fkey(sv4.y) & ~127u) | (unsigned)(ib - 1);
;             v[4 * i + 2] = (fkey(sv4.z) & ~127u) | (unsigned)(ib - 2); v[4 * i + 3] = (fkey(sv4.w) & ~127u) | (unsigned)(ib - 3);
;         }
	s_waitcnt lgkmcnt(0)
	v_ashrrev_i32_e32 v24, 31, v10


; DI unsigned fkey(float f) { const unsigned u = __float_as_uint(f); return (u & 0x80000000u) ? ~u : (u | 0x80000000u); }
; DI void topk_phase(unsigned char* smem_, const bf16_t* __restrict__ qp, const bf16_t* __restrict__ keys, int* __restrict__ eidx, float* __restrict__ gate) {
;     ...
;         for (int i = 0; i < 8; ++i) {
;             const f32x4 sv4 = *(const f32x4*)(S + row * LDS_ + 32 * q + 4 * i);
;             const int ib = 127 - (32 * q + 4 * i);
;             v[4 * i] = (fkey(sv4.x) & ~127u) | (unsigned)ib; v[4 * i + 1] = (fkey(sv4.y) & ~127u) | (unsigned)(ib - 1);
;             v[4 * i + 2] = (fkey(sv4.z) & ~127u) | (unsigned)(ib - 2); v[4 * i + 3] = (fkey(sv4.w) & ~127u) | (unsigned)(ib - 3);
;         }
	v_not_b32_e32 v27, v13
	v_or_b32_e32 v28, 0x80000000, v13
	v_bitop3_b32 v10, v24, s98, v10 bitop3:0x56
	v_and_or_b32 v10, v10, s99, v181

; DI unsigned fkey(float f) { const unsigned u = __float_as_uint(f); return (u & 0x80000000u) ? ~u : (u | 0x80000000u); }
; DI void topk_phase(unsigned char* smem_, const bf16_t* __restrict__ qp, const bf16_t* __restrict__ keys, int* __restrict__ eidx, float* __restrict__ gate) {
;     ...
;         for (int i = 0; i < 8; ++i) {
;             const f32x4 sv4 = *(const f32x4*)(S + row * LDS_ + 32 * q + 4 * i);
;             const int ib = 127 - (32 * q + 4 * i);
;             v[4 * i] = (fkey(sv4.x) & ~127u) | (unsigned)ib; v[4 * i + 1] = (fkey(sv4.y) & ~127u) | (unsigned)(ib - 1);
;             v[4 * i + 2] = (fkey(sv4.z) & ~127u) | (unsigned)(ib - 2); v[4 * i + 3] = (fkey(sv4.w) & ~127u) | (unsigned)(ib - 3);
;         }
	v_mov_b32_e32 v24, v10
	v_not_b32_e32 v10, v11
	v_or_b32_e32 v25, 0x80000000, v11
	v_cmp_gt_i32_e32 vcc, 0, v11
	v_ashrrev_i32_e32 v11, 31, v12
	v_add_u32_e32 v23, -3, v23
	v_cndmask_b32_e32 v10, v25, v10, vcc
	v_and_or_b32 v10, v10, s99, v181

; DI unsigned fkey(float f) { const unsigned u = __float_as_uint(f); return (u & 0x80000000u) ? ~u : (u | 0x80000000u); }
; DI void topk_phase(unsigned char* smem_, const bf16_t* __restrict__ qp, const bf16_t* __restrict__ keys, int* __restrict__ eidx, float* __restrict__ gate) {
;     ...
;         for (int i = 0; i < 8; ++i) {
;             const f32x4 sv4 = *(const f32x4*)(S + row * LDS_ + 32 * q + 4 * i);
;             const int ib = 127 - (32 * q + 4 * i);
;             v[4 * i] = (fkey(sv4.x) & ~127u) | (unsigned)ib; v[4 * i + 1] = (fkey(sv4.y) & ~127u) | (unsigned)(ib - 1);
;             v[4 * i + 2] = (fkey(sv4.z) & ~127u) | (unsigned)(ib - 2); v[4 * i + 3] = (fkey(sv4.w) & ~127u) | (unsigned)(ib - 3);
;         }
	v_add_u32_e32 v25, -1, v10


; DI unsigned fkey(float f) { const unsigned u = __float_as_uint(f); return (u & 0x80000000u) ? ~u : (u | 0x80000000u); }
; DI void topk_phase(unsigned char* smem_, const bf16_t* __restrict__ qp, const bf16_t* __restrict__ keys, int* __restrict__ eidx, float* __restrict__ gate) {
;     ...
;         for (int i = 0; i < 8; ++i) {
;             const f32x4 sv4 = *(const f32x4*)(S + row * LDS_ + 32 * q + 4 * i);
;             const int ib = 127 - (32 * q + 4 * i);
;             v[4 * i] = (fkey(sv4.x) & ~127u) | (unsigned)ib; v[4 * i + 1] = (fkey(sv4.y) & ~127u) | (unsigned)(ib - 1);
;             v[4 * i + 2] = (fkey(sv4.z) & ~127u) | (unsigned)(ib - 2); v[4 * i + 3] = (fkey(sv4.w) & ~127u) | (unsigned)(ib - 3);
;         }
	s_nop 1
	v_bitop3_b32 v10, v11, s98, v12 bitop3:0x56
	v_and_or_b32 v10, v10, s99, v181

; DI unsigned fkey(float f) { const unsigned u = __float_as_uint(f); return (u & 0x80000000u) ? ~u : (u | 0x80000000u); }
; DI void topk_phase(unsigned char* smem_, const bf16_t* __restrict__ qp, const bf16_t* __restrict__ keys, int* __restrict__ eidx, float* __restrict__ gate) {
;     ...
;         for (int i = 0; i < 8; ++i) {
;             const f32x4 sv4 = *(const f32x4*)(S + row * LDS_ + 32 * q + 4 * i);
;             const int ib = 127 - (32 * q + 4 * i);
;             v[4 * i] = (fkey(sv4.x) & ~127u) | (unsigned)ib; v[4 * i + 1] = (fkey(sv4.y) & ~127u) | (unsigned)(ib - 1);
;             v[4 * i + 2] = (fkey(sv4.z) & ~127u) | (unsigned)(ib - 2); v[4 * i + 3] = (fkey(sv4.w) & ~127u) | (unsigned)(ib - 3);
;         }
	v_add_u32_e32 v26, -2, v10
	v_cmp_gt_i32_e32 vcc, 0, v13
	ds_read_b128 v[10:13], v171 offset:17504
	s_waitcnt lgkmcnt(0)
	v_ashrrev_i32_e32 v29, 31, v10
	v_cndmask_b32_e32 v27, v28, v27, vcc


; DI unsigned fkey(float f) { const unsigned u = __float_as_uint(f); return (u & 0x80000000u) ? ~u : (u | 0x80000000u); }
; DI void topk_phase(unsigned char* smem_, const bf16_t* __restrict__ qp, const bf16_t* __restrict__ keys, int* __restrict__ eidx, float* __restrict__ gate) {
;     ...
;         for (int i = 0; i < 8; ++i) {
;             const f32x4 sv4 = *(const f32x4*)(S + row * LDS_ + 32 * q + 4 * i);
;             const int ib = 127 - (32 * q + 4 * i);
;             v[4 * i] = (fkey(sv4.x) & ~127u) | (unsigned)ib; v[4 * i + 1] = (fkey(sv4.y) & ~127u) | (unsigned)(ib - 1);
;             v[4 * i + 2] = (fkey(sv4.z) & ~127u) | (unsigned)(ib - 2); v[4 * i + 3] = (fkey(sv4.w) & ~127u) | (unsigned)(ib - 3);
;         }
	v_not_b32_e32 v31, v13
	v_or_b32_e32 v116, 0x80000000, v13
	v_bitop3_b32 v10, v29, s98, v10 bitop3:0x56
	v_and_or_b32 v10, v10, s99, v182

; DI unsigned fkey(float f) { const unsigned u = __float_as_uint(f); return (u & 0x80000000u) ? ~u : (u | 0x80000000u); }
; DI void topk_phase(unsigned char* smem_, const bf16_t* __restrict__ qp, const bf16_t* __restrict__ keys, int* __restrict__ eidx, float* __restrict__ gate) {
;     ...
;         for (int i = 0; i < 8; ++i) {
;             const f32x4 sv4 = *(const f32x4*)(S + row * LDS_ + 32 * q + 4 * i);
;             const int ib = 127 - (32 * q + 4 * i);
;             v[4 * i] = (fkey(sv4.x) & ~127u) | (unsigned)ib; v[4 * i + 1] = (fkey(sv4.y) & ~127u) | (unsigned)(ib - 1);
;             v[4 * i + 2] = (fkey(sv4.z) & ~127u) | (unsigned)(ib - 2); v[4 * i + 3] = (fkey(sv4.w) & ~127u) | (unsigned)(ib - 3);
;         }
	v_mov_b32_e32 v28, v10
	v_not_b32_e32 v10, v11
	v_or_b32_e32 v29, 0x80000000, v11
	v_cmp_gt_i32_e32 vcc, 0, v11
	v_ashrrev_i32_e32 v11, 31, v12
	v_and_or_b32 v27, v27, s99, v181
	v_cndmask_b32_e32 v10, v29, v10, vcc
	v_and_or_b32 v10, v10, s99, v182

; DI unsigned fkey(float f) { const unsigned u = __float_as_uint(f); return (u & 0x80000000u) ? ~u : (u | 0x80000000u); }
; DI void topk_phase(unsigned char* smem_, const bf16_t* __restrict__ qp, const bf16_t* __restrict__ keys, int* __restrict__ eidx, float* __restrict__ gate) {
;     ...
;         for (int i = 0; i < 8; ++i) {
;             const f32x4 sv4 = *(const f32x4*)(S + row * LDS_ + 32 * q + 4 * i);
;             const int ib = 127 - (32 * q + 4 * i);
;             v[4 * i] = (fkey(sv4.x) & ~127u) | (unsigned)ib; v[4 * i + 1] = (fkey(sv4.y) & ~127u) | (unsigned)(ib - 1);
;             v[4 * i + 2] = (fkey(sv4.z) & ~127u) | (unsigned)(ib - 2); v[4 * i + 3] = (fkey(sv4.w) & ~127u) | (unsigned)(ib - 3);
;         }
	v_add_u32_e32 v29, -1, v10


; DI unsigned fkey(float f) { const unsigned u = __float_as_uint(f); return (u & 0x80000000u) ? ~u : (u | 0x80000000u); }
; DI void topk_phase(unsigned char* smem_, const bf16_t* __restrict__ qp, const bf16_t* __restrict__ keys, int* __restrict__ eidx, float* __restrict__ gate) {
;     ...
;         for (int i = 0; i < 8; ++i) {
;             const f32x4 sv4 = *(const f32x4*)(S + row * LDS_ + 32 * q + 4 * i);
;             const int ib = 127 - (32 * q + 4 * i);
;             v[4 * i] = (fkey(sv4.x) & ~127u) | (unsigned)ib; v[4 * i + 1] = (fkey(sv4.y) & ~127u) | (unsigned)(ib - 1);
;             v[4 * i + 2] = (fkey(sv4.z) & ~127u) | (unsigned)(ib - 2); v[4 * i + 3] = (fkey(sv4.w) & ~127u) | (unsigned)(ib - 3);
;         }
	v_add_u32_e32 v27, -3, v27
	v_bitop3_b32 v10, v11, s98, v12 bitop3:0x56
	v_and_or_b32 v10, v10, s99, v182

; DI unsigned fkey(float f) { const unsigned u = __float_as_uint(f); return (u & 0x80000000u) ? ~u : (u | 0x80000000u); }
; DI void topk_phase(unsigned char* smem_, const bf16_t* __restrict__ qp, const bf16_t* __restrict__ keys, int* __restrict__ eidx, float* __restrict__ gate) {
;     ...
;         for (int i = 0; i < 8; ++i) {
;             const f32x4 sv4 = *(const f32x4*)(S + row * LDS_ + 32 * q + 4 * i);
;             const int ib = 127 - (32 * q + 4 * i);
;             v[4 * i] = (fkey(sv4.x) & ~127u) | (unsigned)ib; v[4 * i + 1] = (fkey(sv4.y) & ~127u) | (unsigned)(ib - 1);
;             v[4 * i + 2] = (fkey(sv4.z) & ~127u) | (unsigned)(ib - 2); v[4 * i + 3] = (fkey(sv4.w) & ~127u) | (unsigned)(ib - 3);
;         }
	v_add_u32_e32 v30, -2, v10
	v_cmp_gt_i32_e32 vcc, 0, v13
	ds_read_b128 v[10:13], v171 offset:17520
	s_waitcnt lgkmcnt(0)
	v_ashrrev_i32_e32 v117, 31, v10
	v_cndmask_b32_e32 v31, v116, v31, vcc


; DI unsigned fkey(float f) { const unsigned u = __float_as_uint(f); return (u & 0x80000000u) ? ~u : (u | 0x80000000u); }
; DI void topk_phase(unsigned char* smem_, const bf16_t* __restrict__ qp, const bf16_t* __restrict__ keys, int* __restrict__ eidx, float* __restrict__ gate) {
;     ...
;         for (int i = 0; i < 8; ++i) {
;             const f32x4 sv4 = *(const f32x4*)(S + row * LDS_ + 32 * q + 4 * i);
;             const int ib = 127 - (32 * q + 4 * i);
;             v[4 * i] = (fkey(sv4.x) & ~127u) | (unsigned)ib; v[4 * i + 1] = (fkey(sv4.y) & ~127u) | (unsigned)(ib - 1);
;             v[4 * i + 2] = (fkey(sv4.z) & ~127u) | (unsigned)(ib - 2); v[4 * i + 3] = (fkey(sv4.w) & ~127u) | (unsigned)(ib - 3);
;         }
	v_and_or_b32 v31, v31, s99, v182

; DI unsigned fkey(float f) { const unsigned u = __float_as_uint(f); return (u & 0x80000000u) ? ~u : (u | 0x80000000u); }
; DI void topk_phase(unsigned char* smem_, const bf16_t* __restrict__ qp, const bf16_t* __restrict__ keys, int* __restrict__ eidx, float* __restrict__ gate) {
;     ...
;         for (int i = 0; i < 8; ++i) {
;             const f32x4 sv4 = *(const f32x4*)(S + row * LDS_ + 32 * q + 4 * i);
;             const int ib = 127 - (32 * q + 4 * i);
;             v[4 * i] = (fkey(sv4.x) & ~127u) | (unsigned)ib; v[4 * i + 1] = (fkey(sv4.y) & ~127u) | (unsigned)(ib - 1);
;             v[4 * i + 2] = (fkey(sv4.z) & ~127u) | (unsigned)(ib - 2); v[4 * i + 3] = (fkey(sv4.w) & ~127u) | (unsigned)(ib - 3);
;         }
	v_bitop3_b32 v10, v117, s98, v10 bitop3:0x56
	v_ashrrev_i32_e32 v116, 31, v11


; DI unsigned fkey(float f) { const unsigned u = __float_as_uint(f); return (u & 0x80000000u) ? ~u : (u | 0x80000000u); }
; DI void topk_phase(unsigned char* smem_, const bf16_t* __restrict__ qp, const bf16_t* __restrict__ keys, int* __restrict__ eidx, float* __restrict__ gate) {
;     ...
;         for (int i = 0; i < 8; ++i) {
;             const f32x4 sv4 = *(const f32x4*)(S + row * LDS_ + 32 * q + 4 * i);
;             const int ib = 127 - (32 * q + 4 * i);
;             v[4 * i] = (fkey(sv4.x) & ~127u) | (unsigned)ib; v[4 * i + 1] = (fkey(sv4.y) & ~127u) | (unsigned)(ib - 1);
;             v[4 * i + 2] = (fkey(sv4.z) & ~127u) | (unsigned)(ib - 2); v[4 * i + 3] = (fkey(sv4.w) & ~127u) | (unsigned)(ib - 3);
;         }
	v_and_or_b32 v10, v10, s99, v183

; DI unsigned fkey(float f) { const unsigned u = __float_as_uint(f); return (u & 0x80000000u) ? ~u : (u | 0x80000000u); }
; DI void topk_phase(unsigned char* smem_, const bf16_t* __restrict__ qp, const bf16_t* __restrict__ keys, int* __restrict__ eidx, float* __restrict__ gate) {
;     ...
;         for (int i = 0; i < 8; ++i) {
;             const f32x4 sv4 = *(const f32x4*)(S + row * LDS_ + 32 * q + 4 * i);
;             const int ib = 127 - (32 * q + 4 * i);
;             v[4 * i] = (fkey(sv4.x) & ~127u) | (unsigned)ib; v[4 * i + 1] = (fkey(sv4.y) & ~127u) | (unsigned)(ib - 1);
;             v[4 * i + 2] = (fkey(sv4.z) & ~127u) | (unsigned)(ib - 2); v[4 * i + 3] = (fkey(sv4.w) & ~127u) | (unsigned)(ib - 3);
;         }
	v_bitop3_b32 v11, v116, s98, v11 bitop3:0x56
	v_ashrrev_i32_e32 v116, 31, v12


; DI unsigned fkey(float f) { const unsigned u = __float_as_uint(f); return (u & 0x80000000u) ? ~u : (u | 0x80000000u); }
; DI void topk_phase(unsigned char* smem_, const bf16_t* __restrict__ qp, const bf16_t* __restrict__ keys, int* __restrict__ eidx, float* __restrict__ gate) {
;     ...
;         for (int i = 0; i < 8; ++i) {
;             const f32x4 sv4 = *(const f32x4*)(S + row * LDS_ + 32 * q + 4 * i);
;             const int ib = 127 - (32 * q + 4 * i);
;             v[4 * i] = (fkey(sv4.x) & ~127u) | (unsigned)ib; v[4 * i + 1] = (fkey(sv4.y) & ~127u) | (unsigned)(ib - 1);
;             v[4 * i + 2] = (fkey(sv4.z) & ~127u) | (unsigned)(ib - 2); v[4 * i + 3] = (fkey(sv4.w) & ~127u) | (unsigned)(ib - 3);
;         }
	v_and_or_b32 v11, v11, s99, v183

; DI unsigned fkey(float f) { const unsigned u = __float_as_uint(f); return (u & 0x80000000u) ? ~u : (u | 0x80000000u); }
; DI void topk_phase(unsigned char* smem_, const bf16_t* __restrict__ qp, const bf16_t* __restrict__ keys, int* __restrict__ eidx, float* __restrict__ gate) {
;     ...
;         for (int i = 0; i < 8; ++i) {
;             const f32x4 sv4 = *(const f32x4*)(S + row * LDS_ + 32 * q + 4 * i);
;             const int ib = 127 - (32 * q + 4 * i);
;             v[4 * i] = (fkey(sv4.x) & ~127u) | (unsigned)ib; v[4 * i + 1] = (fkey(sv4.y) & ~127u) | (unsigned)(ib - 1);
;             v[4 * i + 2] = (fkey(sv4.z) & ~127u) | (unsigned)(ib - 2); v[4 * i + 3] = (fkey(sv4.w) & ~127u) | (unsigned)(ib - 3);
;         }
	v_bitop3_b32 v12, v116, s98, v12 bitop3:0x56
	v_ashrrev_i32_e32 v116, 31, v13


; DI unsigned fkey(float f) { const unsigned u = __float_as_uint(f); return (u & 0x80000000u) ? ~u : (u | 0x80000000u); }
; DI void topk_phase(unsigned char* smem_, const bf16_t* __restrict__ qp, const bf16_t* __restrict__ keys, int* __restrict__ eidx, float* __restrict__ gate) {
;     ...
;         for (int i = 0; i < 8; ++i) {
;             const f32x4 sv4 = *(const f32x4*)(S + row * LDS_ + 32 * q + 4 * i);
;             const int ib = 127 - (32 * q + 4 * i);
;             v[4 * i] = (fkey(sv4.x) & ~127u) | (unsigned)ib; v[4 * i + 1] = (fkey(sv4.y) & ~127u) | (unsigned)(ib - 1);
;             v[4 * i + 2] = (fkey(sv4.z) & ~127u) | (unsigned)(ib - 2); v[4 * i + 3] = (fkey(sv4.w) & ~127u) | (unsigned)(ib - 3);
;         }
	v_and_or_b32 v12, v12, s99, v183

; DI unsigned fkey(float f) { const unsigned u = __float_as_uint(f); return (u & 0x80000000u) ? ~u : (u | 0x80000000u); }
; DI void topk_phase(unsigned char* smem_, const bf16_t* __restrict__ qp, const bf16_t* __restrict__ keys, int* __restrict__ eidx, float* __restrict__ gate) {
;     ...
;         for (int i = 0; i < 8; ++i) {
;             const f32x4 sv4 = *(const f32x4*)(S + row * LDS_ + 32 * q + 4 * i);
;             const int ib = 127 - (32 * q + 4 * i);
;             v[4 * i] = (fkey(sv4.x) & ~127u) | (unsigned)ib; v[4 * i + 1] = (fkey(sv4.y) & ~127u) | (unsigned)(ib - 1);
;             v[4 * i + 2] = (fkey(sv4.z) & ~127u) | (unsigned)(ib - 2); v[4 * i + 3] = (fkey(sv4.w) & ~127u) | (unsigned)(ib - 3);
;         }
	v_bitop3_b32 v13, v116, s98, v13 bitop3:0x56
	v_and_or_b32 v13, v13, s99, v183

; DI unsigned fkey(float f) { const unsigned u = __float_as_uint(f); return (u & 0x80000000u) ? ~u : (u | 0x80000000u); }
; DI void topk_phase(unsigned char* smem_, const bf16_t* __restrict__ qp, const bf16_t* __restrict__ keys, int* __restrict__ eidx, float* __restrict__ gate) {
;     ...
;         for (int i = 0; i < 8; ++i) {
;             const f32x4 sv4 = *(const f32x4*)(S + row * LDS_ + 32 * q + 4 * i);
;             const int ib = 127 - (32 * q + 4 * i);
;             v[4 * i] = (fkey(sv4.x) & ~127u) | (unsigned)ib; v[4 * i + 1] = (fkey(sv4.y) & ~127u) | (unsigned)(ib - 1);
;             v[4 * i + 2] = (fkey(sv4.z) & ~127u) | (unsigned)(ib - 2); v[4 * i + 3] = (fkey(sv4.w) & ~127u) | (unsigned)(ib - 3);
;         }
	v_add_u32_e32 v31, -3, v31

; DI unsigned fkey(float f) { const unsigned u = __float_as_uint(f); return (u & 0x80000000u) ? ~u : (u | 0x80000000u); }
; template <int N> DI void bitonic_sort_desc(unsigned (&v)[N]) {
; #pragma unroll
;     for (int k = 2; k <= N; k <<= 1)
; #pragma unroll
;         for (int j = k >> 1; j > 0; j >>= 1)
; #pragma unroll
;             for (int i = 0; i < N; ++i) { const int l = i ^ j; if (l > i) { if ((i & k) == 0) cswap(v[i], v[l]); else cswap(v[l], v[i]); } }
; }
; DI void topk_phase(unsigned char* smem_, const bf16_t* __restrict__ qp, const bf16_t* __restrict__ keys, int* __restrict__ eidx, float* __restrict__ gate) {
;     ...
;         for (int i = 0; i < 8; ++i) {
;             const f32x4 sv4 = *(const f32x4*)(S + row * LDS_ + 32 * q + 4 * i);
;             const int ib = 127 - (32 * q + 4 * i);
;             v[4 * i] = (fkey(sv4.x) & ~127u) | (unsigned)ib; v[4 * i + 1] = (fkey(sv4.y) & ~127u) | (unsigned)(ib - 1);
;             v[4 * i + 2] = (fkey(sv4.z) & ~127u) | (unsigned)(ib - 2); v[4 * i + 3] = (fkey(sv4.w) & ~127u) | (unsigned)(ib - 3);
;         }
	v_add_u32_e32 v11, -1, v11
	v_add_u32_e32 v12, -2, v12
	v_add_u32_e32 v13, -3, v13
	v_max_u32_e32 v116, v0, v1
	v_min_u32_e32 v0, v0, v1
	v_max_u32_e32 v1, v3, v2
	v_min_u32_e32 v2, v3, v2
	v_max_u32_e32 v3, v4, v5
	v_min_u32_e32 v4, v4, v5
	v_max_u32_e32 v5, v7, v6
	v_min_u32_e32 v6, v7, v6
	v_max_u32_e32 v7, v8, v9
	v_min_u32_e32 v8, v8, v9
	v_max_u32_e32 v9, v17, v16
	v_min_u32_e32 v16, v17, v16
	v_max_u32_e32 v17, v18, v19
	v_min_u32_e32 v18, v18, v19
	v_max_u32_e32 v19, v15, v14
	v_min_u32_e32 v14, v15, v14
	v_max_u32_e32 v15, v20, v21
	v_min_u32_e32 v20, v20, v21
	v_max_u32_e32 v21, v23, v22
	v_min_u32_e32 v22, v23, v22
	v_max_u32_e32 v23, v24, v25
	v_min_u32_e32 v24, v24, v25
	v_max_u32_e32 v25, v27, v26
	v_min_u32_e32 v26, v27, v26
	v_max_u32_e32 v27, v28, v29
	v_min_u32_e32 v28, v28, v29
	v_max_u32_e32 v29, v31, v30
	v_min_u32_e32 v30, v31, v30
	v_max_u32_e32 v31, v10, v11
	v_min_u32_e32 v10, v10, v11
	v_max_u32_e32 v11, v13, v12
	v_min_u32_e32 v12, v13, v12
	v_max_u32_e32 v13, v116, v2
	v_min_u32_e32 v2, v116, v2
	v_max_u32_e32 v116, v0, v1
	v_min_u32_e32 v0, v0, v1
	v_max_u32_e32 v1, v6, v3
	v_min_u32_e32 v3, v6, v3
	v_max_u32_e32 v6, v5, v4
	v_min_u32_e32 v4, v5, v4
	v_max_u32_e32 v5, v7, v16
	v_min_u32_e32 v7, v7, v16
	v_max_u32_e32 v16, v8, v9
	v_min_u32_e32 v8, v8, v9
	v_max_u32_e32 v9, v14, v17
	v_min_u32_e32 v14, v14, v17
	v_max_u32_e32 v17, v19, v18
	v_min_u32_e32 v18, v19, v18
	v_max_u32_e32 v19, v15, v22
	v_min_u32_e32 v15, v15, v22
	v_max_u32_e32 v22, v20, v21
	v_min_u32_e32 v20, v20, v21
	v_max_u32_e32 v21, v26, v23
	v_min_u32_e32 v23, v26, v23
	v_max_u32_e32 v26, v25, v24
	v_min_u32_e32 v24, v25, v24
	v_max_u32_e32 v25, v27, v30
	v_min_u32_e32 v27, v27, v30
	v_max_u32_e32 v30, v28, v29
	v_min_u32_e32 v28, v28, v29
	v_max_u32_e32 v29, v12, v31
	v_min_u32_e32 v12, v12, v31
	v_max_u32_e32 v31, v11, v10
	v_min_u32_e32 v10, v11, v10
	v_max_u32_e32 v11, v13, v116
	v_min_u32_e32 v13, v13, v116
	v_max_u32_e32 v116, v2, v0
	v_min_u32_e32 v0, v2, v0
	v_max_u32_e32 v2, v4, v3
	v_min_u32_e32 v3, v4, v3
	v_max_u32_e32 v4, v6, v1
	v_min_u32_e32 v1, v6, v1
	v_max_u32_e32 v6, v5, v16
	v_min_u32_e32 v5, v5, v16
	v_max_u32_e32 v16, v7, v8
	v_min_u32_e32 v7, v7, v8
	v_max_u32_e32 v8, v18, v14
	v_min_u32_e32 v14, v18, v14
	v_max_u32_e32 v18, v17, v9
	v_min_u32_e32 v9, v17, v9
	v_max_u32_e32 v17, v19, v22
	v_min_u32_e32 v19, v19, v22
	v_max_u32_e32 v22, v15, v20
	v_min_u32_e32 v15, v15, v20
	v_max_u32_e32 v20, v24, v23
	v_min_u32_e32 v23, v24, v23
	v_max_u32_e32 v24, v26, v21
	v_min_u32_e32 v21, v26, v21
	v_max_u32_e32 v26, v25, v30
	v_min_u32_e32 v25, v25, v30
	v_max_u32_e32 v30, v27, v28
	v_min_u32_e32 v27, v27, v28
	v_max_u32_e32 v28, v10, v12
	v_min_u32_e32 v10, v10, v12
	v_max_u32_e32 v12, v31, v29
	v_min_u32_e32 v29, v31, v29
	v_max_u32_e32 v31, v11, v3
	v_min_u32_e32 v3, v11, v3
	v_max_u32_e32 v11, v13, v2
	v_min_u32_e32 v2, v13, v2
	v_max_u32_e32 v13, v116, v1
	v_min_u32_e32 v1, v116, v1
	v_max_u32_e32 v116, v0, v4
	v_min_u32_e32 v0, v0, v4
	v_max_u32_e32 v4, v14, v6
	v_min_u32_e32 v6, v14, v6
	v_max_u32_e32 v14, v8, v5
	v_min_u32_e32 v5, v8, v5
	v_max_u32_e32 v8, v9, v16
	v_min_u32_e32 v9, v9, v16
	v_max_u32_e32 v16, v18, v7
	v_min_u32_e32 v7, v18, v7
	v_max_u32_e32 v18, v17, v23
	v_min_u32_e32 v17, v17, v23
	v_max_u32_e32 v23, v19, v20
	v_min_u32_e32 v19, v19, v20
	v_max_u32_e32 v20, v22, v21
	v_min_u32_e32 v21, v22, v21
	v_max_u32_e32 v22, v15, v24
	v_min_u32_e32 v15, v15, v24
	v_max_u32_e32 v24, v10, v26
	v_min_u32_e32 v10, v10, v26
	v_max_u32_e32 v26, v28, v25
	v_min_u32_e32 v25, v28, v25
	v_max_u32_e32 v28, v29, v30
	v_min_u32_e32 v29, v29, v30
	v_max_u32_e32 v30, v12, v27
	v_min_u32_e32 v12, v12, v27
	v_max_u32_e32 v27, v31, v13
	v_min_u32_e32 v13, v31, v13
	v_max_u32_e32 v31, v11, v116
	v_min_u32_e32 v11, v11, v116
	v_max_u32_e32 v116, v3, v1
	v_min_u32_e32 v1, v3, v1
	v_max_u32_e32 v3, v2, v0
	v_min_u32_e32 v0, v2, v0
	v_max_u32_e32 v2, v9, v6
	v_min_u32_e32 v6, v9, v6
	v_max_u32_e32 v9, v7, v5
	v_min_u32_e32 v5, v7, v5
	v_max_u32_e32 v7, v8, v4
	v_min_u32_e32 v4, v8, v4
	v_max_u32_e32 v8, v16, v14
	v_min_u32_e32 v14, v16, v14
	v_max_u32_e32 v16, v18, v20
	v_min_u32_e32 v18, v18, v20
	v_max_u32_e32 v20, v23, v22
	v_min_u32_e32 v22, v23, v22
	v_max_u32_e32 v23, v17, v21
	v_min_u32_e32 v17, v17, v21
	v_max_u32_e32 v21, v19, v15
	v_min_u32_e32 v15, v19, v15
	v_max_u32_e32 v19, v29, v10
	v_min_u32_e32 v10, v29, v10
	v_max_u32_e32 v29, v12, v25
	v_min_u32_e32 v12, v12, v25
	v_max_u32_e32 v25, v28, v24
	v_min_u32_e32 v24, v28, v24
	v_max_u32_e32 v28, v30, v26
	v_min_u32_e32 v26, v30, v26
	v_max_u32_e32 v30, v27, v31
	v_min_u32_e32 v27, v27, v31
	v_max_u32_e32 v31, v13, v11
	v_min_u32_e32 v11, v13, v11
	v_max_u32_e32 v13, v116, v3
	v_min_u32_e32 v3, v116, v3
	v_max_u32_e32 v116, v1, v0
	v_min_u32_e32 v0, v1, v0
	v_max_u32_e32 v1, v5, v6
	v_min_u32_e32 v5, v5, v6
	v_max_u32_e32 v6, v9, v2
	v_min_u32_e32 v2, v9, v2
	v_max_u32_e32 v9, v14, v4
	v_min_u32_e32 v4, v14, v4
	v_max_u32_e32 v14, v8, v7
	v_min_u32_e32 v7, v8, v7
	v_max_u32_e32 v8, v16, v20
	v_min_u32_e32 v16, v16, v20
	v_max_u32_e32 v20, v18, v22
	v_min_u32_e32 v18, v18, v22
	v_max_u32_e32 v22, v23, v21
	v_min_u32_e32 v21, v23, v21
	v_max_u32_e32 v23, v17, v15
	v_min_u32_e32 v15, v17, v15
	v_max_u32_e32 v17, v12, v10
	v_min_u32_e32 v10, v12, v10
	v_max_u32_e32 v12, v29, v19
	v_min_u32_e32 v19, v29, v19
	v_max_u32_e32 v29, v26, v24
	v_min_u32_e32 v24, v26, v24
	v_max_u32_e32 v26, v28, v25
	v_min_u32_e32 v25, v28, v25
	v_max_u32_e32 v28, v30, v5
	v_min_u32_e32 v5, v30, v5
	v_max_u32_e32 v30, v27, v1
	v_min_u32_e32 v1, v27, v1
	v_max_u32_e32 v27, v31, v2
	v_min_u32_e32 v2, v31, v2
; template <int N> DI void bitonic_sort_desc(unsigned (&v)[N]) {
; #pragma unroll
;     for (int k = 2; k <= N; k <<= 1)
; #pragma unroll
;         for (int j = k >> 1; j > 0; j >>= 1)
; #pragma unroll
;             for (int i = 0; i < N; ++i) { const int l = i ^ j; if (l > i) { if ((i & k) == 0) cswap(v[i], v[l]); else cswap(v[l], v[i]); } }
; }
; DI void merge_top16(unsigned (&v)[16], int st) {
;     unsigned x[16];
; #pragma unroll
;     for (int i = 0; i < 16; ++i) x[i] = (unsigned)__shfl_xor((int)v[15 - i], st);
; #pragma unroll
;     for (int i = 0; i < 16; ++i) v[i] = max(v[i], x[i]);
; #pragma unroll
;     for (int j = 8; j > 0; j >>= 1)
; #pragma unroll
;         for (int i = 0; i < 16; ++i) { const int l = i ^ j; if (l > i) cswap(v[i], v[l]); }
; }
	v_max_u32_e32 v31, v11, v6
	v_min_u32_e32 v6, v11, v6
	v_max_u32_e32 v11, v13, v4
	v_min_u32_e32 v4, v13, v4
	v_max_u32_e32 v13, v3, v9
	v_min_u32_e32 v3, v3, v9
	v_max_u32_e32 v9, v116, v7
	v_min_u32_e32 v7, v116, v7
	v_max_u32_e32 v116, v0, v14
	v_min_u32_e32 v0, v0, v14
	v_max_u32_e32 v14, v10, v8
	v_min_u32_e32 v8, v10, v8
	v_max_u32_e32 v10, v17, v16
	v_min_u32_e32 v16, v17, v16
	v_max_u32_e32 v17, v19, v20
	v_min_u32_e32 v19, v19, v20
	v_max_u32_e32 v20, v12, v18
	v_min_u32_e32 v12, v12, v18
	v_max_u32_e32 v18, v24, v22
	v_min_u32_e32 v22, v24, v22
	v_max_u32_e32 v24, v29, v21
	v_min_u32_e32 v21, v29, v21
	v_max_u32_e32 v29, v25, v23
	v_min_u32_e32 v23, v25, v23
	v_max_u32_e32 v25, v26, v15
	v_min_u32_e32 v15, v26, v15
	v_max_u32_e32 v26, v28, v11
	v_min_u32_e32 v11, v28, v11
	v_max_u32_e32 v28, v30, v13
	v_min_u32_e32 v13, v30, v13
	v_max_u32_e32 v30, v27, v9
	v_min_u32_e32 v9, v27, v9
	v_max_u32_e32 v27, v31, v116
	v_min_u32_e32 v31, v31, v116
	v_max_u32_e32 v116, v5, v4
	v_min_u32_e32 v4, v5, v4
	v_max_u32_e32 v5, v1, v3
	v_min_u32_e32 v1, v1, v3
	v_max_u32_e32 v3, v2, v7
	v_min_u32_e32 v2, v2, v7
	v_max_u32_e32 v7, v6, v0
	v_min_u32_e32 v0, v6, v0
	v_max_u32_e32 v6, v22, v8
	v_min_u32_e32 v8, v22, v8
	v_max_u32_e32 v22, v21, v16
	v_min_u32_e32 v16, v21, v16
	v_max_u32_e32 v21, v23, v19
	v_min_u32_e32 v19, v23, v19
	v_max_u32_e32 v23, v15, v12
	v_min_u32_e32 v12, v15, v12
	v_max_u32_e32 v15, v18, v14
	v_min_u32_e32 v14, v18, v14
	v_max_u32_e32 v18, v24, v10
	v_min_u32_e32 v10, v24, v10
	v_max_u32_e32 v24, v29, v17
	v_min_u32_e32 v17, v29, v17
	v_max_u32_e32 v29, v25, v20
	v_min_u32_e32 v20, v25, v20
	v_max_u32_e32 v25, v26, v30
	v_min_u32_e32 v26, v26, v30
	v_max_u32_e32 v30, v28, v27
	v_min_u32_e32 v27, v28, v27
	v_max_u32_e32 v28, v11, v9
	v_min_u32_e32 v9, v11, v9
	v_max_u32_e32 v11, v13, v31
	v_min_u32_e32 v13, v13, v31
	v_max_u32_e32 v31, v116, v3
	v_min_u32_e32 v3, v116, v3
	v_max_u32_e32 v116, v5, v7
	v_min_u32_e32 v5, v5, v7
	v_max_u32_e32 v7, v4, v2
	v_min_u32_e32 v2, v4, v2
	v_max_u32_e32 v4, v1, v0
	v_min_u32_e32 v0, v1, v0
	v_max_u32_e32 v1, v19, v8
	v_min_u32_e32 v8, v19, v8
	v_max_u32_e32 v19, v12, v16
	v_min_u32_e32 v12, v12, v16
	v_max_u32_e32 v16, v21, v6
	v_min_u32_e32 v6, v21, v6
	v_max_u32_e32 v21, v23, v22
	v_min_u32_e32 v22, v23, v22
	v_max_u32_e32 v23, v17, v14
	v_min_u32_e32 v14, v17, v14
	v_max_u32_e32 v17, v20, v10
	v_min_u32_e32 v10, v20, v10
	v_max_u32_e32 v20, v24, v15
	v_min_u32_e32 v15, v24, v15
	v_max_u32_e32 v24, v29, v18
	v_min_u32_e32 v18, v29, v18
	v_min_u32_e32 v29, v25, v30
	v_min_u32_e32 v117, v26, v27
	v_min_u32_e32 v118, v28, v11
	v_min_u32_e32 v119, v9, v13
	v_min_u32_e32 v120, v31, v116
	v_min_u32_e32 v121, v3, v5
	v_min_u32_e32 v122, v7, v4
	v_min_u32_e32 v123, v2, v0
	v_min_u32_e32 v124, v12, v8
	v_min_u32_e32 v125, v19, v1
	v_min_u32_e32 v126, v22, v6
	v_min_u32_e32 v127, v21, v16
	v_min_u32_e32 v142, v10, v14
	v_min_u32_e32 v143, v17, v23
	v_min_u32_e32 v144, v18, v15
	v_min_u32_e32 v145, v24, v20
	v_max3_u32 v25, v25, v30, v124
	v_max3_u32 v8, v29, v12, v8
	v_max3_u32 v12, v26, v27, v125
	v_max3_u32 v1, v117, v19, v1
	v_max3_u32 v11, v28, v11, v126
	v_max3_u32 v6, v118, v22, v6
	v_max3_u32 v9, v9, v13, v127
	v_max3_u32 v13, v119, v21, v16
	v_max3_u32 v16, v31, v116, v142
	v_max3_u32 v10, v120, v10, v14
	v_max3_u32 v3, v3, v5, v143
	v_max3_u32 v5, v121, v17, v23
	v_max3_u32 v4, v7, v4, v144
	v_max3_u32 v7, v122, v18, v15
	v_max3_u32 v0, v2, v0, v145
	v_max3_u32 v2, v123, v24, v20
	v_max_u32_e32 v14, v25, v16
	v_min_u32_e32 v15, v25, v16
	v_max_u32_e32 v16, v8, v10
	v_min_u32_e32 v8, v8, v10
	v_max_u32_e32 v10, v12, v3
	v_min_u32_e32 v3, v12, v3
	v_max_u32_e32 v12, v1, v5
	v_min_u32_e32 v1, v1, v5
	v_max_u32_e32 v5, v11, v4
	v_min_u32_e32 v4, v11, v4
	v_max_u32_e32 v11, v6, v7
	v_min_u32_e32 v6, v6, v7
	v_max_u32_e32 v7, v9, v0
	v_min_u32_e32 v0, v9, v0
	v_max_u32_e32 v9, v13, v2
	v_min_u32_e32 v2, v13, v2
	v_max_u32_e32 v13, v14, v5
	v_min_u32_e32 v5, v14, v5
	v_max_u32_e32 v14, v16, v11
	v_min_u32_e32 v11, v16, v11
	v_max_u32_e32 v16, v10, v7
	v_min_u32_e32 v7, v10, v7
	v_max_u32_e32 v10, v12, v9
	v_min_u32_e32 v9, v12, v9
	v_max_u32_e32 v12, v15, v4
	v_min_u32_e32 v4, v15, v4
	v_max_u32_e32 v15, v8, v6
	v_min_u32_e32 v6, v8, v6
	v_max_u32_e32 v8, v3, v0
	v_min_u32_e32 v0, v3, v0
	v_max_u32_e32 v3, v1, v2
	v_min_u32_e32 v1, v1, v2
	v_max_u32_e32 v2, v13, v16
	v_min_u32_e32 v13, v13, v16
	v_max_u32_e32 v16, v14, v10
	v_min_u32_e32 v10, v14, v10
	v_max_u32_e32 v14, v5, v7
	v_min_u32_e32 v5, v5, v7
	v_max_u32_e32 v7, v11, v9
	v_min_u32_e32 v9, v11, v9
	v_max_u32_e32 v11, v12, v8
	v_min_u32_e32 v8, v12, v8
	v_max_u32_e32 v12, v15, v3
	v_min_u32_e32 v3, v15, v3
	v_max_u32_e32 v15, v4, v0
	v_min_u32_e32 v0, v4, v0
	v_max_u32_e32 v4, v6, v1
	v_min_u32_e32 v1, v6, v1
	v_max_u32_e32 v6, v2, v16
	v_min_u32_e32 v2, v2, v16
	v_max_u32_e32 v16, v13, v10
	v_min_u32_e32 v10, v13, v10
	v_max_u32_e32 v13, v14, v7
	v_min_u32_e32 v7, v14, v7
	v_max_u32_e32 v14, v5, v9
	v_min_u32_e32 v5, v5, v9
	v_max_u32_e32 v9, v11, v12
	v_min_u32_e32 v11, v11, v12
	v_max_u32_e32 v12, v8, v3
	v_min_u32_e32 v3, v8, v3
	v_max_u32_e32 v8, v15, v4
	v_min_u32_e32 v4, v15, v4
	v_max_u32_e32 v15, v0, v1
	v_min_u32_e32 v0, v0, v1
	s_nop 1
	v_mov_b32_dpp v1, v0 quad_perm:[1,0,3,2] row_mask:0xf bank_mask:0xf
	v_mov_b32_dpp v17, v15 quad_perm:[1,0,3,2] row_mask:0xf bank_mask:0xf
	v_mov_b32_dpp v18, v4 quad_perm:[1,0,3,2] row_mask:0xf bank_mask:0xf
	v_mov_b32_dpp v19, v8 quad_perm:[1,0,3,2] row_mask:0xf bank_mask:0xf
	v_mov_b32_dpp v20, v3 quad_perm:[1,0,3,2] row_mask:0xf bank_mask:0xf
	v_mov_b32_dpp v21, v12 quad_perm:[1,0,3,2] row_mask:0xf bank_mask:0xf
	v_mov_b32_dpp v22, v11 quad_perm:[1,0,3,2] row_mask:0xf bank_mask:0xf
	v_mov_b32_dpp v23, v9 quad_perm:[1,0,3,2] row_mask:0xf bank_mask:0xf
	v_mov_b32_dpp v24, v5 quad_perm:[1,0,3,2] row_mask:0xf bank_mask:0xf
	v_mov_b32_dpp v25, v14 quad_perm:[1,0,3,2] row_mask:0xf bank_mask:0xf
	v_mov_b32_dpp v26, v7 quad_perm:[1,0,3,2] row_mask:0xf bank_mask:0xf
	v_mov_b32_dpp v27, v13 quad_perm:[1,0,3,2] row_mask:0xf bank_mask:0xf
	v_mov_b32_dpp v28, v10 quad_perm:[1,0,3,2] row_mask:0xf bank_mask:0xf
	v_mov_b32_dpp v29, v16 quad_perm:[1,0,3,2] row_mask:0xf bank_mask:0xf
	v_mov_b32_dpp v30, v2 quad_perm:[1,0,3,2] row_mask:0xf bank_mask:0xf
	v_mov_b32_dpp v31, v6 quad_perm:[1,0,3,2] row_mask:0xf bank_mask:0xf
	s_waitcnt lgkmcnt(0)
; DI void merge_top16(unsigned (&v)[16], int st) {
;     unsigned x[16];
; #pragma unroll
;     for (int i = 0; i < 16; ++i) x[i] = (unsigned)__shfl_xor((int)v[15 - i], st);
; #pragma unroll
;     for (int i = 0; i < 16; ++i) v[i] = max(v[i], x[i]);
; #pragma unroll
;     for (int j = 8; j > 0; j >>= 1)
; #pragma unroll
;         for (int i = 0; i < 16; ++i) { const int l = i ^ j; if (l > i) cswap(v[i], v[l]); }
; }
; DI void topk_phase(unsigned char* smem_, const bf16_t* __restrict__ qp, const bf16_t* __restrict__ keys, int* __restrict__ eidx, float* __restrict__ gate) {
;     ...
;         for (int i = 0; i < 16; ++i) if ((i >> 2) == q) { const int idx = 127 - (int)(t16[i] & 127u); SI[row * 32 + 16 * p + i] = idx; SV[row * 32 + 16 * p + i] = S[row * LDS_ + idx]; }
	v_max_u32_e32 v1, v6, v1
	v_max_u32_e32 v2, v2, v17
	v_max_u32_e32 v6, v16, v18
	v_max_u32_e32 v10, v10, v19
	v_max_u32_e32 v13, v13, v20
	v_max_u32_e32 v7, v7, v21
	v_max_u32_e32 v14, v14, v22
	v_max_u32_e32 v5, v5, v23
	v_max_u32_e32 v9, v9, v24
	v_max_u32_e32 v11, v11, v25
	v_max_u32_e32 v12, v12, v26
	v_max_u32_e32 v3, v3, v27
	v_max_u32_e32 v8, v8, v28
	v_max_u32_e32 v4, v4, v29
	v_max_u32_e32 v15, v15, v30
	v_max_u32_e32 v0, v0, v31
	v_max_u32_e32 v16, v1, v9
	v_min_u32_e32 v1, v1, v9
	v_max_u32_e32 v9, v2, v11
	v_min_u32_e32 v2, v2, v11
	v_max_u32_e32 v11, v6, v12
	v_min_u32_e32 v6, v6, v12
	v_max_u32_e32 v12, v10, v3
	v_min_u32_e32 v3, v10, v3
	v_max_u32_e32 v10, v13, v8
	v_min_u32_e32 v8, v13, v8
	v_max_u32_e32 v13, v7, v4
	v_min_u32_e32 v4, v7, v4
	v_max_u32_e32 v7, v14, v15
	v_min_u32_e32 v14, v14, v15
	v_max_u32_e32 v15, v5, v0
	v_min_u32_e32 v0, v5, v0
	v_max_u32_e32 v5, v16, v10
	v_min_u32_e32 v10, v16, v10
	v_max_u32_e32 v16, v9, v13
	v_min_u32_e32 v9, v9, v13
	v_max_u32_e32 v13, v11, v7
	v_min_u32_e32 v7, v11, v7
	v_max_u32_e32 v11, v12, v15
	v_min_u32_e32 v12, v12, v15
	v_max_u32_e32 v15, v1, v8
	v_min_u32_e32 v1, v1, v8
	v_max_u32_e32 v8, v2, v4
	v_min_u32_e32 v2, v2, v4
	v_max_u32_e32 v4, v6, v14
	v_min_u32_e32 v6, v6, v14
	v_max_u32_e32 v14, v3, v0
	v_min_u32_e32 v0, v3, v0
	v_max_u32_e32 v3, v5, v13
	v_min_u32_e32 v5, v5, v13
	v_max_u32_e32 v13, v16, v11
	v_min_u32_e32 v11, v16, v11
	v_max_u32_e32 v16, v10, v7
	v_min_u32_e32 v7, v10, v7
	v_max_u32_e32 v10, v9, v12
	v_min_u32_e32 v9, v9, v12
	v_max_u32_e32 v12, v15, v4
	v_min_u32_e32 v4, v15, v4
	v_max_u32_e32 v15, v8, v14
	v_min_u32_e32 v8, v8, v14
	v_max_u32_e32 v14, v1, v6
	v_min_u32_e32 v1, v1, v6
	v_max_u32_e32 v6, v2, v0
	v_min_u32_e32 v0, v2, v0
	v_max_u32_e32 v2, v3, v13
	v_min_u32_e32 v3, v3, v13
	v_max_u32_e32 v13, v5, v11
	v_min_u32_e32 v5, v5, v11
	v_max_u32_e32 v11, v16, v10
	v_min_u32_e32 v10, v16, v10
	v_max_u32_e32 v16, v7, v9
	v_min_u32_e32 v7, v7, v9
	v_max_u32_e32 v9, v12, v15
	v_min_u32_e32 v12, v12, v15
	v_max_u32_e32 v15, v4, v8
	v_min_u32_e32 v17, v4, v8
	v_max_u32_e32 v18, v14, v6
	v_min_u32_e32 v14, v14, v6
	v_max_u32_e32 v19, v1, v0
	v_min_u32_e32 v20, v1, v0
	s_nop 1
	v_mov_b32_dpp v0, v20 quad_perm:[2,3,0,1] row_mask:0xf bank_mask:0xf
	v_mov_b32_dpp v1, v19 quad_perm:[2,3,0,1] row_mask:0xf bank_mask:0xf
	v_mov_b32_dpp v4, v14 quad_perm:[2,3,0,1] row_mask:0xf bank_mask:0xf
	v_mov_b32_dpp v6, v18 quad_perm:[2,3,0,1] row_mask:0xf bank_mask:0xf
	v_mov_b32_dpp v8, v17 quad_perm:[2,3,0,1] row_mask:0xf bank_mask:0xf
	v_mov_b32_dpp v21, v15 quad_perm:[2,3,0,1] row_mask:0xf bank_mask:0xf
	v_mov_b32_dpp v22, v12 quad_perm:[2,3,0,1] row_mask:0xf bank_mask:0xf
	v_mov_b32_dpp v23, v9 quad_perm:[2,3,0,1] row_mask:0xf bank_mask:0xf
	v_mov_b32_dpp v24, v7 quad_perm:[2,3,0,1] row_mask:0xf bank_mask:0xf
	v_mov_b32_dpp v25, v16 quad_perm:[2,3,0,1] row_mask:0xf bank_mask:0xf
	v_mov_b32_dpp v26, v10 quad_perm:[2,3,0,1] row_mask:0xf bank_mask:0xf
	v_mov_b32_dpp v27, v11 quad_perm:[2,3,0,1] row_mask:0xf bank_mask:0xf
	v_mov_b32_dpp v28, v5 quad_perm:[2,3,0,1] row_mask:0xf bank_mask:0xf
	v_mov_b32_dpp v29, v13 quad_perm:[2,3,0,1] row_mask:0xf bank_mask:0xf
	v_mov_b32_dpp v30, v3 quad_perm:[2,3,0,1] row_mask:0xf bank_mask:0xf
	v_mov_b32_dpp v31, v2 quad_perm:[2,3,0,1] row_mask:0xf bank_mask:0xf
	s_waitcnt lgkmcnt(0)
	v_max_u32_e32 v0, v2, v0
	v_max_u32_e32 v1, v3, v1
	v_max_u32_e32 v2, v13, v4
	v_max_u32_e32 v3, v5, v6
	v_max_u32_e32 v4, v11, v8
	v_max_u32_e32 v5, v10, v21
	v_max_u32_e32 v6, v16, v22
	v_max_u32_e32 v7, v7, v23
	v_max_u32_e32 v8, v9, v24
	v_max_u32_e32 v9, v12, v25
	v_max_u32_e32 v10, v15, v26
	v_max_u32_e32 v11, v17, v27
	v_max_u32_e32 v12, v18, v28
	v_max_u32_e32 v13, v14, v29
	v_max_u32_e32 v14, v19, v30
	v_max_u32_e32 v15, v20, v31
	v_max_u32_e32 v16, v0, v8
	v_max_u32_e32 v17, v1, v9
	v_max_u32_e32 v18, v2, v10
	v_max_u32_e32 v19, v3, v11
	v_max_u32_e32 v20, v4, v12
	v_max_u32_e32 v21, v5, v13
	v_max_u32_e32 v22, v6, v14
	v_max_u32_e32 v23, v7, v15
	s_and_saveexec_b64 s[0:1], s[4:5]
	s_cbranch_execz .LBB0_59
	v_max_u32_e32 v24, v16, v20
	v_max_u32_e32 v25, v18, v22
	v_max_u32_e32 v27, v17, v21
	v_max_u32_e32 v28, v19, v23
	v_min_u32_e32 v26, v24, v25
	v_min_u32_e32 v29, v27, v28
	v_max_u32_e32 v24, v24, v25
	v_max_u32_e32 v25, v27, v28
	v_min_u32_e32 v30, v26, v29
	v_max_u32_e32 v29, v26, v29
	v_min_u32_e32 v26, v24, v25
	v_max_u32_e32 v24, v24, v25
	v_xor_b32_e32 v25, -1, v26
	v_xor_b32_e32 v24, -1, v24
	v_and_b32_e32 v25, 0x7f, v25
	v_and_b32_e32 v24, 0x7f, v24
	v_lshl_add_u32 v26, v24, 2, v169
	v_lshl_add_u32 v27, v25, 2, v169
	ds_read_b32 v26, v26 offset:17408
	ds_read_b32 v27, v27 offset:17408
	v_xor_b32_e32 v28, -1, v29
	s_waitcnt lgkmcnt(0)
	ds_write_b64 v175, v[26:27] offset:53248
	v_xor_b32_e32 v26, -1, v30
	v_and_b32_e32 v27, 0x7f, v26
	v_and_b32_e32 v26, 0x7f, v28
	v_lshl_add_u32 v28, v26, 2, v169
	ds_write_b128 v184, v[24:27] offset:61440
	v_lshl_add_u32 v24, v27, 2, v169
	ds_read_b32 v28, v28 offset:17408
	ds_read_b32 v29, v24 offset:17408
	s_waitcnt lgkmcnt(0)
	ds_write_b64 v184, v[28:29] offset:53256

; DI unsigned fkey(float f) { const unsigned u = __float_as_uint(f); return (u & 0x80000000u) ? ~u : (u | 0x80000000u); }
; DI void topk_phase(unsigned char* smem_, const bf16_t* __restrict__ qp, const bf16_t* __restrict__ keys, int* __restrict__ eidx, float* __restrict__ gate) {
;     ...
;         for (int i = 0; i < 8; ++i) {
;             const f32x4 sv4 = *(const f32x4*)(S + row * LDS_ + 32 * q + 4 * i);
;             const int ib = 127 - (32 * q + 4 * i);
;             v[4 * i] = (fkey(sv4.x) & ~127u) | (unsigned)ib; v[4 * i + 1] = (fkey(sv4.y) & ~127u) | (unsigned)(ib - 1);
;             v[4 * i + 2] = (fkey(sv4.z) & ~127u) | (unsigned)(ib - 2); v[4 * i + 3] = (fkey(sv4.w) & ~127u) | (unsigned)(ib - 3);
;         }
.LBB0_67:
	ds_read_b128 v[0:3], v171 offset:17408
	ds_read_b128 v[4:7], v171 offset:17424
	ds_read_b128 v[8:11], v171 offset:17440
	ds_read_b128 v[12:15], v171 offset:17456
	s_waitcnt lgkmcnt(3)
	v_ashrrev_i32_e32 v16, 31, v0


; DI unsigned fkey(float f) { const unsigned u = __float_as_uint(f); return (u & 0x80000000u) ? ~u : (u | 0x80000000u); }
; DI void topk_phase(unsigned char* smem_, const bf16_t* __restrict__ qp, const bf16_t* __restrict__ keys, int* __restrict__ eidx, float* __restrict__ gate) {
;     ...
;         for (int i = 0; i < 8; ++i) {
;             const f32x4 sv4 = *(const f32x4*)(S + row * LDS_ + 32 * q + 4 * i);
;             const int ib = 127 - (32 * q + 4 * i);
;             v[4 * i] = (fkey(sv4.x) & ~127u) | (unsigned)ib; v[4 * i + 1] = (fkey(sv4.y) & ~127u) | (unsigned)(ib - 1);
;             v[4 * i + 2] = (fkey(sv4.z) & ~127u) | (unsigned)(ib - 2); v[4 * i + 3] = (fkey(sv4.w) & ~127u) | (unsigned)(ib - 3);
;         }
	s_nop 1
	v_bitop3_b32 v0, v16, s98, v0 bitop3:0x56
	v_and_or_b32 v0, v0, s99, v170

; DI unsigned fkey(float f) { const unsigned u = __float_as_uint(f); return (u & 0x80000000u) ? ~u : (u | 0x80000000u); }
; DI void topk_phase(unsigned char* smem_, const bf16_t* __restrict__ qp, const bf16_t* __restrict__ keys, int* __restrict__ eidx, float* __restrict__ gate) {
;     ...
;         for (int i = 0; i < 8; ++i) {
;             const f32x4 sv4 = *(const f32x4*)(S + row * LDS_ + 32 * q + 4 * i);
;             const int ib = 127 - (32 * q + 4 * i);
;             v[4 * i] = (fkey(sv4.x) & ~127u) | (unsigned)ib; v[4 * i + 1] = (fkey(sv4.y) & ~127u) | (unsigned)(ib - 1);
;             v[4 * i + 2] = (fkey(sv4.z) & ~127u) | (unsigned)(ib - 2); v[4 * i + 3] = (fkey(sv4.w) & ~127u) | (unsigned)(ib - 3);
;         }
	v_mov_b32_e32 v16, v0
	v_not_b32_e32 v0, v1
	v_or_b32_e32 v17, 0x80000000, v1
	v_cmp_gt_i32_e32 vcc, 0, v1
	v_ashrrev_i32_e32 v1, 31, v2
	s_nop 0
	v_cndmask_b32_e32 v0, v17, v0, vcc
	v_and_or_b32 v0, v0, s99, v170

; DI unsigned fkey(float f) { const unsigned u = __float_as_uint(f); return (u & 0x80000000u) ? ~u : (u | 0x80000000u); }
; DI void topk_phase(unsigned char* smem_, const bf16_t* __restrict__ qp, const bf16_t* __restrict__ keys, int* __restrict__ eidx, float* __restrict__ gate) {
;     ...
;         for (int i = 0; i < 8; ++i) {
;             const f32x4 sv4 = *(const f32x4*)(S + row * LDS_ + 32 * q + 4 * i);
;             const int ib = 127 - (32 * q + 4 * i);
;             v[4 * i] = (fkey(sv4.x) & ~127u) | (unsigned)ib; v[4 * i + 1] = (fkey(sv4.y) & ~127u) | (unsigned)(ib - 1);
;             v[4 * i + 2] = (fkey(sv4.z) & ~127u) | (unsigned)(ib - 2); v[4 * i + 3] = (fkey(sv4.w) & ~127u) | (unsigned)(ib - 3);
;         }
	v_add_u32_e32 v17, -1, v0


; DI unsigned fkey(float f) { const unsigned u = __float_as_uint(f); return (u & 0x80000000u) ? ~u : (u | 0x80000000u); }
; DI void topk_phase(unsigned char* smem_, const bf16_t* __restrict__ qp, const bf16_t* __restrict__ keys, int* __restrict__ eidx, float* __restrict__ gate) {
;     ...
;         for (int i = 0; i < 8; ++i) {
;             const f32x4 sv4 = *(const f32x4*)(S + row * LDS_ + 32 * q + 4 * i);
;             const int ib = 127 - (32 * q + 4 * i);
;             v[4 * i] = (fkey(sv4.x) & ~127u) | (unsigned)ib; v[4 * i + 1] = (fkey(sv4.y) & ~127u) | (unsigned)(ib - 1);
;             v[4 * i + 2] = (fkey(sv4.z) & ~127u) | (unsigned)(ib - 2); v[4 * i + 3] = (fkey(sv4.w) & ~127u) | (unsigned)(ib - 3);
;         }
	s_nop 1
	v_bitop3_b32 v0, v1, s98, v2 bitop3:0x56
	v_and_or_b32 v0, v0, s99, v170

; DI unsigned fkey(float f) { const unsigned u = __float_as_uint(f); return (u & 0x80000000u) ? ~u : (u | 0x80000000u); }
; DI void topk_phase(unsigned char* smem_, const bf16_t* __restrict__ qp, const bf16_t* __restrict__ keys, int* __restrict__ eidx, float* __restrict__ gate) {
;     ...
;         for (int i = 0; i < 8; ++i) {
;             const f32x4 sv4 = *(const f32x4*)(S + row * LDS_ + 32 * q + 4 * i);
;             const int ib = 127 - (32 * q + 4 * i);
;             v[4 * i] = (fkey(sv4.x) & ~127u) | (unsigned)ib; v[4 * i + 1] = (fkey(sv4.y) & ~127u) | (unsigned)(ib - 1);
;             v[4 * i + 2] = (fkey(sv4.z) & ~127u) | (unsigned)(ib - 2); v[4 * i + 3] = (fkey(sv4.w) & ~127u) | (unsigned)(ib - 3);
;         }
	v_add_u32_e32 v18, -2, v0
	v_ashrrev_i32_e32 v0, 31, v3


; DI unsigned fkey(float f) { const unsigned u = __float_as_uint(f); return (u & 0x80000000u) ? ~u : (u | 0x80000000u); }
; DI void topk_phase(unsigned char* smem_, const bf16_t* __restrict__ qp, const bf16_t* __restrict__ keys, int* __restrict__ eidx, float* __restrict__ gate) {
;     ...
;         for (int i = 0; i < 8; ++i) {
;             const f32x4 sv4 = *(const f32x4*)(S + row * LDS_ + 32 * q + 4 * i);
;             const int ib = 127 - (32 * q + 4 * i);
;             v[4 * i] = (fkey(sv4.x) & ~127u) | (unsigned)ib; v[4 * i + 1] = (fkey(sv4.y) & ~127u) | (unsigned)(ib - 1);
;             v[4 * i + 2] = (fkey(sv4.z) & ~127u) | (unsigned)(ib - 2); v[4 * i + 3] = (fkey(sv4.w) & ~127u) | (unsigned)(ib - 3);
;         }
	s_nop 1
	v_bitop3_b32 v0, v0, s98, v3 bitop3:0x56
	v_and_or_b32 v0, v0, s99, v170

; DI unsigned fkey(float f) { const unsigned u = __float_as_uint(f); return (u & 0x80000000u) ? ~u : (u | 0x80000000u); }
; DI void topk_phase(unsigned char* smem_, const bf16_t* __restrict__ qp, const bf16_t* __restrict__ keys, int* __restrict__ eidx, float* __restrict__ gate) {
;     ...
;         for (int i = 0; i < 8; ++i) {
;             const f32x4 sv4 = *(const f32x4*)(S + row * LDS_ + 32 * q + 4 * i);
;             const int ib = 127 - (32 * q + 4 * i);
;             v[4 * i] = (fkey(sv4.x) & ~127u) | (unsigned)ib; v[4 * i + 1] = (fkey(sv4.y) & ~127u) | (unsigned)(ib - 1);
;             v[4 * i + 2] = (fkey(sv4.z) & ~127u) | (unsigned)(ib - 2); v[4 * i + 3] = (fkey(sv4.w) & ~127u) | (unsigned)(ib - 3);
;         }
	v_add_u32_e32 v19, -3, v0
	s_waitcnt lgkmcnt(2)
	v_ashrrev_i32_e32 v0, 31, v4


; DI unsigned fkey(float f) { const unsigned u = __float_as_uint(f); return (u & 0x80000000u) ? ~u : (u | 0x80000000u); }
; DI void topk_phase(unsigned char* smem_, const bf16_t* __restrict__ qp, const bf16_t* __restrict__ keys, int* __restrict__ eidx, float* __restrict__ gate) {
;     ...
;         for (int i = 0; i < 8; ++i) {
;             const f32x4 sv4 = *(const f32x4*)(S + row * LDS_ + 32 * q + 4 * i);
;             const int ib = 127 - (32 * q + 4 * i);
;             v[4 * i] = (fkey(sv4.x) & ~127u) | (unsigned)ib; v[4 * i + 1] = (fkey(sv4.y) & ~127u) | (unsigned)(ib - 1);
;             v[4 * i + 2] = (fkey(sv4.z) & ~127u) | (unsigned)(ib - 2); v[4 * i + 3] = (fkey(sv4.w) & ~127u) | (unsigned)(ib - 3);
;         }
	s_nop 1
	v_bitop3_b32 v0, v0, s98, v4 bitop3:0x56
	v_and_or_b32 v0, v0, s99, v177

; DI unsigned fkey(float f) { const unsigned u = __float_as_uint(f); return (u & 0x80000000u) ? ~u : (u | 0x80000000u); }
; DI void topk_phase(unsigned char* smem_, const bf16_t* __restrict__ qp, const bf16_t* __restrict__ keys, int* __restrict__ eidx, float* __restrict__ gate) {
;     ...
;         for (int i = 0; i < 8; ++i) {
;             const f32x4 sv4 = *(const f32x4*)(S + row * LDS_ + 32 * q + 4 * i);
;             const int ib = 127 - (32 * q + 4 * i);
;             v[4 * i] = (fkey(sv4.x) & ~127u) | (unsigned)ib; v[4 * i + 1] = (fkey(sv4.y) & ~127u) | (unsigned)(ib - 1);
;             v[4 * i + 2] = (fkey(sv4.z) & ~127u) | (unsigned)(ib - 2); v[4 * i + 3] = (fkey(sv4.w) & ~127u) | (unsigned)(ib - 3);
;         }
	v_mov_b32_e32 v20, v0
	v_ashrrev_i32_e32 v0, 31, v5


; DI unsigned fkey(float f) { const unsigned u = __float_as_uint(f); return (u & 0x80000000u) ? ~u : (u | 0x80000000u); }
; DI void topk_phase(unsigned char* smem_, const bf16_t* __restrict__ qp, const bf16_t* __restrict__ keys, int* __restrict__ eidx, float* __restrict__ gate) {
;     ...
;         for (int i = 0; i < 8; ++i) {
;             const f32x4 sv4 = *(const f32x4*)(S + row * LDS_ + 32 * q + 4 * i);
;             const int ib = 127 - (32 * q + 4 * i);
;             v[4 * i] = (fkey(sv4.x) & ~127u) | (unsigned)ib; v[4 * i + 1] = (fkey(sv4.y) & ~127u) | (unsigned)(ib - 1);
;             v[4 * i + 2] = (fkey(sv4.z) & ~127u) | (unsigned)(ib - 2); v[4 * i + 3] = (fkey(sv4.w) & ~127u) | (unsigned)(ib - 3);
;         }
	s_nop 1
	v_bitop3_b32 v0, v0, s98, v5 bitop3:0x56
	v_and_or_b32 v0, v0, s99, v177

; DI unsigned fkey(float f) { const unsigned u = __float_as_uint(f); return (u & 0x80000000u) ? ~u : (u | 0x80000000u); }
; DI void topk_phase(unsigned char* smem_, const bf16_t* __restrict__ qp, const bf16_t* __restrict__ keys, int* __restrict__ eidx, float* __restrict__ gate) {
;     ...
;         for (int i = 0; i < 8; ++i) {
;             const f32x4 sv4 = *(const f32x4*)(S + row * LDS_ + 32 * q + 4 * i);
;             const int ib = 127 - (32 * q + 4 * i);
;             v[4 * i] = (fkey(sv4.x) & ~127u) | (unsigned)ib; v[4 * i + 1] = (fkey(sv4.y) & ~127u) | (unsigned)(ib - 1);
;             v[4 * i + 2] = (fkey(sv4.z) & ~127u) | (unsigned)(ib - 2); v[4 * i + 3] = (fkey(sv4.w) & ~127u) | (unsigned)(ib - 3);
;         }
	v_add_u32_e32 v21, -1, v0
	v_ashrrev_i32_e32 v0, 31, v6


; DI unsigned fkey(float f) { const unsigned u = __float_as_uint(f); return (u & 0x80000000u) ? ~u : (u | 0x80000000u); }
; DI void topk_phase(unsigned char* smem_, const bf16_t* __restrict__ qp, const bf16_t* __restrict__ keys, int* __restrict__ eidx, float* __restrict__ gate) {
;     ...
;         for (int i = 0; i < 8; ++i) {
;             const f32x4 sv4 = *(const f32x4*)(S + row * LDS_ + 32 * q + 4 * i);
;             const int ib = 127 - (32 * q + 4 * i);
;             v[4 * i] = (fkey(sv4.x) & ~127u) | (unsigned)ib; v[4 * i + 1] = (fkey(sv4.y) & ~127u) | (unsigned)(ib - 1);
;             v[4 * i + 2] = (fkey(sv4.z) & ~127u) | (unsigned)(ib - 2); v[4 * i + 3] = (fkey(sv4.w) & ~127u) | (unsigned)(ib - 3);
;         }
	s_nop 1
	v_bitop3_b32 v0, v0, s98, v6 bitop3:0x56
	v_and_or_b32 v0, v0, s99, v177

; DI unsigned fkey(float f) { const unsigned u = __float_as_uint(f); return (u & 0x80000000u) ? ~u : (u | 0x80000000u); }
; DI void topk_phase(unsigned char* smem_, const bf16_t* __restrict__ qp, const bf16_t* __restrict__ keys, int* __restrict__ eidx, float* __restrict__ gate) {
;     ...
;         for (int i = 0; i < 8; ++i) {
;             const f32x4 sv4 = *(const f32x4*)(S + row * LDS_ + 32 * q + 4 * i);
;             const int ib = 127 - (32 * q + 4 * i);
;             v[4 * i] = (fkey(sv4.x) & ~127u) | (unsigned)ib; v[4 * i + 1] = (fkey(sv4.y) & ~127u) | (unsigned)(ib - 1);
;             v[4 * i + 2] = (fkey(sv4.z) & ~127u) | (unsigned)(ib - 2); v[4 * i + 3] = (fkey(sv4.w) & ~127u) | (unsigned)(ib - 3);
;         }
	v_add_u32_e32 v22, -2, v0
	v_ashrrev_i32_e32 v0, 31, v7


; DI unsigned fkey(float f) { const unsigned u = __float_as_uint(f); return (u & 0x80000000u) ? ~u : (u | 0x80000000u); }
; DI void topk_phase(unsigned char* smem_, const bf16_t* __restrict__ qp, const bf16_t* __restrict__ keys, int* __restrict__ eidx, float* __restrict__ gate) {
;     ...
;         for (int i = 0; i < 8; ++i) {
;             const f32x4 sv4 = *(const f32x4*)(S + row * LDS_ + 32 * q + 4 * i);
;             const int ib = 127 - (32 * q + 4 * i);
;             v[4 * i] = (fkey(sv4.x) & ~127u) | (unsigned)ib; v[4 * i + 1] = (fkey(sv4.y) & ~127u) | (unsigned)(ib - 1);
;             v[4 * i + 2] = (fkey(sv4.z) & ~127u) | (unsigned)(ib - 2); v[4 * i + 3] = (fkey(sv4.w) & ~127u) | (unsigned)(ib - 3);
;         }
	s_nop 1
	v_bitop3_b32 v0, v0, s98, v7 bitop3:0x56
	v_and_or_b32 v0, v0, s99, v177

; DI unsigned fkey(float f) { const unsigned u = __float_as_uint(f); return (u & 0x80000000u) ? ~u : (u | 0x80000000u); }
; DI void topk_phase(unsigned char* smem_, const bf16_t* __restrict__ qp, const bf16_t* __restrict__ keys, int* __restrict__ eidx, float* __restrict__ gate) {
;     ...
;         for (int i = 0; i < 8; ++i) {
;             const f32x4 sv4 = *(const f32x4*)(S + row * LDS_ + 32 * q + 4 * i);
;             const int ib = 127 - (32 * q + 4 * i);
;             v[4 * i] = (fkey(sv4.x) & ~127u) | (unsigned)ib; v[4 * i + 1] = (fkey(sv4.y) & ~127u) | (unsigned)(ib - 1);
;             v[4 * i + 2] = (fkey(sv4.z) & ~127u) | (unsigned)(ib - 2); v[4 * i + 3] = (fkey(sv4.w) & ~127u) | (unsigned)(ib - 3);
;         }
	v_add_u32_e32 v23, -3, v0
	s_waitcnt lgkmcnt(1)
	v_ashrrev_i32_e32 v0, 31, v8


; DI unsigned fkey(float f) { const unsigned u = __float_as_uint(f); return (u & 0x80000000u) ? ~u : (u | 0x80000000u); }
; DI void topk_phase(unsigned char* smem_, const bf16_t* __restrict__ qp, const bf16_t* __restrict__ keys, int* __restrict__ eidx, float* __restrict__ gate) {
;     ...
;         for (int i = 0; i < 8; ++i) {
;             const f32x4 sv4 = *(const f32x4*)(S + row * LDS_ + 32 * q + 4 * i);
;             const int ib = 127 - (32 * q + 4 * i);
;             v[4 * i] = (fkey(sv4.x) & ~127u) | (unsigned)ib; v[4 * i + 1] = (fkey(sv4.y) & ~127u) | (unsigned)(ib - 1);
;             v[4 * i + 2] = (fkey(sv4.z) & ~127u) | (unsigned)(ib - 2); v[4 * i + 3] = (fkey(sv4.w) & ~127u) | (unsigned)(ib - 3);
;         }
	s_nop 1
	v_bitop3_b32 v0, v0, s98, v8 bitop3:0x56
	v_and_or_b32 v0, v0, s99, v178

; DI unsigned fkey(float f) { const unsigned u = __float_as_uint(f); return (u & 0x80000000u) ? ~u : (u | 0x80000000u); }
; DI void topk_phase(unsigned char* smem_, const bf16_t* __restrict__ qp, const bf16_t* __restrict__ keys, int* __restrict__ eidx, float* __restrict__ gate) {
;     ...
;         for (int i = 0; i < 8; ++i) {
;             const f32x4 sv4 = *(const f32x4*)(S + row * LDS_ + 32 * q + 4 * i);
;             const int ib = 127 - (32 * q + 4 * i);
;             v[4 * i] = (fkey(sv4.x) & ~127u) | (unsigned)ib; v[4 * i + 1] = (fkey(sv4.y) & ~127u) | (unsigned)(ib - 1);
;             v[4 * i + 2] = (fkey(sv4.z) & ~127u) | (unsigned)(ib - 2); v[4 * i + 3] = (fkey(sv4.w) & ~127u) | (unsigned)(ib - 3);
;         }
	v_mov_b32_e32 v8, v0
	v_ashrrev_i32_e32 v0, 31, v9


; DI unsigned fkey(float f) { const unsigned u = __float_as_uint(f); return (u & 0x80000000u) ? ~u : (u | 0x80000000u); }
; DI void topk_phase(unsigned char* smem_, const bf16_t* __restrict__ qp, const bf16_t* __restrict__ keys, int* __restrict__ eidx, float* __restrict__ gate) {
;     ...
;         for (int i = 0; i < 8; ++i) {
;             const f32x4 sv4 = *(const f32x4*)(S + row * LDS_ + 32 * q + 4 * i);
;             const int ib = 127 - (32 * q + 4 * i);
;             v[4 * i] = (fkey(sv4.x) & ~127u) | (unsigned)ib; v[4 * i + 1] = (fkey(sv4.y) & ~127u) | (unsigned)(ib - 1);
;             v[4 * i + 2] = (fkey(sv4.z) & ~127u) | (unsigned)(ib - 2); v[4 * i + 3] = (fkey(sv4.w) & ~127u) | (unsigned)(ib - 3);
;         }
	s_nop 1
	v_bitop3_b32 v0, v0, s98, v9 bitop3:0x56
	v_and_or_b32 v0, v0, s99, v178

; DI unsigned fkey(float f) { const unsigned u = __float_as_uint(f); return (u & 0x80000000u) ? ~u : (u | 0x80000000u); }
; DI void topk_phase(unsigned char* smem_, const bf16_t* __restrict__ qp, const bf16_t* __restrict__ keys, int* __restrict__ eidx, float* __restrict__ gate) {
;     ...
;         for (int i = 0; i < 8; ++i) {
;             const f32x4 sv4 = *(const f32x4*)(S + row * LDS_ + 32 * q + 4 * i);
;             const int ib = 127 - (32 * q + 4 * i);
;             v[4 * i] = (fkey(sv4.x) & ~127u) | (unsigned)ib; v[4 * i + 1] = (fkey(sv4.y) & ~127u) | (unsigned)(ib - 1);
;             v[4 * i + 2] = (fkey(sv4.z) & ~127u) | (unsigned)(ib - 2); v[4 * i + 3] = (fkey(sv4.w) & ~127u) | (unsigned)(ib - 3);
;         }
	v_add_u32_e32 v9, -1, v0
	v_ashrrev_i32_e32 v0, 31, v10


; DI unsigned fkey(float f) { const unsigned u = __float_as_uint(f); return (u & 0x80000000u) ? ~u : (u | 0x80000000u); }
; DI void topk_phase(unsigned char* smem_, const bf16_t* __restrict__ qp, const bf16_t* __restrict__ keys, int* __restrict__ eidx, float* __restrict__ gate) {
;     ...
;         for (int i = 0; i < 8; ++i) {
;             const f32x4 sv4 = *(const f32x4*)(S + row * LDS_ + 32 * q + 4 * i);
;             const int ib = 127 - (32 * q + 4 * i);
;             v[4 * i] = (fkey(sv4.x) & ~127u) | (unsigned)ib; v[4 * i + 1] = (fkey(sv4.y) & ~127u) | (unsigned)(ib - 1);
;             v[4 * i + 2] = (fkey(sv4.z) & ~127u) | (unsigned)(ib - 2); v[4 * i + 3] = (fkey(sv4.w) & ~127u) | (unsigned)(ib - 3);
;         }
	s_nop 1
	v_bitop3_b32 v0, v0, s98, v10 bitop3:0x56
	v_and_or_b32 v0, v0, s99, v178

; DI unsigned fkey(float f) { const unsigned u = __float_as_uint(f); return (u & 0x80000000u) ? ~u : (u | 0x80000000u); }
; DI void topk_phase(unsigned char* smem_, const bf16_t* __restrict__ qp, const bf16_t* __restrict__ keys, int* __restrict__ eidx, float* __restrict__ gate) {
;     ...
;         for (int i = 0; i < 8; ++i) {
;             const f32x4 sv4 = *(const f32x4*)(S + row * LDS_ + 32 * q + 4 * i);
;             const int ib = 127 - (32 * q + 4 * i);
;             v[4 * i] = (fkey(sv4.x) & ~127u) | (unsigned)ib; v[4 * i + 1] = (fkey(sv4.y) & ~127u) | (unsigned)(ib - 1);
;             v[4 * i + 2] = (fkey(sv4.z) & ~127u) | (unsigned)(ib - 2); v[4 * i + 3] = (fkey(sv4.w) & ~127u) | (unsigned)(ib - 3);
;         }
	v_add_u32_e32 v10, -2, v0
	v_ashrrev_i32_e32 v0, 31, v11


; DI unsigned fkey(float f) { const unsigned u = __float_as_uint(f); return (u & 0x80000000u) ? ~u : (u | 0x80000000u); }
; DI void topk_phase(unsigned char* smem_, const bf16_t* __restrict__ qp, const bf16_t* __restrict__ keys, int* __restrict__ eidx, float* __restrict__ gate) {
;     ...
;         for (int i = 0; i < 8; ++i) {
;             const f32x4 sv4 = *(const f32x4*)(S + row * LDS_ + 32 * q + 4 * i);
;             const int ib = 127 - (32 * q + 4 * i);
;             v[4 * i] = (fkey(sv4.x) & ~127u) | (unsigned)ib; v[4 * i + 1] = (fkey(sv4.y) & ~127u) | (unsigned)(ib - 1);
;             v[4 * i + 2] = (fkey(sv4.z) & ~127u) | (unsigned)(ib - 2); v[4 * i + 3] = (fkey(sv4.w) & ~127u) | (unsigned)(ib - 3);
;         }
	s_nop 1
	v_bitop3_b32 v0, v0, s98, v11 bitop3:0x56
	v_and_or_b32 v0, v0, s99, v178

; DI unsigned fkey(float f) { const unsigned u = __float_as_uint(f); return (u & 0x80000000u) ? ~u : (u | 0x80000000u); }
; DI void topk_phase(unsigned char* smem_, const bf16_t* __restrict__ qp, const bf16_t* __restrict__ keys, int* __restrict__ eidx, float* __restrict__ gate) {
;     ...
;         for (int i = 0; i < 8; ++i) {
;             const f32x4 sv4 = *(const f32x4*)(S + row * LDS_ + 32 * q + 4 * i);
;             const int ib = 127 - (32 * q + 4 * i);
;             v[4 * i] = (fkey(sv4.x) & ~127u) | (unsigned)ib; v[4 * i + 1] = (fkey(sv4.y) & ~127u) | (unsigned)(ib - 1);
;             v[4 * i + 2] = (fkey(sv4.z) & ~127u) | (unsigned)(ib - 2); v[4 * i + 3] = (fkey(sv4.w) & ~127u) | (unsigned)(ib - 3);
;         }
	v_add_u32_e32 v11, -3, v0
	s_waitcnt lgkmcnt(0)
	v_ashrrev_i32_e32 v0, 31, v12


; DI unsigned fkey(float f) { const unsigned u = __float_as_uint(f); return (u & 0x80000000u) ? ~u : (u | 0x80000000u); }
; DI void topk_phase(unsigned char* smem_, const bf16_t* __restrict__ qp, const bf16_t* __restrict__ keys, int* __restrict__ eidx, float* __restrict__ gate) {
;     ...
;         for (int i = 0; i < 8; ++i) {
;             const f32x4 sv4 = *(const f32x4*)(S + row * LDS_ + 32 * q + 4 * i);
;             const int ib = 127 - (32 * q + 4 * i);
;             v[4 * i] = (fkey(sv4.x) & ~127u) | (unsigned)ib; v[4 * i + 1] = (fkey(sv4.y) & ~127u) | (unsigned)(ib - 1);
;             v[4 * i + 2] = (fkey(sv4.z) & ~127u) | (unsigned)(ib - 2); v[4 * i + 3] = (fkey(sv4.w) & ~127u) | (unsigned)(ib - 3);
;         }
	s_nop 1
	v_bitop3_b32 v0, v0, s98, v12 bitop3:0x56
	v_and_or_b32 v0, v0, s99, v179

; DI unsigned fkey(float f) { const unsigned u = __float_as_uint(f); return (u & 0x80000000u) ? ~u : (u | 0x80000000u); }
; DI void topk_phase(unsigned char* smem_, const bf16_t* __restrict__ qp, const bf16_t* __restrict__ keys, int* __restrict__ eidx, float* __restrict__ gate) {
;     ...
;         for (int i = 0; i < 8; ++i) {
;             const f32x4 sv4 = *(const f32x4*)(S + row * LDS_ + 32 * q + 4 * i);
;             const int ib = 127 - (32 * q + 4 * i);
;             v[4 * i] = (fkey(sv4.x) & ~127u) | (unsigned)ib; v[4 * i + 1] = (fkey(sv4.y) & ~127u) | (unsigned)(ib - 1);
;             v[4 * i + 2] = (fkey(sv4.z) & ~127u) | (unsigned)(ib - 2); v[4 * i + 3] = (fkey(sv4.w) & ~127u) | (unsigned)(ib - 3);
;         }
	v_mov_b32_e32 v12, v0
	v_ashrrev_i32_e32 v0, 31, v13


; DI unsigned fkey(float f) { const unsigned u = __float_as_uint(f); return (u & 0x80000000u) ? ~u : (u | 0x80000000u); }
; DI void topk_phase(unsigned char* smem_, const bf16_t* __restrict__ qp, const bf16_t* __restrict__ keys, int* __restrict__ eidx, float* __restrict__ gate) {
;     ...
;         for (int i = 0; i < 8; ++i) {
;             const f32x4 sv4 = *(const f32x4*)(S + row * LDS_ + 32 * q + 4 * i);
;             const int ib = 127 - (32 * q + 4 * i);
;             v[4 * i] = (fkey(sv4.x) & ~127u) | (unsigned)ib; v[4 * i + 1] = (fkey(sv4.y) & ~127u) | (unsigned)(ib - 1);
;             v[4 * i + 2] = (fkey(sv4.z) & ~127u) | (unsigned)(ib - 2); v[4 * i + 3] = (fkey(sv4.w) & ~127u) | (unsigned)(ib - 3);
;         }
	s_nop 1
	v_bitop3_b32 v0, v0, s98, v13 bitop3:0x56
	v_and_or_b32 v0, v0, s99, v179

; DI unsigned fkey(float f) { const unsigned u = __float_as_uint(f); return (u & 0x80000000u) ? ~u : (u | 0x80000000u); }
; DI void topk_phase(unsigned char* smem_, const bf16_t* __restrict__ qp, const bf16_t* __restrict__ keys, int* __restrict__ eidx, float* __restrict__ gate) {
;     ...
;             v[4 * i] = (fkey(sv4.x) & ~127u) | (unsigned)ib; v[4 * i + 1] = (fkey(sv4.y) & ~127u) | (unsigned)(ib - 1);
	v_add_u32_e32 v13, -1, v0
	v_ashrrev_i32_e32 v0, 31, v14


; DI unsigned fkey(float f) { const unsigned u = __float_as_uint(f); return (u & 0x80000000u) ? ~u : (u | 0x80000000u); }
; DI void topk_phase(unsigned char* smem_, const bf16_t* __restrict__ qp, const bf16_t* __restrict__ keys, int* __restrict__ eidx, float* __restrict__ gate) {
;     ...
;         for (int i = 0; i < 8; ++i) {
;             const f32x4 sv4 = *(const f32x4*)(S + row * LDS_ + 32 * q + 4 * i);
;             const int ib = 127 - (32 * q + 4 * i);
;             v[4 * i] = (fkey(sv4.x) & ~127u) | (unsigned)ib; v[4 * i + 1] = (fkey(sv4.y) & ~127u) | (unsigned)(ib - 1);
;             v[4 * i + 2] = (fkey(sv4.z) & ~127u) | (unsigned)(ib - 2); v[4 * i + 3] = (fkey(sv4.w) & ~127u) | (unsigned)(ib - 3);
;         }
	s_nop 1
	v_bitop3_b32 v0, v0, s98, v14 bitop3:0x56
	v_and_or_b32 v0, v0, s99, v179

; DI unsigned fkey(float f) { const unsigned u = __float_as_uint(f); return (u & 0x80000000u) ? ~u : (u | 0x80000000u); }
; DI void topk_phase(unsigned char* smem_, const bf16_t* __restrict__ qp, const bf16_t* __restrict__ keys, int* __restrict__ eidx, float* __restrict__ gate) {
;     ...
;             v[4 * i + 2] = (fkey(sv4.z) & ~127u) | (unsigned)(ib - 2); v[4 * i + 3] = (fkey(sv4.w) & ~127u) | (unsigned)(ib - 3);
	v_add_u32_e32 v14, -2, v0
	v_ashrrev_i32_e32 v0, 31, v15


; DI unsigned fkey(float f) { const unsigned u = __float_as_uint(f); return (u & 0x80000000u) ? ~u : (u | 0x80000000u); }
; DI void topk_phase(unsigned char* smem_, const bf16_t* __restrict__ qp, const bf16_t* __restrict__ keys, int* __restrict__ eidx, float* __restrict__ gate) {
;     ...
;         for (int i = 0; i < 8; ++i) {
;             const f32x4 sv4 = *(const f32x4*)(S + row * LDS_ + 32 * q + 4 * i);
;             const int ib = 127 - (32 * q + 4 * i);
;             v[4 * i] = (fkey(sv4.x) & ~127u) | (unsigned)ib; v[4 * i + 1] = (fkey(sv4.y) & ~127u) | (unsigned)(ib - 1);
;             v[4 * i + 2] = (fkey(sv4.z) & ~127u) | (unsigned)(ib - 2); v[4 * i + 3] = (fkey(sv4.w) & ~127u) | (unsigned)(ib - 3);
;         }
	s_nop 1
	v_bitop3_b32 v4, v0, s98, v15 bitop3:0x56
	ds_read_b128 v[0:3], v171 offset:17472
	v_and_or_b32 v4, v4, s99, v179

; DI unsigned fkey(float f) { const unsigned u = __float_as_uint(f); return (u & 0x80000000u) ? ~u : (u | 0x80000000u); }
; DI void topk_phase(unsigned char* smem_, const bf16_t* __restrict__ qp, const bf16_t* __restrict__ keys, int* __restrict__ eidx, float* __restrict__ gate) {
;     ...
;             const f32x4 sv4 = *(const f32x4*)(S + row * LDS_ + 32 * q + 4 * i);
;             const int ib = 127 - (32 * q + 4 * i);
;             v[4 * i] = (fkey(sv4.x) & ~127u) | (unsigned)ib; v[4 * i + 1] = (fkey(sv4.y) & ~127u) | (unsigned)(ib - 1);
;             v[4 * i + 2] = (fkey(sv4.z) & ~127u) | (unsigned)(ib - 2); v[4 * i + 3] = (fkey(sv4.w) & ~127u) | (unsigned)(ib - 3);
	v_add_u32_e32 v15, -3, v4
	ds_read_b128 v[4:7], v171 offset:17488
	s_waitcnt lgkmcnt(1)
	v_ashrrev_i32_e32 v24, 31, v0


; DI unsigned fkey(float f) { const unsigned u = __float_as_uint(f); return (u & 0x80000000u) ? ~u : (u | 0x80000000u); }
; DI void topk_phase(unsigned char* smem_, const bf16_t* __restrict__ qp, const bf16_t* __restrict__ keys, int* __restrict__ eidx, float* __restrict__ gate) {
;     ...
;         for (int i = 0; i < 8; ++i) {
;             const f32x4 sv4 = *(const f32x4*)(S + row * LDS_ + 32 * q + 4 * i);
;             const int ib = 127 - (32 * q + 4 * i);
;             v[4 * i] = (fkey(sv4.x) & ~127u) | (unsigned)ib; v[4 * i + 1] = (fkey(sv4.y) & ~127u) | (unsigned)(ib - 1);
;             v[4 * i + 2] = (fkey(sv4.z) & ~127u) | (unsigned)(ib - 2); v[4 * i + 3] = (fkey(sv4.w) & ~127u) | (unsigned)(ib - 3);
;         }
	s_nop 1
	v_bitop3_b32 v0, v24, s98, v0 bitop3:0x56
	v_and_or_b32 v0, v0, s99, v180

; DI unsigned fkey(float f) { const unsigned u = __float_as_uint(f); return (u & 0x80000000u) ? ~u : (u | 0x80000000u); }
; DI void topk_phase(unsigned char* smem_, const bf16_t* __restrict__ qp, const bf16_t* __restrict__ keys, int* __restrict__ eidx, float* __restrict__ gate) {
;     ...
;             v[4 * i] = (fkey(sv4.x) & ~127u) | (unsigned)ib; v[4 * i + 1] = (fkey(sv4.y) & ~127u) | (unsigned)(ib - 1);
	v_mov_b32_e32 v24, v0
	v_not_b32_e32 v0, v1
	v_or_b32_e32 v25, 0x80000000, v1
	v_cmp_gt_i32_e32 vcc, 0, v1
	v_ashrrev_i32_e32 v1, 31, v2
	s_nop 0
	v_cndmask_b32_e32 v0, v25, v0, vcc
	v_and_or_b32 v0, v0, s99, v180

; DI unsigned fkey(float f) { const unsigned u = __float_as_uint(f); return (u & 0x80000000u) ? ~u : (u | 0x80000000u); }
; DI void topk_phase(unsigned char* smem_, const bf16_t* __restrict__ qp, const bf16_t* __restrict__ keys, int* __restrict__ eidx, float* __restrict__ gate) {
;     ...
;             v[4 * i] = (fkey(sv4.x) & ~127u) | (unsigned)ib; v[4 * i + 1] = (fkey(sv4.y) & ~127u) | (unsigned)(ib - 1);
	v_add_u32_e32 v25, -1, v0


; DI unsigned fkey(float f) { const unsigned u = __float_as_uint(f); return (u & 0x80000000u) ? ~u : (u | 0x80000000u); }
; DI void topk_phase(unsigned char* smem_, const bf16_t* __restrict__ qp, const bf16_t* __restrict__ keys, int* __restrict__ eidx, float* __restrict__ gate) {
;     ...
;             v[4 * i + 2] = (fkey(sv4.z) & ~127u) | (unsigned)(ib - 2); v[4 * i + 3] = (fkey(sv4.w) & ~127u) | (unsigned)(ib - 3);
	s_nop 1
	v_bitop3_b32 v0, v1, s98, v2 bitop3:0x56
	v_and_or_b32 v0, v0, s99, v180

; DI unsigned fkey(float f) { const unsigned u = __float_as_uint(f); return (u & 0x80000000u) ? ~u : (u | 0x80000000u); }
; DI void topk_phase(unsigned char* smem_, const bf16_t* __restrict__ qp, const bf16_t* __restrict__ keys, int* __restrict__ eidx, float* __restrict__ gate) {
;     ...
;             v[4 * i + 2] = (fkey(sv4.z) & ~127u) | (unsigned)(ib - 2); v[4 * i + 3] = (fkey(sv4.w) & ~127u) | (unsigned)(ib - 3);
	v_add_u32_e32 v26, -2, v0
	v_ashrrev_i32_e32 v0, 31, v3


; DI unsigned fkey(float f) { const unsigned u = __float_as_uint(f); return (u & 0x80000000u) ? ~u : (u | 0x80000000u); }
; DI void topk_phase(unsigned char* smem_, const bf16_t* __restrict__ qp, const bf16_t* __restrict__ keys, int* __restrict__ eidx, float* __restrict__ gate) {
;     ...
;             v[4 * i + 2] = (fkey(sv4.z) & ~127u) | (unsigned)(ib - 2); v[4 * i + 3] = (fkey(sv4.w) & ~127u) | (unsigned)(ib - 3);
	s_nop 1
	v_bitop3_b32 v0, v0, s98, v3 bitop3:0x56
	v_and_or_b32 v0, v0, s99, v180

; DI unsigned fkey(float f) { const unsigned u = __float_as_uint(f); return (u & 0x80000000u) ? ~u : (u | 0x80000000u); }
; DI void topk_phase(unsigned char* smem_, const bf16_t* __restrict__ qp, const bf16_t* __restrict__ keys, int* __restrict__ eidx, float* __restrict__ gate) {
;     ...
;             v[4 * i + 2] = (fkey(sv4.z) & ~127u) | (unsigned)(ib - 2); v[4 * i + 3] = (fkey(sv4.w) & ~127u) | (unsigned)(ib - 3);
	v_add_u32_e32 v27, -3, v0
	s_waitcnt lgkmcnt(0)
	v_ashrrev_i32_e32 v0, 31, v4


; DI unsigned fkey(float f) { const unsigned u = __float_as_uint(f); return (u & 0x80000000u) ? ~u : (u | 0x80000000u); }
; DI void topk_phase(unsigned char* smem_, const bf16_t* __restrict__ qp, const bf16_t* __restrict__ keys, int* __restrict__ eidx, float* __restrict__ gate) {
;     ...
;         for (int i = 0; i < 8; ++i) {
;             const f32x4 sv4 = *(const f32x4*)(S + row * LDS_ + 32 * q + 4 * i);
;             const int ib = 127 - (32 * q + 4 * i);
;             v[4 * i] = (fkey(sv4.x) & ~127u) | (unsigned)ib; v[4 * i + 1] = (fkey(sv4.y) & ~127u) | (unsigned)(ib - 1);
;             v[4 * i + 2] = (fkey(sv4.z) & ~127u) | (unsigned)(ib - 2); v[4 * i + 3] = (fkey(sv4.w) & ~127u) | (unsigned)(ib - 3);
;         }
	s_nop 1
	v_bitop3_b32 v0, v0, s98, v4 bitop3:0x56
	v_and_or_b32 v0, v0, s99, v181

; DI unsigned fkey(float f) { const unsigned u = __float_as_uint(f); return (u & 0x80000000u) ? ~u : (u | 0x80000000u); }
; DI void topk_phase(unsigned char* smem_, const bf16_t* __restrict__ qp, const bf16_t* __restrict__ keys, int* __restrict__ eidx, float* __restrict__ gate) {
;     ...
;             v[4 * i] = (fkey(sv4.x) & ~127u) | (unsigned)ib; v[4 * i + 1] = (fkey(sv4.y) & ~127u) | (unsigned)(ib - 1);
	v_mov_b32_e32 v28, v0
	v_ashrrev_i32_e32 v0, 31, v5


; DI unsigned fkey(float f) { const unsigned u = __float_as_uint(f); return (u & 0x80000000u) ? ~u : (u | 0x80000000u); }
; DI void topk_phase(unsigned char* smem_, const bf16_t* __restrict__ qp, const bf16_t* __restrict__ keys, int* __restrict__ eidx, float* __restrict__ gate) {
;     ...
;             v[4 * i] = (fkey(sv4.x) & ~127u) | (unsigned)ib; v[4 * i + 1] = (fkey(sv4.y) & ~127u) | (unsigned)(ib - 1);
	s_nop 1
	v_bitop3_b32 v0, v0, s98, v5 bitop3:0x56
	v_and_or_b32 v0, v0, s99, v181

; DI unsigned fkey(float f) { const unsigned u = __float_as_uint(f); return (u & 0x80000000u) ? ~u : (u | 0x80000000u); }
; DI void topk_phase(unsigned char* smem_, const bf16_t* __restrict__ qp, const bf16_t* __restrict__ keys, int* __restrict__ eidx, float* __restrict__ gate) {
;     ...
;             v[4 * i] = (fkey(sv4.x) & ~127u) | (unsigned)ib; v[4 * i + 1] = (fkey(sv4.y) & ~127u) | (unsigned)(ib - 1);
	v_add_u32_e32 v29, -1, v0
	v_ashrrev_i32_e32 v0, 31, v6


; DI unsigned fkey(float f) { const unsigned u = __float_as_uint(f); return (u & 0x80000000u) ? ~u : (u | 0x80000000u); }
; DI void topk_phase(unsigned char* smem_, const bf16_t* __restrict__ qp, const bf16_t* __restrict__ keys, int* __restrict__ eidx, float* __restrict__ gate) {
;     ...
;             v[4 * i + 2] = (fkey(sv4.z) & ~127u) | (unsigned)(ib - 2); v[4 * i + 3] = (fkey(sv4.w) & ~127u) | (unsigned)(ib - 3);
	s_nop 1
	v_bitop3_b32 v0, v0, s98, v6 bitop3:0x56
	v_and_or_b32 v0, v0, s99, v181

; DI unsigned fkey(float f) { const unsigned u = __float_as_uint(f); return (u & 0x80000000u) ? ~u : (u | 0x80000000u); }
; DI void topk_phase(unsigned char* smem_, const bf16_t* __restrict__ qp, const bf16_t* __restrict__ keys, int* __restrict__ eidx, float* __restrict__ gate) {
;     ...
;             v[4 * i + 2] = (fkey(sv4.z) & ~127u) | (unsigned)(ib - 2); v[4 * i + 3] = (fkey(sv4.w) & ~127u) | (unsigned)(ib - 3);
	v_add_u32_e32 v30, -2, v0
	v_ashrrev_i32_e32 v0, 31, v7


; DI unsigned fkey(float f) { const unsigned u = __float_as_uint(f); return (u & 0x80000000u) ? ~u : (u | 0x80000000u); }
; DI void topk_phase(unsigned char* smem_, const bf16_t* __restrict__ qp, const bf16_t* __restrict__ keys, int* __restrict__ eidx, float* __restrict__ gate) {
;     ...
;         for (int i = 0; i < 8; ++i) {
;             const f32x4 sv4 = *(const f32x4*)(S + row * LDS_ + 32 * q + 4 * i);
;             const int ib = 127 - (32 * q + 4 * i);
;             v[4 * i] = (fkey(sv4.x) & ~127u) | (unsigned)ib; v[4 * i + 1] = (fkey(sv4.y) & ~127u) | (unsigned)(ib - 1);
;             v[4 * i + 2] = (fkey(sv4.z) & ~127u) | (unsigned)(ib - 2); v[4 * i + 3] = (fkey(sv4.w) & ~127u) | (unsigned)(ib - 3);
;         }
	s_nop 1
	v_bitop3_b32 v4, v0, s98, v7 bitop3:0x56
	ds_read_b128 v[0:3], v171 offset:17504
	v_and_or_b32 v4, v4, s99, v181

; DI unsigned fkey(float f) { const unsigned u = __float_as_uint(f); return (u & 0x80000000u) ? ~u : (u | 0x80000000u); }
; DI void topk_phase(unsigned char* smem_, const bf16_t* __restrict__ qp, const bf16_t* __restrict__ keys, int* __restrict__ eidx, float* __restrict__ gate) {
;     ...
;             const f32x4 sv4 = *(const f32x4*)(S + row * LDS_ + 32 * q + 4 * i);
;             const int ib = 127 - (32 * q + 4 * i);
;             v[4 * i] = (fkey(sv4.x) & ~127u) | (unsigned)ib; v[4 * i + 1] = (fkey(sv4.y) & ~127u) | (unsigned)(ib - 1);
;             v[4 * i + 2] = (fkey(sv4.z) & ~127u) | (unsigned)(ib - 2); v[4 * i + 3] = (fkey(sv4.w) & ~127u) | (unsigned)(ib - 3);
	v_add_u32_e32 v31, -3, v4
	ds_read_b128 v[4:7], v171 offset:17520
	s_waitcnt lgkmcnt(1)
	v_ashrrev_i32_e32 v117, 31, v0


; DI unsigned fkey(float f) { const unsigned u = __float_as_uint(f); return (u & 0x80000000u) ? ~u : (u | 0x80000000u); }
; DI void topk_phase(unsigned char* smem_, const bf16_t* __restrict__ qp, const bf16_t* __restrict__ keys, int* __restrict__ eidx, float* __restrict__ gate) {
;     ...
;             v[4 * i] = (fkey(sv4.x) & ~127u) | (unsigned)ib; v[4 * i + 1] = (fkey(sv4.y) & ~127u) | (unsigned)(ib - 1);
	s_nop 1
	v_bitop3_b32 v0, v117, s98, v0 bitop3:0x56
	v_ashrrev_i32_e32 v117, 31, v1


; DI unsigned fkey(float f) { const unsigned u = __float_as_uint(f); return (u & 0x80000000u) ? ~u : (u | 0x80000000u); }
; DI void topk_phase(unsigned char* smem_, const bf16_t* __restrict__ qp, const bf16_t* __restrict__ keys, int* __restrict__ eidx, float* __restrict__ gate) {
;     ...
;             v[4 * i] = (fkey(sv4.x) & ~127u) | (unsigned)ib; v[4 * i + 1] = (fkey(sv4.y) & ~127u) | (unsigned)(ib - 1);
	v_and_or_b32 v0, v0, s99, v182

; DI unsigned fkey(float f) { const unsigned u = __float_as_uint(f); return (u & 0x80000000u) ? ~u : (u | 0x80000000u); }
; DI void topk_phase(unsigned char* smem_, const bf16_t* __restrict__ qp, const bf16_t* __restrict__ keys, int* __restrict__ eidx, float* __restrict__ gate) {
;     ...
;             v[4 * i] = (fkey(sv4.x) & ~127u) | (unsigned)ib; v[4 * i + 1] = (fkey(sv4.y) & ~127u) | (unsigned)(ib - 1);
	v_bitop3_b32 v1, v117, s98, v1 bitop3:0x56
	v_ashrrev_i32_e32 v117, 31, v2


; DI unsigned fkey(float f) { const unsigned u = __float_as_uint(f); return (u & 0x80000000u) ? ~u : (u | 0x80000000u); }
; DI void topk_phase(unsigned char* smem_, const bf16_t* __restrict__ qp, const bf16_t* __restrict__ keys, int* __restrict__ eidx, float* __restrict__ gate) {
;     ...
;             v[4 * i] = (fkey(sv4.x) & ~127u) | (unsigned)ib; v[4 * i + 1] = (fkey(sv4.y) & ~127u) | (unsigned)(ib - 1);
	v_and_or_b32 v1, v1, s99, v182

; DI unsigned fkey(float f) { const unsigned u = __float_as_uint(f); return (u & 0x80000000u) ? ~u : (u | 0x80000000u); }
; DI void topk_phase(unsigned char* smem_, const bf16_t* __restrict__ qp, const bf16_t* __restrict__ keys, int* __restrict__ eidx, float* __restrict__ gate) {
;     ...
;             v[4 * i + 2] = (fkey(sv4.z) & ~127u) | (unsigned)(ib - 2); v[4 * i + 3] = (fkey(sv4.w) & ~127u) | (unsigned)(ib - 3);
	v_bitop3_b32 v2, v117, s98, v2 bitop3:0x56
	v_ashrrev_i32_e32 v117, 31, v3


; DI unsigned fkey(float f) { const unsigned u = __float_as_uint(f); return (u & 0x80000000u) ? ~u : (u | 0x80000000u); }
; DI void topk_phase(unsigned char* smem_, const bf16_t* __restrict__ qp, const bf16_t* __restrict__ keys, int* __restrict__ eidx, float* __restrict__ gate) {
;     ...
;             v[4 * i + 2] = (fkey(sv4.z) & ~127u) | (unsigned)(ib - 2); v[4 * i + 3] = (fkey(sv4.w) & ~127u) | (unsigned)(ib - 3);
	v_and_or_b32 v2, v2, s99, v182

; DI unsigned fkey(float f) { const unsigned u = __float_as_uint(f); return (u & 0x80000000u) ? ~u : (u | 0x80000000u); }
; DI void topk_phase(unsigned char* smem_, const bf16_t* __restrict__ qp, const bf16_t* __restrict__ keys, int* __restrict__ eidx, float* __restrict__ gate) {
;     ...
;             v[4 * i + 2] = (fkey(sv4.z) & ~127u) | (unsigned)(ib - 2); v[4 * i + 3] = (fkey(sv4.w) & ~127u) | (unsigned)(ib - 3);
	v_bitop3_b32 v3, v117, s98, v3 bitop3:0x56
	s_waitcnt lgkmcnt(0)
	v_ashrrev_i32_e32 v117, 31, v4


; DI unsigned fkey(float f) { const unsigned u = __float_as_uint(f); return (u & 0x80000000u) ? ~u : (u | 0x80000000u); }
; DI void topk_phase(unsigned char* smem_, const bf16_t* __restrict__ qp, const bf16_t* __restrict__ keys, int* __restrict__ eidx, float* __restrict__ gate) {
;     ...
;             v[4 * i + 2] = (fkey(sv4.z) & ~127u) | (unsigned)(ib - 2); v[4 * i + 3] = (fkey(sv4.w) & ~127u) | (unsigned)(ib - 3);
	v_and_or_b32 v3, v3, s99, v182

; DI unsigned fkey(float f) { const unsigned u = __float_as_uint(f); return (u & 0x80000000u) ? ~u : (u | 0x80000000u); }
; DI void topk_phase(unsigned char* smem_, const bf16_t* __restrict__ qp, const bf16_t* __restrict__ keys, int* __restrict__ eidx, float* __restrict__ gate) {
;     ...
;             v[4 * i] = (fkey(sv4.x) & ~127u) | (unsigned)ib; v[4 * i + 1] = (fkey(sv4.y) & ~127u) | (unsigned)(ib - 1);
	v_bitop3_b32 v4, v117, s98, v4 bitop3:0x56
	v_ashrrev_i32_e32 v117, 31, v5


; DI unsigned fkey(float f) { const unsigned u = __float_as_uint(f); return (u & 0x80000000u) ? ~u : (u | 0x80000000u); }
; DI void topk_phase(unsigned char* smem_, const bf16_t* __restrict__ qp, const bf16_t* __restrict__ keys, int* __restrict__ eidx, float* __restrict__ gate) {
;     ...
;             v[4 * i] = (fkey(sv4.x) & ~127u) | (unsigned)ib; v[4 * i + 1] = (fkey(sv4.y) & ~127u) | (unsigned)(ib - 1);
	v_and_or_b32 v4, v4, s99, v183

; DI unsigned fkey(float f) { const unsigned u = __float_as_uint(f); return (u & 0x80000000u) ? ~u : (u | 0x80000000u); }
; DI void topk_phase(unsigned char* smem_, const bf16_t* __restrict__ qp, const bf16_t* __restrict__ keys, int* __restrict__ eidx, float* __restrict__ gate) {
;     ...
;             v[4 * i] = (fkey(sv4.x) & ~127u) | (unsigned)ib; v[4 * i + 1] = (fkey(sv4.y) & ~127u) | (unsigned)(ib - 1);
	v_bitop3_b32 v5, v117, s98, v5 bitop3:0x56
	v_ashrrev_i32_e32 v117, 31, v6


; DI unsigned fkey(float f) { const unsigned u = __float_as_uint(f); return (u & 0x80000000u) ? ~u : (u | 0x80000000u); }
; DI void topk_phase(unsigned char* smem_, const bf16_t* __restrict__ qp, const bf16_t* __restrict__ keys, int* __restrict__ eidx, float* __restrict__ gate) {
;     ...
;             v[4 * i] = (fkey(sv4.x) & ~127u) | (unsigned)ib; v[4 * i + 1] = (fkey(sv4.y) & ~127u) | (unsigned)(ib - 1);
	v_and_or_b32 v5, v5, s99, v183

; DI unsigned fkey(float f) { const unsigned u = __float_as_uint(f); return (u & 0x80000000u) ? ~u : (u | 0x80000000u); }
; DI void topk_phase(unsigned char* smem_, const bf16_t* __restrict__ qp, const bf16_t* __restrict__ keys, int* __restrict__ eidx, float* __restrict__ gate) {
;     ...
;             v[4 * i + 2] = (fkey(sv4.z) & ~127u) | (unsigned)(ib - 2); v[4 * i + 3] = (fkey(sv4.w) & ~127u) | (unsigned)(ib - 3);
	v_bitop3_b32 v6, v117, s98, v6 bitop3:0x56
	v_ashrrev_i32_e32 v117, 31, v7


; DI unsigned fkey(float f) { const unsigned u = __float_as_uint(f); return (u & 0x80000000u) ? ~u : (u | 0x80000000u); }
; DI void topk_phase(unsigned char* smem_, const bf16_t* __restrict__ qp, const bf16_t* __restrict__ keys, int* __restrict__ eidx, float* __restrict__ gate) {
;     ...
;             v[4 * i + 2] = (fkey(sv4.z) & ~127u) | (unsigned)(ib - 2); v[4 * i + 3] = (fkey(sv4.w) & ~127u) | (unsigned)(ib - 3);
	v_and_or_b32 v6, v6, s99, v183

; DI unsigned fkey(float f) { const unsigned u = __float_as_uint(f); return (u & 0x80000000u) ? ~u : (u | 0x80000000u); }
; DI void topk_phase(unsigned char* smem_, const bf16_t* __restrict__ qp, const bf16_t* __restrict__ keys, int* __restrict__ eidx, float* __restrict__ gate) {
;     ...
;             v[4 * i + 2] = (fkey(sv4.z) & ~127u) | (unsigned)(ib - 2); v[4 * i + 3] = (fkey(sv4.w) & ~127u) | (unsigned)(ib - 3);
	v_bitop3_b32 v7, v117, s98, v7 bitop3:0x56
	v_and_or_b32 v7, v7, s99, v183


; DI unsigned fkey(float f) { const unsigned u = __float_as_uint(f); return (u & 0x80000000u) ? ~u : (u | 0x80000000u); }
; DI void topk_phase(unsigned char* smem_, const bf16_t* __restrict__ qp, const bf16_t* __restrict__ keys, int* __restrict__ eidx, float* __restrict__ gate) {
;     ...
;             v[4 * i] = (fkey(sv4.x) & ~127u) | (unsigned)ib; v[4 * i + 1] = (fkey(sv4.y) & ~127u) | (unsigned)(ib - 1);
;             v[4 * i + 2] = (fkey(sv4.z) & ~127u) | (unsigned)(ib - 2); v[4 * i + 3] = (fkey(sv4.w) & ~127u) | (unsigned)(ib - 3);
	v_add_u32_e32 v1, -1, v1
	v_add_u32_e32 v2, -2, v2
	v_add_u32_e32 v3, -3, v3

; DI unsigned fkey(float f) { const unsigned u = __float_as_uint(f); return (u & 0x80000000u) ? ~u : (u | 0x80000000u); }
; template <int N> DI void bitonic_sort_desc(unsigned (&v)[N]) {
; #pragma unroll
;     for (int k = 2; k <= N; k <<= 1)
; #pragma unroll
;         for (int j = k >> 1; j > 0; j >>= 1)
; #pragma unroll
;             for (int i = 0; i < N; ++i) { const int l = i ^ j; if (l > i) { if ((i & k) == 0) cswap(v[i], v[l]); else cswap(v[l], v[i]); } }
; }
; DI void topk_phase(unsigned char* smem_, const bf16_t* __restrict__ qp, const bf16_t* __restrict__ keys, int* __restrict__ eidx, float* __restrict__ gate) {
;     ...
;             v[4 * i] = (fkey(sv4.x) & ~127u) | (unsigned)ib; v[4 * i + 1] = (fkey(sv4.y) & ~127u) | (unsigned)(ib - 1);
;             v[4 * i + 2] = (fkey(sv4.z) & ~127u) | (unsigned)(ib - 2); v[4 * i + 3] = (fkey(sv4.w) & ~127u) | (unsigned)(ib - 3);
;         }
;         bitonic_sort_desc<32>(v);
	v_add_u32_e32 v5, -1, v5
	v_add_u32_e32 v6, -2, v6
	v_add_u32_e32 v7, -3, v7
	v_max_u32_e32 v117, v16, v17
	v_min_u32_e32 v16, v16, v17
	v_max_u32_e32 v17, v19, v18
	v_min_u32_e32 v18, v19, v18
	v_max_u32_e32 v19, v20, v21
	v_min_u32_e32 v20, v20, v21
	v_max_u32_e32 v21, v23, v22
	v_min_u32_e32 v22, v23, v22
	v_max_u32_e32 v23, v8, v9
	v_min_u32_e32 v8, v8, v9
	v_max_u32_e32 v9, v11, v10
	v_min_u32_e32 v10, v11, v10
	v_max_u32_e32 v11, v12, v13
	v_min_u32_e32 v12, v12, v13
	v_max_u32_e32 v13, v15, v14
	v_min_u32_e32 v14, v15, v14
	v_max_u32_e32 v15, v24, v25
	v_min_u32_e32 v24, v24, v25
	v_max_u32_e32 v25, v27, v26
	v_min_u32_e32 v26, v27, v26
	v_max_u32_e32 v27, v28, v29
	v_min_u32_e32 v28, v28, v29
	v_max_u32_e32 v29, v31, v30
	v_min_u32_e32 v30, v31, v30
	v_max_u32_e32 v31, v0, v1
	v_min_u32_e32 v0, v0, v1
	v_max_u32_e32 v1, v3, v2
	v_min_u32_e32 v2, v3, v2
	v_max_u32_e32 v3, v4, v5
	v_min_u32_e32 v4, v4, v5
	v_max_u32_e32 v5, v7, v6
	v_min_u32_e32 v6, v7, v6
	v_max_u32_e32 v7, v117, v18
	v_min_u32_e32 v18, v117, v18
	v_max_u32_e32 v117, v16, v17
	v_min_u32_e32 v16, v16, v17
	v_max_u32_e32 v17, v22, v19
	v_min_u32_e32 v19, v22, v19
	v_max_u32_e32 v22, v21, v20
	v_min_u32_e32 v20, v21, v20
	v_max_u32_e32 v21, v23, v10
	v_min_u32_e32 v10, v23, v10
	v_max_u32_e32 v23, v8, v9
	v_min_u32_e32 v8, v8, v9
	v_max_u32_e32 v9, v14, v11
	v_min_u32_e32 v11, v14, v11
	v_max_u32_e32 v14, v13, v12
	v_min_u32_e32 v12, v13, v12
	v_max_u32_e32 v13, v15, v26
	v_min_u32_e32 v15, v15, v26
	v_max_u32_e32 v26, v24, v25
	v_min_u32_e32 v24, v24, v25
	v_max_u32_e32 v25, v30, v27
	v_min_u32_e32 v27, v30, v27
	v_max_u32_e32 v30, v29, v28
	v_min_u32_e32 v28, v29, v28
	v_max_u32_e32 v29, v31, v2
	v_min_u32_e32 v2, v31, v2
	v_max_u32_e32 v31, v0, v1
	v_min_u32_e32 v0, v0, v1
	v_max_u32_e32 v1, v6, v3
	v_min_u32_e32 v3, v6, v3
	v_max_u32_e32 v6, v5, v4
	v_min_u32_e32 v4, v5, v4
	v_max_u32_e32 v5, v7, v117
	v_min_u32_e32 v7, v7, v117
	v_max_u32_e32 v117, v18, v16
	v_min_u32_e32 v16, v18, v16
	v_max_u32_e32 v18, v20, v19
	v_min_u32_e32 v19, v20, v19
	v_max_u32_e32 v20, v22, v17
	v_min_u32_e32 v17, v22, v17
	v_max_u32_e32 v22, v21, v23
	v_min_u32_e32 v21, v21, v23
	v_max_u32_e32 v23, v10, v8
	v_min_u32_e32 v8, v10, v8
	v_max_u32_e32 v10, v12, v11
	v_min_u32_e32 v11, v12, v11
	v_max_u32_e32 v12, v14, v9
	v_min_u32_e32 v9, v14, v9
	v_max_u32_e32 v14, v13, v26
	v_min_u32_e32 v13, v13, v26
	v_max_u32_e32 v26, v15, v24
	v_min_u32_e32 v15, v15, v24
	v_max_u32_e32 v24, v28, v27
	v_min_u32_e32 v27, v28, v27
	v_max_u32_e32 v28, v30, v25
	v_min_u32_e32 v25, v30, v25
	v_max_u32_e32 v30, v29, v31
	v_min_u32_e32 v29, v29, v31
	v_max_u32_e32 v31, v2, v0
	v_min_u32_e32 v0, v2, v0
	v_max_u32_e32 v2, v4, v3
	v_min_u32_e32 v3, v4, v3
	v_max_u32_e32 v4, v6, v1
	v_min_u32_e32 v1, v6, v1
	v_max_u32_e32 v6, v5, v19
	v_min_u32_e32 v5, v5, v19
	v_max_u32_e32 v19, v7, v18
	v_min_u32_e32 v7, v7, v18
	v_max_u32_e32 v18, v117, v17
	v_min_u32_e32 v17, v117, v17
	v_max_u32_e32 v117, v16, v20
	v_min_u32_e32 v16, v16, v20
	v_max_u32_e32 v20, v11, v22
	v_min_u32_e32 v11, v11, v22
	v_max_u32_e32 v22, v10, v21
	v_min_u32_e32 v10, v10, v21
	v_max_u32_e32 v21, v9, v23
	v_min_u32_e32 v9, v9, v23
	v_max_u32_e32 v23, v12, v8
	v_min_u32_e32 v8, v12, v8
	v_max_u32_e32 v12, v14, v27
	v_min_u32_e32 v14, v14, v27
	v_max_u32_e32 v27, v13, v24
	v_min_u32_e32 v13, v13, v24
	v_max_u32_e32 v24, v26, v25
	v_min_u32_e32 v25, v26, v25
	v_max_u32_e32 v26, v15, v28
	v_min_u32_e32 v15, v15, v28
	v_max_u32_e32 v28, v3, v30
	v_min_u32_e32 v3, v3, v30
	v_max_u32_e32 v30, v2, v29
	v_min_u32_e32 v2, v2, v29
	v_max_u32_e32 v29, v1, v31
	v_min_u32_e32 v1, v1, v31
	v_max_u32_e32 v31, v4, v0
	v_min_u32_e32 v0, v4, v0
	v_max_u32_e32 v4, v6, v18
	v_min_u32_e32 v6, v6, v18
	v_max_u32_e32 v18, v19, v117
	v_min_u32_e32 v19, v19, v117
	v_max_u32_e32 v117, v5, v17
	v_min_u32_e32 v5, v5, v17
	v_max_u32_e32 v17, v7, v16
	v_min_u32_e32 v7, v7, v16
	v_max_u32_e32 v16, v9, v11
	v_min_u32_e32 v9, v9, v11
	v_max_u32_e32 v11, v8, v10
	v_min_u32_e32 v8, v8, v10
	v_max_u32_e32 v10, v21, v20
	v_min_u32_e32 v20, v21, v20
	v_max_u32_e32 v21, v23, v22
	v_min_u32_e32 v22, v23, v22
	v_max_u32_e32 v23, v12, v24
	v_min_u32_e32 v12, v12, v24
	v_max_u32_e32 v24, v27, v26
	v_min_u32_e32 v26, v27, v26
	v_max_u32_e32 v27, v14, v25
	v_min_u32_e32 v14, v14, v25
	v_max_u32_e32 v25, v13, v15
	v_min_u32_e32 v13, v13, v15
	v_max_u32_e32 v15, v1, v3
	v_min_u32_e32 v1, v1, v3
	v_max_u32_e32 v3, v0, v2
	v_min_u32_e32 v0, v0, v2
	v_max_u32_e32 v2, v29, v28
	v_min_u32_e32 v28, v29, v28
	v_max_u32_e32 v29, v31, v30
	v_min_u32_e32 v30, v31, v30
	v_max_u32_e32 v31, v4, v18
	v_min_u32_e32 v4, v4, v18
	v_max_u32_e32 v18, v6, v19
	v_min_u32_e32 v6, v6, v19
	v_max_u32_e32 v19, v117, v17
	v_min_u32_e32 v17, v117, v17
	v_max_u32_e32 v117, v5, v7
	v_min_u32_e32 v5, v5, v7
	v_max_u32_e32 v7, v8, v9
	v_min_u32_e32 v8, v8, v9
	v_max_u32_e32 v9, v11, v16
	v_min_u32_e32 v11, v11, v16
	v_max_u32_e32 v16, v22, v20
	v_min_u32_e32 v20, v22, v20
	v_max_u32_e32 v22, v21, v10
	v_min_u32_e32 v10, v21, v10
	v_max_u32_e32 v21, v23, v24
	v_min_u32_e32 v23, v23, v24
	v_max_u32_e32 v24, v12, v26
	v_min_u32_e32 v12, v12, v26
	v_max_u32_e32 v26, v27, v25
	v_min_u32_e32 v25, v27, v25
	v_max_u32_e32 v27, v14, v13
	v_min_u32_e32 v13, v14, v13
	v_max_u32_e32 v14, v0, v1
	v_min_u32_e32 v0, v0, v1
	v_max_u32_e32 v1, v3, v15
	v_min_u32_e32 v3, v3, v15
	v_max_u32_e32 v15, v30, v28
	v_min_u32_e32 v28, v30, v28
	v_max_u32_e32 v30, v29, v2
	v_min_u32_e32 v2, v29, v2
	v_max_u32_e32 v29, v31, v8
	v_min_u32_e32 v8, v31, v8
	v_max_u32_e32 v31, v4, v7
	v_min_u32_e32 v4, v4, v7
	v_max_u32_e32 v7, v18, v11
; template <int N> DI void bitonic_sort_desc(unsigned (&v)[N]) {
; #pragma unroll
;     for (int k = 2; k <= N; k <<= 1)
; #pragma unroll
;         for (int j = k >> 1; j > 0; j >>= 1)
; #pragma unroll
;             for (int i = 0; i < N; ++i) { const int l = i ^ j; if (l > i) { if ((i & k) == 0) cswap(v[i], v[l]); else cswap(v[l], v[i]); } }
; }
; DI void merge_top16(unsigned (&v)[16], int st) {
;     unsigned x[16];
; #pragma unroll
;     for (int i = 0; i < 16; ++i) x[i] = (unsigned)__shfl_xor((int)v[15 - i], st);
; #pragma unroll
;     for (int i = 0; i < 16; ++i) v[i] = max(v[i], x[i]);
; #pragma unroll
;     for (int j = 8; j > 0; j >>= 1)
; #pragma unroll
;         for (int i = 0; i < 16; ++i) { const int l = i ^ j; if (l > i) cswap(v[i], v[l]); }
; }
; DI void topk_phase(unsigned char* smem_, const bf16_t* __restrict__ qp, const bf16_t* __restrict__ keys, int* __restrict__ eidx, float* __restrict__ gate) {
;     ...
;         bitonic_sort_desc<32>(v);
;         unsigned t16[16];
; #pragma unroll
;         for (int i = 0; i < 16; ++i) t16[i] = v[i];
;         merge_top16(t16, 1);
	v_min_u32_e32 v11, v18, v11
	v_max_u32_e32 v18, v6, v9
	v_min_u32_e32 v6, v6, v9
	v_max_u32_e32 v9, v19, v20
	v_min_u32_e32 v19, v19, v20
	v_max_u32_e32 v20, v17, v16
	v_min_u32_e32 v16, v17, v16
	v_max_u32_e32 v17, v117, v10
	v_min_u32_e32 v10, v117, v10
	v_max_u32_e32 v117, v5, v22
	v_min_u32_e32 v5, v5, v22
	v_max_u32_e32 v22, v0, v21
	v_min_u32_e32 v0, v0, v21
	v_max_u32_e32 v21, v14, v23
	v_min_u32_e32 v14, v14, v23
	v_max_u32_e32 v23, v3, v24
	v_min_u32_e32 v3, v3, v24
	v_max_u32_e32 v24, v1, v12
	v_min_u32_e32 v1, v1, v12
	v_max_u32_e32 v12, v28, v26
	v_min_u32_e32 v26, v28, v26
	v_max_u32_e32 v28, v15, v25
	v_min_u32_e32 v15, v15, v25
	v_max_u32_e32 v25, v2, v27
	v_min_u32_e32 v2, v2, v27
	v_max_u32_e32 v27, v30, v13
	v_min_u32_e32 v13, v30, v13
	v_max_u32_e32 v30, v29, v9
	v_min_u32_e32 v9, v29, v9
	v_max_u32_e32 v29, v31, v20
	v_min_u32_e32 v20, v31, v20
	v_max_u32_e32 v31, v7, v17
	v_min_u32_e32 v7, v7, v17
	v_max_u32_e32 v17, v18, v117
	v_min_u32_e32 v18, v18, v117
	v_max_u32_e32 v117, v8, v19
	v_min_u32_e32 v8, v8, v19
	v_max_u32_e32 v19, v4, v16
	v_min_u32_e32 v4, v4, v16
	v_max_u32_e32 v16, v11, v10
	v_min_u32_e32 v10, v11, v10
	v_max_u32_e32 v11, v6, v5
	v_min_u32_e32 v5, v6, v5
	v_max_u32_e32 v6, v26, v0
	v_min_u32_e32 v0, v26, v0
	v_max_u32_e32 v26, v15, v14
	v_min_u32_e32 v14, v15, v14
	v_max_u32_e32 v15, v2, v3
	v_min_u32_e32 v2, v2, v3
	v_max_u32_e32 v3, v13, v1
	v_min_u32_e32 v1, v13, v1
	v_max_u32_e32 v13, v12, v22
	v_min_u32_e32 v12, v12, v22
	v_max_u32_e32 v22, v28, v21
	v_min_u32_e32 v21, v28, v21
	v_max_u32_e32 v28, v25, v23
	v_min_u32_e32 v23, v25, v23
	v_max_u32_e32 v25, v27, v24
	v_min_u32_e32 v24, v27, v24
	v_max_u32_e32 v27, v30, v31
	v_min_u32_e32 v30, v30, v31
	v_max_u32_e32 v31, v29, v17
	v_min_u32_e32 v17, v29, v17
	v_max_u32_e32 v29, v9, v7
	v_min_u32_e32 v7, v9, v7
	v_max_u32_e32 v9, v20, v18
	v_min_u32_e32 v18, v20, v18
	v_max_u32_e32 v20, v117, v16
	v_min_u32_e32 v16, v117, v16
	v_max_u32_e32 v117, v19, v11
	v_min_u32_e32 v11, v19, v11
	v_max_u32_e32 v19, v8, v10
	v_min_u32_e32 v8, v8, v10
	v_max_u32_e32 v10, v4, v5
	v_min_u32_e32 v4, v4, v5
	v_max_u32_e32 v5, v2, v0
	v_min_u32_e32 v0, v2, v0
	v_max_u32_e32 v2, v1, v14
	v_min_u32_e32 v1, v1, v14
	v_max_u32_e32 v14, v15, v6
	v_min_u32_e32 v6, v15, v6
	v_max_u32_e32 v15, v3, v26
	v_min_u32_e32 v3, v3, v26
	v_max_u32_e32 v26, v23, v12
	v_min_u32_e32 v12, v23, v12
	v_max_u32_e32 v23, v24, v21
	v_min_u32_e32 v21, v24, v21
	v_max_u32_e32 v24, v28, v13
	v_min_u32_e32 v13, v28, v13
	v_max_u32_e32 v28, v25, v22
	v_min_u32_e32 v22, v25, v22
	v_min_u32_e32 v25, v27, v31
	v_min_u32_e32 v118, v30, v17
	v_min_u32_e32 v119, v29, v9
	v_min_u32_e32 v120, v7, v18
	v_min_u32_e32 v121, v20, v117
	v_min_u32_e32 v122, v16, v11
	v_min_u32_e32 v123, v19, v10
	v_min_u32_e32 v124, v8, v4
	v_min_u32_e32 v125, v1, v0
	v_min_u32_e32 v126, v2, v5
	v_min_u32_e32 v127, v3, v6
	v_min_u32_e32 v142, v15, v14
	v_min_u32_e32 v143, v21, v12
	v_min_u32_e32 v144, v23, v26
	v_min_u32_e32 v145, v22, v13
	v_min_u32_e32 v146, v28, v24
	v_max3_u32 v27, v27, v31, v125
	v_max3_u32 v0, v25, v1, v0
	v_max3_u32 v1, v30, v17, v126
	v_max3_u32 v2, v118, v2, v5
	v_max3_u32 v5, v29, v9, v127
	v_max3_u32 v3, v119, v3, v6
	v_max3_u32 v6, v7, v18, v142
	v_max3_u32 v7, v120, v15, v14
	v_max3_u32 v9, v20, v117, v143
	v_max3_u32 v12, v121, v21, v12
	v_max3_u32 v11, v16, v11, v144
	v_max3_u32 v14, v122, v23, v26
	v_max3_u32 v10, v19, v10, v145
	v_max3_u32 v13, v123, v22, v13
	v_max3_u32 v4, v8, v4, v146
	v_max3_u32 v8, v124, v28, v24
	v_max_u32_e32 v15, v27, v9
	v_min_u32_e32 v9, v27, v9
	v_max_u32_e32 v16, v0, v12
	v_min_u32_e32 v0, v0, v12
	v_max_u32_e32 v12, v1, v11
	v_min_u32_e32 v1, v1, v11
	v_max_u32_e32 v11, v2, v14
	v_min_u32_e32 v2, v2, v14
	v_max_u32_e32 v14, v5, v10
	v_min_u32_e32 v5, v5, v10
	v_max_u32_e32 v10, v3, v13
	v_min_u32_e32 v3, v3, v13
	v_max_u32_e32 v13, v6, v4
	v_min_u32_e32 v4, v6, v4
	v_max_u32_e32 v6, v7, v8
	v_min_u32_e32 v7, v7, v8
	v_max_u32_e32 v8, v15, v14
	v_min_u32_e32 v14, v15, v14
	v_max_u32_e32 v15, v16, v10
	v_min_u32_e32 v10, v16, v10
	v_max_u32_e32 v16, v12, v13
	v_min_u32_e32 v12, v12, v13
	v_max_u32_e32 v13, v11, v6
	v_min_u32_e32 v6, v11, v6
	v_max_u32_e32 v11, v9, v5
	v_min_u32_e32 v5, v9, v5
	v_max_u32_e32 v9, v0, v3
	v_min_u32_e32 v0, v0, v3
	v_max_u32_e32 v3, v1, v4
	v_min_u32_e32 v1, v1, v4
	v_max_u32_e32 v4, v2, v7
	v_min_u32_e32 v2, v2, v7
	v_max_u32_e32 v7, v8, v16
	v_min_u32_e32 v8, v8, v16
	v_max_u32_e32 v16, v15, v13
	v_min_u32_e32 v13, v15, v13
	v_max_u32_e32 v15, v14, v12
	v_min_u32_e32 v12, v14, v12
	v_max_u32_e32 v14, v10, v6
	v_min_u32_e32 v6, v10, v6
	v_max_u32_e32 v10, v11, v3
	v_min_u32_e32 v3, v11, v3
	v_max_u32_e32 v11, v9, v4
	v_min_u32_e32 v4, v9, v4
	v_max_u32_e32 v9, v5, v1
	v_min_u32_e32 v1, v5, v1
	v_max_u32_e32 v5, v0, v2
	v_min_u32_e32 v0, v0, v2
	v_max_u32_e32 v2, v7, v16
	v_min_u32_e32 v7, v7, v16
	v_max_u32_e32 v16, v8, v13
	v_min_u32_e32 v8, v8, v13
	v_max_u32_e32 v13, v15, v14
	v_min_u32_e32 v14, v15, v14
	v_max_u32_e32 v15, v12, v6
	v_min_u32_e32 v6, v12, v6
	v_max_u32_e32 v12, v10, v11
	v_min_u32_e32 v10, v10, v11
	v_max_u32_e32 v11, v3, v4
	v_min_u32_e32 v3, v3, v4
	v_max_u32_e32 v4, v9, v5
	v_min_u32_e32 v5, v9, v5
	v_max_u32_e32 v9, v1, v0
	v_min_u32_e32 v0, v1, v0
	s_nop 1
	v_mov_b32_dpp v1, v0 quad_perm:[1,0,3,2] row_mask:0xf bank_mask:0xf
	v_mov_b32_dpp v17, v9 quad_perm:[1,0,3,2] row_mask:0xf bank_mask:0xf
	v_mov_b32_dpp v18, v5 quad_perm:[1,0,3,2] row_mask:0xf bank_mask:0xf
	v_mov_b32_dpp v19, v4 quad_perm:[1,0,3,2] row_mask:0xf bank_mask:0xf
	v_mov_b32_dpp v20, v3 quad_perm:[1,0,3,2] row_mask:0xf bank_mask:0xf
	v_mov_b32_dpp v21, v11 quad_perm:[1,0,3,2] row_mask:0xf bank_mask:0xf
	v_mov_b32_dpp v22, v10 quad_perm:[1,0,3,2] row_mask:0xf bank_mask:0xf
	v_mov_b32_dpp v23, v12 quad_perm:[1,0,3,2] row_mask:0xf bank_mask:0xf
	v_mov_b32_dpp v24, v6 quad_perm:[1,0,3,2] row_mask:0xf bank_mask:0xf
	v_mov_b32_dpp v25, v15 quad_perm:[1,0,3,2] row_mask:0xf bank_mask:0xf
	v_mov_b32_dpp v26, v14 quad_perm:[1,0,3,2] row_mask:0xf bank_mask:0xf
	v_mov_b32_dpp v27, v13 quad_perm:[1,0,3,2] row_mask:0xf bank_mask:0xf
	v_mov_b32_dpp v28, v8 quad_perm:[1,0,3,2] row_mask:0xf bank_mask:0xf
	v_mov_b32_dpp v29, v16 quad_perm:[1,0,3,2] row_mask:0xf bank_mask:0xf
	v_mov_b32_dpp v30, v7 quad_perm:[1,0,3,2] row_mask:0xf bank_mask:0xf
	v_mov_b32_dpp v31, v2 quad_perm:[1,0,3,2] row_mask:0xf bank_mask:0xf
	s_waitcnt lgkmcnt(0)
; DI void merge_top16(unsigned (&v)[16], int st) {
;     unsigned x[16];
; #pragma unroll
;     for (int i = 0; i < 16; ++i) x[i] = (unsigned)__shfl_xor((int)v[15 - i], st);
; #pragma unroll
;     for (int i = 0; i < 16; ++i) v[i] = max(v[i], x[i]);
; #pragma unroll
;     for (int j = 8; j > 0; j >>= 1)
; #pragma unroll
;         for (int i = 0; i < 16; ++i) { const int l = i ^ j; if (l > i) cswap(v[i], v[l]); }
; }
; DI void topk_phase(unsigned char* smem_, const bf16_t* __restrict__ qp, const bf16_t* __restrict__ keys, int* __restrict__ eidx, float* __restrict__ gate) {
;     ...
;         merge_top16(t16, 1);
;         merge_top16(t16, 2);
; #pragma unroll
;         for (int i = 0; i < 16; ++i) if ((i >> 2) == q) { const int idx = 127 - (int)(t16[i] & 127u); SI[row * 32 + 16 * p + i] = idx; SV[row * 32 + 16 * p + i] = S[row * LDS_ + idx]; }
	v_max_u32_e32 v1, v2, v1
	v_max_u32_e32 v2, v7, v17
	v_max_u32_e32 v7, v16, v18
	v_max_u32_e32 v8, v8, v19
	v_max_u32_e32 v13, v13, v20
	v_max_u32_e32 v14, v14, v21
	v_max_u32_e32 v15, v15, v22
	v_max_u32_e32 v6, v6, v23
	v_max_u32_e32 v12, v12, v24
	v_max_u32_e32 v10, v10, v25
	v_max_u32_e32 v11, v11, v26
	v_max_u32_e32 v3, v3, v27
	v_max_u32_e32 v4, v4, v28
	v_max_u32_e32 v5, v5, v29
	v_max_u32_e32 v9, v9, v30
	v_max_u32_e32 v0, v0, v31
	v_max_u32_e32 v16, v1, v12
	v_min_u32_e32 v1, v1, v12
	v_max_u32_e32 v12, v2, v10
	v_min_u32_e32 v2, v2, v10
	v_max_u32_e32 v10, v7, v11
	v_min_u32_e32 v7, v7, v11
	v_max_u32_e32 v11, v8, v3
	v_min_u32_e32 v3, v8, v3
	v_max_u32_e32 v8, v13, v4
	v_min_u32_e32 v4, v13, v4
	v_max_u32_e32 v13, v14, v5
	v_min_u32_e32 v5, v14, v5
	v_max_u32_e32 v14, v15, v9
	v_min_u32_e32 v9, v15, v9
	v_max_u32_e32 v15, v6, v0
	v_min_u32_e32 v0, v6, v0
	v_max_u32_e32 v6, v16, v8
	v_min_u32_e32 v8, v16, v8
	v_max_u32_e32 v16, v12, v13
	v_min_u32_e32 v12, v12, v13
	v_max_u32_e32 v13, v10, v14
	v_min_u32_e32 v10, v10, v14
	v_max_u32_e32 v14, v11, v15
	v_min_u32_e32 v11, v11, v15
	v_max_u32_e32 v15, v1, v4
	v_min_u32_e32 v1, v1, v4
	v_max_u32_e32 v4, v2, v5
	v_min_u32_e32 v2, v2, v5
	v_max_u32_e32 v5, v7, v9
	v_min_u32_e32 v7, v7, v9
	v_max_u32_e32 v9, v3, v0
	v_min_u32_e32 v0, v3, v0
	v_max_u32_e32 v3, v6, v13
	v_min_u32_e32 v6, v6, v13
	v_max_u32_e32 v13, v16, v14
	v_min_u32_e32 v14, v16, v14
	v_max_u32_e32 v16, v8, v10
	v_min_u32_e32 v8, v8, v10
	v_max_u32_e32 v10, v12, v11
	v_min_u32_e32 v11, v12, v11
	v_max_u32_e32 v12, v15, v5
	v_min_u32_e32 v5, v15, v5
	v_max_u32_e32 v15, v4, v9
	v_min_u32_e32 v4, v4, v9
	v_max_u32_e32 v9, v1, v7
	v_min_u32_e32 v1, v1, v7
	v_max_u32_e32 v7, v2, v0
	v_min_u32_e32 v0, v2, v0
	v_max_u32_e32 v2, v3, v13
	v_min_u32_e32 v3, v3, v13
	v_max_u32_e32 v13, v6, v14
	v_min_u32_e32 v6, v6, v14
	v_max_u32_e32 v14, v16, v10
	v_min_u32_e32 v10, v16, v10
	v_max_u32_e32 v16, v8, v11
	v_min_u32_e32 v8, v8, v11
	v_max_u32_e32 v11, v12, v15
	v_min_u32_e32 v12, v12, v15
	v_max_u32_e32 v15, v5, v4
	v_min_u32_e32 v17, v5, v4
	v_max_u32_e32 v18, v9, v7
	v_min_u32_e32 v19, v9, v7
	v_max_u32_e32 v20, v1, v0
	v_min_u32_e32 v21, v1, v0
	s_nop 1
	v_mov_b32_dpp v0, v21 quad_perm:[2,3,0,1] row_mask:0xf bank_mask:0xf
	v_mov_b32_dpp v1, v20 quad_perm:[2,3,0,1] row_mask:0xf bank_mask:0xf
	v_mov_b32_dpp v4, v19 quad_perm:[2,3,0,1] row_mask:0xf bank_mask:0xf
	v_mov_b32_dpp v5, v18 quad_perm:[2,3,0,1] row_mask:0xf bank_mask:0xf
	v_mov_b32_dpp v7, v17 quad_perm:[2,3,0,1] row_mask:0xf bank_mask:0xf
	v_mov_b32_dpp v9, v15 quad_perm:[2,3,0,1] row_mask:0xf bank_mask:0xf
	v_mov_b32_dpp v22, v12 quad_perm:[2,3,0,1] row_mask:0xf bank_mask:0xf
	v_mov_b32_dpp v23, v11 quad_perm:[2,3,0,1] row_mask:0xf bank_mask:0xf
	v_mov_b32_dpp v24, v8 quad_perm:[2,3,0,1] row_mask:0xf bank_mask:0xf
	v_mov_b32_dpp v25, v16 quad_perm:[2,3,0,1] row_mask:0xf bank_mask:0xf
	v_mov_b32_dpp v26, v10 quad_perm:[2,3,0,1] row_mask:0xf bank_mask:0xf
	v_mov_b32_dpp v27, v14 quad_perm:[2,3,0,1] row_mask:0xf bank_mask:0xf
	v_mov_b32_dpp v28, v6 quad_perm:[2,3,0,1] row_mask:0xf bank_mask:0xf
	v_mov_b32_dpp v29, v13 quad_perm:[2,3,0,1] row_mask:0xf bank_mask:0xf
	v_mov_b32_dpp v30, v3 quad_perm:[2,3,0,1] row_mask:0xf bank_mask:0xf
	v_mov_b32_dpp v31, v2 quad_perm:[2,3,0,1] row_mask:0xf bank_mask:0xf
	s_waitcnt lgkmcnt(0)
	v_max_u32_e32 v0, v2, v0
	v_max_u32_e32 v1, v3, v1
	v_max_u32_e32 v2, v13, v4
	v_max_u32_e32 v3, v6, v5
	v_max_u32_e32 v4, v14, v7
	v_max_u32_e32 v5, v10, v9
	v_max_u32_e32 v6, v16, v22
	v_max_u32_e32 v7, v8, v23
	v_max_u32_e32 v8, v11, v24
	v_max_u32_e32 v9, v12, v25
	v_max_u32_e32 v10, v15, v26
	v_max_u32_e32 v11, v17, v27
	v_max_u32_e32 v12, v18, v28
	v_max_u32_e32 v13, v19, v29
	v_max_u32_e32 v14, v20, v30
	v_max_u32_e32 v15, v21, v31
	v_max_u32_e32 v16, v0, v8
	v_max_u32_e32 v17, v1, v9
	v_max_u32_e32 v18, v2, v10
	v_max_u32_e32 v19, v3, v11
	v_max_u32_e32 v20, v4, v12
	v_max_u32_e32 v21, v5, v13
	v_max_u32_e32 v22, v6, v14
	v_max_u32_e32 v23, v7, v15
	s_and_saveexec_b64 s[16:17], s[4:5]
	s_cbranch_execz .LBB0_69
	v_max_u32_e32 v24, v16, v20
	v_max_u32_e32 v25, v18, v22
	v_max_u32_e32 v27, v17, v21
	v_max_u32_e32 v28, v19, v23
	v_min_u32_e32 v26, v24, v25
	v_min_u32_e32 v29, v27, v28
	v_max_u32_e32 v24, v24, v25
	v_max_u32_e32 v25, v27, v28
	v_min_u32_e32 v30, v26, v29
	v_max_u32_e32 v29, v26, v29
	v_min_u32_e32 v26, v24, v25
	v_max_u32_e32 v24, v24, v25
	v_xor_b32_e32 v25, -1, v26
	v_xor_b32_e32 v24, -1, v24
	v_and_b32_e32 v25, 0x7f, v25
	v_and_b32_e32 v24, 0x7f, v24
	v_lshl_add_u32 v26, v24, 2, v169
	v_lshl_add_u32 v27, v25, 2, v169
	ds_read_b32 v26, v26 offset:17408
	ds_read_b32 v27, v27 offset:17408
	v_xor_b32_e32 v28, -1, v29
	s_waitcnt lgkmcnt(0)
	ds_write_b64 v184, v[26:27] offset:53312
	v_xor_b32_e32 v26, -1, v30
	v_and_b32_e32 v27, 0x7f, v26
	v_and_b32_e32 v26, 0x7f, v28
	v_lshl_add_u32 v28, v26, 2, v169
	ds_write2_b64 v116, v[24:25], v[26:27] offset0:8 offset1:9
	v_lshl_add_u32 v24, v27, 2, v169
	ds_read_b32 v28, v28 offset:17408
	ds_read_b32 v29, v24 offset:17408
	s_waitcnt lgkmcnt(0)
	ds_write_b64 v184, v[28:29] offset:53320

; DI void topk_phase(unsigned char* smem_, const bf16_t* __restrict__ qp, const bf16_t* __restrict__ keys, int* __restrict__ eidx, float* __restrict__ gate) {
;     ...
;     const size_t ob = (size_t)(tok0 + row) * 128 + h * 16;
; #pragma unroll
;     for (int i = 0; i < 16; ++i) if ((i >> 2) == q) { eidx[ob + i] = be[i]; gate[ob + i] = ex[i] * inv; }
.LBB0_82:
	v_or_b32_e32 v158, 48, v158
	v_lshl_add_u32 v3, v27, 7, v117
	v_lshl_add_u32 v2, v13, 7, v19
	v_lshl_add_u32 v5, v143, 7, v145
	v_lshl_add_u32 v4, v121, 7, v125
	v_lshl_add_u64 v[10:11], s[92:93], 0, v[158:159]
	v_pk_mul_f32 v[6:7], v[146:147], v[0:1] op_sel_hi:[1,0]
	v_lshl_add_u64 v[12:13], s[76:77], 0, v[158:159]
	v_pk_mul_f32 v[8:9], v[148:149], v[0:1] op_sel_hi:[1,0]
	global_store_dwordx4 v[10:11], v[2:5], off
	global_store_dwordx4 v[12:13], v[6:9], off
	s_branch .LBB0_54
	s_nop 0
	s_nop 0
	s_nop 0
	s_nop 0
	s_nop 0
	s_nop 0
	s_nop 0
	s_nop 0
	s_nop 0
	s_nop 0
	s_nop 0
	s_nop 0
	s_nop 0
	s_nop 0
	s_nop 0
	s_nop 0
	s_nop 0
	s_nop 0
	s_nop 0
	s_nop 0
	s_nop 0
	s_nop 0
	s_nop 0
	s_nop 0
	s_nop 0
	s_nop 0
	s_nop 0
	s_nop 0
	s_nop 0
	s_nop 0
	s_nop 0
	s_nop 0
	s_nop 0
	s_nop 0
	s_nop 0
	s_nop 0
	s_nop 0
	s_nop 0
	s_nop 0
	s_nop 0
	s_nop 0
	s_nop 0
	s_nop 0
	s_nop 0
	s_nop 0
	s_nop 0
	s_nop 0
	s_nop 0
	s_nop 0
	s_nop 0
	s_nop 0
	s_nop 0
	s_nop 0
	s_nop 0
	s_nop 0
	s_nop 0
	s_nop 0
	s_nop 0
	s_nop 0
	s_nop 0
	s_nop 0
	s_nop 0
	s_nop 0
	s_nop 0
	s_nop 0
	s_nop 0
	s_nop 0
	s_nop 0
	s_nop 0
	s_nop 0
	s_nop 0
	s_nop 0
	s_nop 0
	s_nop 0
	s_nop 0
	s_nop 0
	s_nop 0
	s_nop 0
	s_nop 0
	s_nop 0
	s_nop 0
	s_nop 0
	s_nop 0
	s_nop 0
	s_nop 0
	s_nop 0
	s_nop 0
	s_nop 0
	s_nop 0
	s_nop 0
	s_nop 0
	s_nop 0
	s_nop 0
	s_nop 0
	s_nop 0
	s_nop 0
	s_nop 0
	s_nop 0
	s_nop 0
	s_nop 0
	s_nop 0
	s_nop 0
	s_nop 0
	s_nop 0
	s_nop 0
	s_nop 0
	s_nop 0
	s_nop 0
	s_nop 0
	s_nop 0
	s_nop 0
	s_nop 0
	s_nop 0
	s_nop 0
	s_nop 0
	s_nop 0
	s_nop 0
	s_nop 0
	s_nop 0
	s_nop 0
	s_nop 0
	s_nop 0
	s_nop 0
	s_nop 0
	s_nop 0
	s_nop 0
	s_nop 0
	s_nop 0
	s_nop 0
	s_nop 0
	s_nop 0
	s_nop 0
	s_nop 0
	s_nop 0
	s_nop 0
	s_nop 0
	s_nop 0
	s_nop 0
	s_nop 0
	s_nop 0
	s_nop 0
	s_nop 0
	s_nop 0
	s_nop 0
	s_nop 0
	s_nop 0
	s_nop 0
	s_nop 0
	s_nop 0
	s_nop 0
	s_nop 0
	s_nop 0
	s_nop 0
	s_nop 0
	s_nop 0
	s_nop 0
	s_nop 0
	s_nop 0
	s_nop 0
	s_nop 0
	s_nop 0
	s_nop 0
	s_nop 0
	s_nop 0
	s_nop 0
	s_nop 0
	s_nop 0
	s_nop 0
	s_nop 0
	s_nop 0
	s_nop 0
	s_nop 0
	s_nop 0
	s_nop 0
	s_nop 0
	s_nop 0
	s_nop 0
	s_nop 0
	s_nop 0
	s_nop 0
	s_nop 0

; __global__ void __launch_bounds__(512) fwd_kernel(Params p) {
;     extern __shared__ __attribute__((aligned(16))) unsigned char smem[];
	.amdhsa_kernel _Z10fwd_kernel6Params
		.amdhsa_group_segment_fixed_size 6144
		.amdhsa_private_segment_fixed_size 0
		.amdhsa_kernarg_size 424
		.amdhsa_user_sgpr_count 2
		.amdhsa_user_sgpr_dispatch_ptr 0
		.amdhsa_user_sgpr_queue_ptr 0
		.amdhsa_user_sgpr_kernarg_segment_ptr 1
		.amdhsa_user_sgpr_dispatch_id 0
		.amdhsa_user_sgpr_kernarg_preload_length 0
		.amdhsa_user_sgpr_kernarg_preload_offset 0
		.amdhsa_user_sgpr_private_segment_size 0
		.amdhsa_uses_dynamic_stack 0
		.amdhsa_enable_private_segment 0
		.amdhsa_system_sgpr_workgroup_id_x 1
		.amdhsa_system_sgpr_workgroup_id_y 0
		.amdhsa_system_sgpr_workgroup_id_z 0
		.amdhsa_system_sgpr_workgroup_info 0
		.amdhsa_system_vgpr_workitem_id 2
		.amdhsa_next_free_vgpr 253
		.amdhsa_next_free_sgpr 100
		.amdhsa_accum_offset 256
		.amdhsa_reserve_vcc 1
		.amdhsa_float_round_mode_32 0
		.amdhsa_float_round_mode_16_64 0
		.amdhsa_float_denorm_mode_32 3
		.amdhsa_float_denorm_mode_16_64 3
		.amdhsa_dx10_clamp 1
		.amdhsa_ieee_mode 1
		.amdhsa_fp16_overflow 0
		.amdhsa_tg_split 0
		.amdhsa_exception_fp_ieee_invalid_op 0
		.amdhsa_exception_fp_denorm_src 0
		.amdhsa_exception_fp_ieee_div_zero 0
		.amdhsa_exception_fp_ieee_overflow 0
		.amdhsa_exception_fp_ieee_underflow 0
		.amdhsa_exception_fp_ieee_inexact 0
		.amdhsa_exception_int_div_zero 0
	.end_amdhsa_kernel

; __global__ void __launch_bounds__(512) fwd_kernel(Params p) {
;     extern __shared__ __attribute__((aligned(16))) unsigned char smem[];
amdhsa.kernels:
  - .agpr_count:     0
    .args:
      - .offset:         0
        .size:           168
        .value_kind:     by_value
      - .offset:         168
        .size:           4
        .value_kind:     hidden_block_count_x
      - .offset:         172
        .size:           4
        .value_kind:     hidden_block_count_y
      - .offset:         176
        .size:           4
        .value_kind:     hidden_block_count_z
      - .offset:         180
        .size:           2
        .value_kind:     hidden_group_size_x
      - .offset:         182
        .size:           2
        .value_kind:     hidden_group_size_y
      - .offset:         184
        .size:           2
        .value_kind:     hidden_group_size_z
      - .offset:         186
        .size:           2
        .value_kind:     hidden_remainder_x
      - .offset:         188
        .size:           2
        .value_kind:     hidden_remainder_y
      - .offset:         190
        .size:           2
        .value_kind:     hidden_remainder_z
      - .offset:         208
        .size:           8
        .value_kind:     hidden_global_offset_x
      - .offset:         216
        .size:           8
        .value_kind:     hidden_global_offset_y
      - .offset:         224
        .size:           8
        .value_kind:     hidden_global_offset_z
      - .offset:         232
        .size:           2
        .value_kind:     hidden_grid_dims
      - .offset:         256
        .size:           8
        .value_kind:     hidden_multigrid_sync_arg
      - .offset:         288
        .size:           4
        .value_kind:     hidden_dynamic_lds_size
    .group_segment_fixed_size: 6144
    .kernarg_segment_align: 8
    .kernarg_segment_size: 424
    .language:       OpenCL C
    .language_version:
      - 2
      - 0
    .max_flat_workgroup_size: 512
    .name:           _Z10fwd_kernel6Params
    .private_segment_fixed_size: 0
    .sgpr_count:     106
    .sgpr_spill_count: 157
    .symbol:         _Z10fwd_kernel6Params.kd
    .uniform_work_group_size: 1
    .uses_dynamic_stack: false
    .vgpr_count:     253
    .vgpr_spill_count: 0
    .wavefront_size: 64
